# GLA-C and GLA-A q/k fill loops: all u16 gathers prefetched before the fully unrolled loop (were 32 serialized load+wait round trips per job)
# speedup vs baseline: 1.1472x; 1.0205x over previous
.LBB0_264:
	ds_read_b128 v[4:7], v1
	ds_read_b128 v[8:11], v1 offset:16
	ds_read_b128 v[12:15], v1 offset:32
	ds_read_b128 v[36:39], v1 offset:48
	s_waitcnt lgkmcnt(3)
	v_mov_b32_e32 v32, v4
	s_waitcnt lgkmcnt(2)
	v_mov_b32_e32 v33, v8
	v_mov_b32_e32 v8, v5
	s_waitcnt vmcnt(11)
	v_pk_mul_f32 v[4:5], v[18:19], v[8:9]
	v_mov_b32_e32 v8, v6
	v_pk_fma_f32 v[4:5], v[16:17], v[32:33], v[4:5]
	v_mov_b32_e32 v9, v10
	s_waitcnt vmcnt(10)
	v_pk_fma_f32 v[4:5], v[20:21], v[8:9], v[4:5]
	v_mov_b32_e32 v10, v7
	s_waitcnt vmcnt(9)
	v_pk_fma_f32 v[4:5], v[22:23], v[10:11], v[4:5]
	s_waitcnt vmcnt(0)
	v_add_f32_e32 v3, v34, v4
	v_add_f32_e32 v3, v3, v5
	s_waitcnt lgkmcnt(0)
	v_mov_b32_e32 v5, v36
	v_mov_b32_e32 v36, v13
	v_mov_b32_e32 v4, v12
	v_pk_mul_f32 v[6:7], v[26:27], v[36:37]
	s_nop 0
	v_pk_fma_f32 v[4:5], v[24:25], v[4:5], v[6:7]
	v_mov_b32_e32 v6, v14
	v_mov_b32_e32 v7, v38
	v_pk_fma_f32 v[4:5], v[28:29], v[6:7], v[4:5]
	v_mov_b32_e32 v38, v15
	v_pk_fma_f32 v[4:5], v[30:31], v[38:39], v[4:5]
	s_nop 0
	v_add_f32_e32 v3, v3, v4
	v_add_f32_e32 v3, v3, v5
	v_min_f32_e32 v4, 0, v3
	v_mul_f32_e64 v3, |v3|, s8
	v_exp_f32_e32 v3, v3
	s_nop 0
	v_add_f32_e32 v3, 1.0, v3
	v_cmp_gt_f32_e32 vcc, s95, v3
	s_nop 1
	v_cndmask_b32_e64 v5, 0, 32, vcc
	v_ldexp_f32 v3, v3, v5
	v_log_f32_e32 v3, v3
	s_nop 0
	v_mul_f32_e32 v5, 0x3f317217, v3
	v_fma_f32 v5, v3, s9, -v5
	v_fmac_f32_e32 v5, 0x3377d1cf, v3
	v_fmac_f32_e32 v5, 0x3f317217, v3
	v_cmp_lt_f32_e64 s[0:1], |v3|, s10
	s_nop 1
	v_cndmask_b32_e64 v3, v3, v5, s[0:1]
	v_cndmask_b32_e32 v5, 0, v163, vcc
	v_sub_f32_e32 v3, v3, v5
	v_sub_f32_e32 v3, v4, v3
	v_mul_f32_e32 v3, 0x3d800000, v3
	v_cmp_lt_i32_e32 vcc, s45, v0
	s_nop 1
	v_cndmask_b32_e32 v3, 0, v3, vcc
	v_add_f32_e32 v12, v2, v3
	ds_read_b128 v[2:5], v1 offset:80
	ds_read_b128 v[6:9], v1 offset:64
	s_waitcnt lgkmcnt(1)
	v_mov_b32_e32 v11, v2
	s_waitcnt lgkmcnt(0)
	v_mov_b32_e32 v2, v7
	v_mov_b32_e32 v10, v6
	v_pk_mul_f32 v[2:3], v[18:19], v[2:3]
	v_mov_b32_e32 v6, v8
	v_pk_fma_f32 v[2:3], v[16:17], v[10:11], v[2:3]
	v_mov_b32_e32 v7, v4
	v_pk_fma_f32 v[2:3], v[20:21], v[6:7], v[2:3]
	v_mov_b32_e32 v4, v9
	v_pk_fma_f32 v[2:3], v[22:23], v[4:5], v[2:3]
	s_nop 0
	v_add_f32_e32 v2, v34, v2
	v_add_f32_e32 v13, v2, v3
	ds_read_b128 v[2:5], v1 offset:112
	ds_read_b128 v[6:9], v1 offset:96
	v_add_u32_e32 v1, 0x80, v1
	s_waitcnt lgkmcnt(1)
	v_mov_b32_e32 v11, v2
	s_waitcnt lgkmcnt(0)
	v_mov_b32_e32 v2, v7
	v_mov_b32_e32 v10, v6
	v_pk_mul_f32 v[2:3], v[26:27], v[2:3]
	v_mov_b32_e32 v6, v8
	v_pk_fma_f32 v[2:3], v[24:25], v[10:11], v[2:3]
	v_mov_b32_e32 v7, v4
	v_pk_fma_f32 v[2:3], v[28:29], v[6:7], v[2:3]
	v_mov_b32_e32 v4, v9
	v_pk_fma_f32 v[2:3], v[30:31], v[4:5], v[2:3]
	s_nop 0
	v_add_f32_e32 v2, v13, v2
	v_add_f32_e32 v2, v2, v3
	v_min_f32_e32 v3, 0, v2
	v_mul_f32_e64 v2, |v2|, s8
	v_exp_f32_e32 v2, v2
	s_nop 0
	v_add_f32_e32 v2, 1.0, v2
	v_cmp_gt_f32_e32 vcc, s95, v2
	s_nop 1
	v_cndmask_b32_e64 v4, 0, 32, vcc
	v_ldexp_f32 v2, v2, v4
	v_log_f32_e32 v2, v2
	s_nop 0
	v_mul_f32_e32 v4, 0x3f317217, v2
	v_fma_f32 v4, v2, s9, -v4
	v_fmac_f32_e32 v4, 0x3377d1cf, v2
	v_fmac_f32_e32 v4, 0x3f317217, v2
	v_cmp_lt_f32_e64 s[0:1], |v2|, s10
	s_nop 1
	v_cndmask_b32_e64 v2, v2, v4, s[0:1]
	v_cndmask_b32_e32 v4, 0, v163, vcc
	v_sub_f32_e32 v2, v2, v4
	v_sub_f32_e32 v2, v3, v2
	s_add_i32 s0, s45, 1
	v_mul_f32_e32 v2, 0x3d800000, v2
	v_cmp_lt_i32_e32 vcc, s0, v0
	s_add_i32 s45, s45, 2
	s_cmp_lg_u32 s45, 32
	v_cndmask_b32_e32 v2, 0, v2, vcc
	v_add_f32_e32 v2, v12, v2
	s_cbranch_scc1 .LBB0_264
	s_mov_b32 s12, 0x7f800000
	s_mov_b32 s11, 0x3f317217
	s_mov_b32 s10, 0xbfb8aa3b
	s_mov_b32 s8, 0x800000
	v_mov_b32_e32 v41, 0
	ds_write_b32 v122, v2 offset:4096
	s_waitcnt lgkmcnt(0)
	s_barrier
	s_mov_b64 s[0:1], exec
	v_readlane_b32 vcc_lo, v254, 55
	v_readlane_b32 vcc_hi, v254, 56
	s_and_b64 vcc, s[0:1], vcc
	s_mov_b64 exec, vcc
	ds_read_b32 v41, v112 offset:4096
	s_or_b64 exec, exec, s[0:1]
	s_lshl_b32 s0, s44, 1
	s_mov_b32 s1, s3
	v_lshl_add_u64 v[32:33], v[86:87], 0, s[0:1]
	v_add_u32_e32 v35, s7, v121
	s_mov_b32 s95, 0
	v_mov_b32_e32 v36, v120
	v_mov_b32_e32 v37, v114
	s_movk_i32 s9, 0x3200
	v_mad_i64_i32 v[244:245], s[0:1], v35, s9, v[32:33]
	s_mov_b64 s[0:1], 0x3200
	global_load_ushort v44, v[244:245], off offset:1024
	global_load_ushort v45, v[244:245], off
	v_lshl_add_u64 v[244:245], v[244:245], 0, s[0:1]
	global_load_ushort v46, v[244:245], off offset:1024
	global_load_ushort v47, v[244:245], off
	v_lshl_add_u64 v[244:245], v[244:245], 0, s[0:1]
	global_load_ushort v48, v[244:245], off offset:1024
	global_load_ushort v49, v[244:245], off
	v_lshl_add_u64 v[244:245], v[244:245], 0, s[0:1]
	global_load_ushort v50, v[244:245], off offset:1024
	global_load_ushort v51, v[244:245], off
	v_lshl_add_u64 v[244:245], v[244:245], 0, s[0:1]
	global_load_ushort v52, v[244:245], off offset:1024
	global_load_ushort v53, v[244:245], off
	v_lshl_add_u64 v[244:245], v[244:245], 0, s[0:1]
	global_load_ushort v54, v[244:245], off offset:1024
	global_load_ushort v55, v[244:245], off
	v_lshl_add_u64 v[244:245], v[244:245], 0, s[0:1]
	global_load_ushort v56, v[244:245], off offset:1024
	global_load_ushort v57, v[244:245], off
	v_lshl_add_u64 v[244:245], v[244:245], 0, s[0:1]
	global_load_ushort v58, v[244:245], off offset:1024
	global_load_ushort v59, v[244:245], off
	v_lshl_add_u64 v[244:245], v[244:245], 0, s[0:1]
	global_load_ushort v60, v[244:245], off offset:1024
	global_load_ushort v61, v[244:245], off
	v_lshl_add_u64 v[244:245], v[244:245], 0, s[0:1]
	global_load_ushort v62, v[244:245], off offset:1024
	global_load_ushort v63, v[244:245], off
	v_lshl_add_u64 v[244:245], v[244:245], 0, s[0:1]
	global_load_ushort v102, v[244:245], off offset:1024
	global_load_ushort v103, v[244:245], off
	v_lshl_add_u64 v[244:245], v[244:245], 0, s[0:1]
	global_load_ushort v104, v[244:245], off offset:1024
	global_load_ushort v105, v[244:245], off
	v_lshl_add_u64 v[244:245], v[244:245], 0, s[0:1]
	global_load_ushort v106, v[244:245], off offset:1024
	global_load_ushort v107, v[244:245], off
	v_lshl_add_u64 v[244:245], v[244:245], 0, s[0:1]
	global_load_ushort v108, v[244:245], off offset:1024
	global_load_ushort v109, v[244:245], off
	v_lshl_add_u64 v[244:245], v[244:245], 0, s[0:1]
	global_load_ushort v110, v[244:245], off offset:1024
	global_load_ushort v111, v[244:245], off
	v_lshl_add_u64 v[244:245], v[244:245], 0, s[0:1]
	global_load_ushort v209, v[244:245], off offset:1024
	global_load_ushort v210, v[244:245], off
	v_lshl_add_u64 v[244:245], v[244:245], 0, s[0:1]
	global_load_ushort v211, v[244:245], off offset:1024
	global_load_ushort v212, v[244:245], off
	v_lshl_add_u64 v[244:245], v[244:245], 0, s[0:1]
	global_load_ushort v213, v[244:245], off offset:1024
	global_load_ushort v214, v[244:245], off
	v_lshl_add_u64 v[244:245], v[244:245], 0, s[0:1]
	global_load_ushort v215, v[244:245], off offset:1024
	global_load_ushort v216, v[244:245], off
	v_lshl_add_u64 v[244:245], v[244:245], 0, s[0:1]
	global_load_ushort v217, v[244:245], off offset:1024
	global_load_ushort v218, v[244:245], off
	v_lshl_add_u64 v[244:245], v[244:245], 0, s[0:1]
	global_load_ushort v219, v[244:245], off offset:1024
	global_load_ushort v220, v[244:245], off
	v_lshl_add_u64 v[244:245], v[244:245], 0, s[0:1]
	global_load_ushort v221, v[244:245], off offset:1024
	global_load_ushort v222, v[244:245], off
	v_lshl_add_u64 v[244:245], v[244:245], 0, s[0:1]
	global_load_ushort v223, v[244:245], off offset:1024
	global_load_ushort v224, v[244:245], off
	v_lshl_add_u64 v[244:245], v[244:245], 0, s[0:1]
	global_load_ushort v225, v[244:245], off offset:1024
	global_load_ushort v226, v[244:245], off
	v_lshl_add_u64 v[244:245], v[244:245], 0, s[0:1]
	global_load_ushort v227, v[244:245], off offset:1024
	global_load_ushort v228, v[244:245], off
	v_lshl_add_u64 v[244:245], v[244:245], 0, s[0:1]
	global_load_ushort v229, v[244:245], off offset:1024
	global_load_ushort v230, v[244:245], off
	v_lshl_add_u64 v[244:245], v[244:245], 0, s[0:1]
	global_load_ushort v231, v[244:245], off offset:1024
	global_load_ushort v232, v[244:245], off
	v_lshl_add_u64 v[244:245], v[244:245], 0, s[0:1]
	global_load_ushort v233, v[244:245], off offset:1024
	global_load_ushort v234, v[244:245], off
	v_lshl_add_u64 v[244:245], v[244:245], 0, s[0:1]
	global_load_ushort v235, v[244:245], off offset:1024
	global_load_ushort v236, v[244:245], off
	v_lshl_add_u64 v[244:245], v[244:245], 0, s[0:1]
	global_load_ushort v237, v[244:245], off offset:1024
	global_load_ushort v238, v[244:245], off
	v_lshl_add_u64 v[244:245], v[244:245], 0, s[0:1]
	global_load_ushort v239, v[244:245], off offset:1024
	global_load_ushort v240, v[244:245], off
	v_lshl_add_u64 v[244:245], v[244:245], 0, s[0:1]
	global_load_ushort v241, v[244:245], off offset:1024
	global_load_ushort v242, v[244:245], off
	s_branch .Lgc_h0
.Lgc_h0:
	ds_read_b128 v[12:15], v36
	ds_read_b128 v[8:11], v36 offset:16
	ds_read_b128 v[4:7], v36 offset:32
	ds_read_b128 v[0:3], v36 offset:48
	v_add_u32_e32 v38, s95, v121
	v_cmp_gt_i32_e32 vcc, s92, v38
	v_mov_b32_e32 v40, 0
	v_mov_b32_e32 v42, 0
	v_mov_b32_e32 v43, 0
	s_and_saveexec_b64 s[0:1], vcc
	s_cbranch_execz .Lgc_a0
	s_waitcnt vmcnt(62)
	v_lshlrev_b32_e32 v42, 16, v44
	v_lshlrev_b32_e32 v43, 16, v45
.Lgc_a0:
	s_or_b64 exec, exec, s[0:1]
	s_waitcnt lgkmcnt(3)
	v_mul_f32_e32 v13, v18, v13
	v_fmac_f32_e32 v13, v16, v12
	s_waitcnt lgkmcnt(2)
	v_mul_f32_e32 v9, v19, v9
	v_fmac_f32_e32 v13, v20, v14
	v_fmac_f32_e32 v9, v17, v8
	s_waitcnt lgkmcnt(1)
	v_mul_f32_e32 v5, v26, v5
	v_fmac_f32_e32 v13, v22, v15
	v_fmac_f32_e32 v9, v21, v10
	v_fmac_f32_e32 v5, v24, v4
	s_waitcnt lgkmcnt(0)
	v_mul_f32_e32 v1, v27, v1
	v_add_f32_e32 v12, v34, v13
	v_fmac_f32_e32 v9, v23, v11
	v_fmac_f32_e32 v5, v28, v6
	v_fmac_f32_e32 v1, v25, v0
	v_add_f32_e32 v8, v12, v9
	v_fmac_f32_e32 v5, v30, v7
	v_fmac_f32_e32 v1, v29, v2
	v_add_f32_e32 v4, v8, v5
	v_fmac_f32_e32 v1, v31, v3
	v_add_f32_e32 v0, v4, v1
	v_mul_f32_e64 v1, |v0|, s10
	v_exp_f32_e32 v1, v1
	v_min_f32_e32 v0, 0, v0
	v_add_f32_e32 v1, 1.0, v1
	v_cmp_gt_f32_e64 s[0:1], s8, v1
	s_nop 1
	v_cndmask_b32_e64 v2, 0, 32, s[0:1]
	v_ldexp_f32 v1, v1, v2
	v_log_f32_e32 v1, v1
	s_nop 0
	v_mul_f32_e32 v2, 0x3f317217, v1
	v_fma_f32 v2, v1, s11, -v2
	v_fmac_f32_e32 v2, 0x3377d1cf, v1
	v_fmac_f32_e32 v2, 0x3f317217, v1
	v_cmp_lt_f32_e64 s[44:45], |v1|, s12
	s_nop 1
	v_cndmask_b32_e64 v1, v1, v2, s[44:45]
	v_cndmask_b32_e64 v2, 0, v163, s[0:1]
	v_sub_f32_e32 v1, v1, v2
	v_sub_f32_e32 v0, v0, v1
	v_mul_f32_e32 v0, 0x3d800000, v0
	v_cndmask_b32_e32 v0, 0, v0, vcc
	v_add_f32_e32 v39, v41, v0
	v_mul_f32_e32 v0, 0x3fb8aa3b, v39
	v_exp_f32_e32 v0, v0
	v_mul_f32_e32 v1, 0xbfb8aa3b, v39
	v_exp_f32_e32 v1, v1
	v_add_u32_e32 v41, 1, v38
	v_mul_f32_e32 v0, v0, v43
	v_mul_f32_e32 v0, 0x3db504f3, v0
	v_bfe_u32 v2, v0, 16, 1
	v_add3_u32 v0, v0, v2, s33
	ds_write_b16_d16_hi v37, v0
	v_mul_f32_e32 v0, v1, v42
	v_bfe_u32 v1, v0, 16, 1
	v_add3_u32 v0, v0, v1, s33
	ds_write_b16_d16_hi v37, v0 offset:17408
	ds_read_b128 v[12:15], v36 offset:64
	ds_read_b128 v[8:11], v36 offset:80
	ds_read_b128 v[4:7], v36 offset:96
	ds_read_b128 v[0:3], v36 offset:112
	v_cmp_gt_i32_e32 vcc, s92, v41
	v_mov_b32_e32 v42, 0
	s_and_saveexec_b64 s[0:1], vcc
	s_cbranch_execz .Lgc_b0
	s_waitcnt vmcnt(60)
	v_lshlrev_b32_e32 v40, 16, v46
	v_lshlrev_b32_e32 v42, 16, v47
.Lgc_b0:
	s_or_b64 exec, exec, s[0:1]
	s_waitcnt lgkmcnt(3)
	v_mul_f32_e32 v13, v18, v13
	v_fmac_f32_e32 v13, v16, v12
	s_waitcnt lgkmcnt(2)
	v_mul_f32_e32 v9, v19, v9
	v_fmac_f32_e32 v13, v20, v14
	v_fmac_f32_e32 v9, v17, v8
	s_waitcnt lgkmcnt(1)
	v_mul_f32_e32 v5, v26, v5
	v_fmac_f32_e32 v13, v22, v15
	v_fmac_f32_e32 v9, v21, v10
	v_fmac_f32_e32 v5, v24, v4
	s_waitcnt lgkmcnt(0)
	v_mul_f32_e32 v1, v27, v1
	v_add_f32_e32 v12, v34, v13
	v_fmac_f32_e32 v9, v23, v11
	v_fmac_f32_e32 v5, v28, v6
	v_fmac_f32_e32 v1, v25, v0
	v_add_f32_e32 v8, v12, v9
	v_fmac_f32_e32 v5, v30, v7
	v_fmac_f32_e32 v1, v29, v2
	v_add_f32_e32 v4, v8, v5
	v_fmac_f32_e32 v1, v31, v3
	v_add_f32_e32 v0, v4, v1
	v_mul_f32_e64 v1, |v0|, s10
	v_exp_f32_e32 v1, v1
	v_min_f32_e32 v0, 0, v0
	v_mov_b32_e32 v43, 0
	v_add_f32_e32 v1, 1.0, v1
	v_cmp_gt_f32_e64 s[0:1], s8, v1
	s_nop 1
	v_cndmask_b32_e64 v2, 0, 32, s[0:1]
	v_ldexp_f32 v1, v1, v2
	v_log_f32_e32 v1, v1
	s_nop 0
	v_mul_f32_e32 v2, 0x3f317217, v1
	v_fma_f32 v2, v1, s11, -v2
	v_fmac_f32_e32 v2, 0x3377d1cf, v1
	v_fmac_f32_e32 v2, 0x3f317217, v1
	v_cmp_lt_f32_e64 s[44:45], |v1|, s12
	s_nop 1
	v_cndmask_b32_e64 v1, v1, v2, s[44:45]
	v_cndmask_b32_e64 v2, 0, v163, s[0:1]
	v_sub_f32_e32 v1, v1, v2
	v_sub_f32_e32 v0, v0, v1
	v_mul_f32_e32 v0, 0x3d800000, v0
	v_cndmask_b32_e32 v0, 0, v0, vcc
	v_add_f32_e32 v41, v39, v0
	v_mul_f32_e32 v0, 0x3fb8aa3b, v41
	v_exp_f32_e32 v0, v0
	v_mul_f32_e32 v1, 0xbfb8aa3b, v41
	v_exp_f32_e32 v1, v1
	v_mov_b32_e32 v39, 0
	v_mul_f32_e32 v0, v0, v42
	v_mul_f32_e32 v0, 0x3db504f3, v0
	v_bfe_u32 v2, v0, 16, 1
	v_add3_u32 v0, v0, v2, s33
	ds_write_b16_d16_hi v37, v0 offset:272
	v_mul_f32_e32 v0, v1, v40
	v_bfe_u32 v1, v0, 16, 1
	v_add3_u32 v0, v0, v1, s33
	ds_write_b16_d16_hi v37, v0 offset:17680
	ds_read_b128 v[12:15], v36 offset:128
	ds_read_b128 v[8:11], v36 offset:144
	ds_read_b128 v[4:7], v36 offset:160
	ds_read_b128 v[0:3], v36 offset:176
	v_add_u32_e32 v40, 2, v38
	v_cmp_gt_i32_e32 vcc, s92, v40
	v_mov_b32_e32 v42, 0
	s_and_saveexec_b64 s[0:1], vcc
	s_cbranch_execz .Lgc_c0
	s_waitcnt vmcnt(58)
	v_lshlrev_b32_e32 v42, 16, v48
	v_lshlrev_b32_e32 v43, 16, v49
.Lgc_c0:
	s_or_b64 exec, exec, s[0:1]
	s_waitcnt lgkmcnt(3)
	v_mul_f32_e32 v13, v18, v13
	v_fmac_f32_e32 v13, v16, v12
	s_waitcnt lgkmcnt(2)
	v_mul_f32_e32 v9, v19, v9
	v_fmac_f32_e32 v13, v20, v14
	v_fmac_f32_e32 v9, v17, v8
	s_waitcnt lgkmcnt(1)
	v_mul_f32_e32 v5, v26, v5
	v_fmac_f32_e32 v13, v22, v15
	v_fmac_f32_e32 v9, v21, v10
	v_fmac_f32_e32 v5, v24, v4
	s_waitcnt lgkmcnt(0)
	v_mul_f32_e32 v1, v27, v1
	v_add_f32_e32 v12, v34, v13
	v_fmac_f32_e32 v9, v23, v11
	v_fmac_f32_e32 v5, v28, v6
	v_fmac_f32_e32 v1, v25, v0
	v_add_f32_e32 v8, v12, v9
	v_fmac_f32_e32 v5, v30, v7
	v_fmac_f32_e32 v1, v29, v2
	v_add_f32_e32 v4, v8, v5
	v_fmac_f32_e32 v1, v31, v3
	v_add_f32_e32 v0, v4, v1
	v_mul_f32_e64 v1, |v0|, s10
	v_exp_f32_e32 v1, v1
	v_min_f32_e32 v0, 0, v0
	v_add_u32_e32 v38, 3, v38
	v_add_f32_e32 v1, 1.0, v1
	v_cmp_gt_f32_e64 s[0:1], s8, v1
	s_nop 1
	v_cndmask_b32_e64 v2, 0, 32, s[0:1]
	v_ldexp_f32 v1, v1, v2
	v_log_f32_e32 v1, v1
	s_nop 0
	v_mul_f32_e32 v2, 0x3f317217, v1
	v_fma_f32 v2, v1, s11, -v2
	v_fmac_f32_e32 v2, 0x3377d1cf, v1
	v_fmac_f32_e32 v2, 0x3f317217, v1
	v_cmp_lt_f32_e64 s[44:45], |v1|, s12
	s_nop 1
	v_cndmask_b32_e64 v1, v1, v2, s[44:45]
	v_cndmask_b32_e64 v2, 0, v163, s[0:1]
	v_sub_f32_e32 v1, v1, v2
	v_sub_f32_e32 v0, v0, v1
	v_mul_f32_e32 v0, 0x3d800000, v0
	v_cndmask_b32_e32 v0, 0, v0, vcc
	v_add_f32_e32 v40, v41, v0
	v_mul_f32_e32 v0, 0x3fb8aa3b, v40
	v_exp_f32_e32 v0, v0
	v_mul_f32_e32 v1, 0xbfb8aa3b, v40
	v_exp_f32_e32 v1, v1
	v_cmp_gt_i32_e32 vcc, s92, v38
	v_mul_f32_e32 v0, v0, v43
	v_mul_f32_e32 v0, 0x3db504f3, v0
	v_bfe_u32 v2, v0, 16, 1
	v_add3_u32 v0, v0, v2, s33
	ds_write_b16_d16_hi v37, v0 offset:544
	v_mul_f32_e32 v0, v1, v42
	v_bfe_u32 v1, v0, 16, 1
	v_add3_u32 v0, v0, v1, s33
	ds_write_b16_d16_hi v37, v0 offset:17952
	ds_read_b128 v[12:15], v36 offset:192
	ds_read_b128 v[8:11], v36 offset:208
	ds_read_b128 v[4:7], v36 offset:224
	ds_read_b128 v[0:3], v36 offset:240
	v_mov_b32_e32 v38, 0
	s_and_saveexec_b64 s[0:1], vcc
	s_cbranch_execz .Lgc_l0
	s_waitcnt vmcnt(56)
	v_lshlrev_b32_e32 v39, 16, v50
	v_lshlrev_b32_e32 v38, 16, v51
	s_branch .Lgc_l0

.Lgc_h1:
	ds_read_b128 v[12:15], v36
	ds_read_b128 v[8:11], v36 offset:16
	ds_read_b128 v[4:7], v36 offset:32
	ds_read_b128 v[0:3], v36 offset:48
	v_add_u32_e32 v38, s95, v121
	v_cmp_gt_i32_e32 vcc, s92, v38
	v_mov_b32_e32 v40, 0
	v_mov_b32_e32 v42, 0
	v_mov_b32_e32 v43, 0
	s_and_saveexec_b64 s[0:1], vcc
	s_cbranch_execz .Lgc_a1
	s_waitcnt vmcnt(54)
	v_lshlrev_b32_e32 v42, 16, v52
	v_lshlrev_b32_e32 v43, 16, v53
.Lgc_a1:
	s_or_b64 exec, exec, s[0:1]
	s_waitcnt lgkmcnt(3)
	v_mul_f32_e32 v13, v18, v13
	v_fmac_f32_e32 v13, v16, v12
	s_waitcnt lgkmcnt(2)
	v_mul_f32_e32 v9, v19, v9
	v_fmac_f32_e32 v13, v20, v14
	v_fmac_f32_e32 v9, v17, v8
	s_waitcnt lgkmcnt(1)
	v_mul_f32_e32 v5, v26, v5
	v_fmac_f32_e32 v13, v22, v15
	v_fmac_f32_e32 v9, v21, v10
	v_fmac_f32_e32 v5, v24, v4
	s_waitcnt lgkmcnt(0)
	v_mul_f32_e32 v1, v27, v1
	v_add_f32_e32 v12, v34, v13
	v_fmac_f32_e32 v9, v23, v11
	v_fmac_f32_e32 v5, v28, v6
	v_fmac_f32_e32 v1, v25, v0
	v_add_f32_e32 v8, v12, v9
	v_fmac_f32_e32 v5, v30, v7
	v_fmac_f32_e32 v1, v29, v2
	v_add_f32_e32 v4, v8, v5
	v_fmac_f32_e32 v1, v31, v3
	v_add_f32_e32 v0, v4, v1
	v_mul_f32_e64 v1, |v0|, s10
	v_exp_f32_e32 v1, v1
	v_min_f32_e32 v0, 0, v0
	v_add_f32_e32 v1, 1.0, v1
	v_cmp_gt_f32_e64 s[0:1], s8, v1
	s_nop 1
	v_cndmask_b32_e64 v2, 0, 32, s[0:1]
	v_ldexp_f32 v1, v1, v2
	v_log_f32_e32 v1, v1
	s_nop 0
	v_mul_f32_e32 v2, 0x3f317217, v1
	v_fma_f32 v2, v1, s11, -v2
	v_fmac_f32_e32 v2, 0x3377d1cf, v1
	v_fmac_f32_e32 v2, 0x3f317217, v1
	v_cmp_lt_f32_e64 s[44:45], |v1|, s12
	s_nop 1
	v_cndmask_b32_e64 v1, v1, v2, s[44:45]
	v_cndmask_b32_e64 v2, 0, v163, s[0:1]
	v_sub_f32_e32 v1, v1, v2
	v_sub_f32_e32 v0, v0, v1
	v_mul_f32_e32 v0, 0x3d800000, v0
	v_cndmask_b32_e32 v0, 0, v0, vcc
	v_add_f32_e32 v39, v41, v0
	v_mul_f32_e32 v0, 0x3fb8aa3b, v39
	v_exp_f32_e32 v0, v0
	v_mul_f32_e32 v1, 0xbfb8aa3b, v39
	v_exp_f32_e32 v1, v1
	v_add_u32_e32 v41, 1, v38
	v_mul_f32_e32 v0, v0, v43
	v_mul_f32_e32 v0, 0x3db504f3, v0
	v_bfe_u32 v2, v0, 16, 1
	v_add3_u32 v0, v0, v2, s33
	ds_write_b16_d16_hi v37, v0
	v_mul_f32_e32 v0, v1, v42
	v_bfe_u32 v1, v0, 16, 1
	v_add3_u32 v0, v0, v1, s33
	ds_write_b16_d16_hi v37, v0 offset:17408
	ds_read_b128 v[12:15], v36 offset:64
	ds_read_b128 v[8:11], v36 offset:80
	ds_read_b128 v[4:7], v36 offset:96
	ds_read_b128 v[0:3], v36 offset:112
	v_cmp_gt_i32_e32 vcc, s92, v41
	v_mov_b32_e32 v42, 0
	s_and_saveexec_b64 s[0:1], vcc
	s_cbranch_execz .Lgc_b1
	s_waitcnt vmcnt(52)
	v_lshlrev_b32_e32 v40, 16, v54
	v_lshlrev_b32_e32 v42, 16, v55
.Lgc_b1:
	s_or_b64 exec, exec, s[0:1]
	s_waitcnt lgkmcnt(3)
	v_mul_f32_e32 v13, v18, v13
	v_fmac_f32_e32 v13, v16, v12
	s_waitcnt lgkmcnt(2)
	v_mul_f32_e32 v9, v19, v9
	v_fmac_f32_e32 v13, v20, v14
	v_fmac_f32_e32 v9, v17, v8
	s_waitcnt lgkmcnt(1)
	v_mul_f32_e32 v5, v26, v5
	v_fmac_f32_e32 v13, v22, v15
	v_fmac_f32_e32 v9, v21, v10
	v_fmac_f32_e32 v5, v24, v4
	s_waitcnt lgkmcnt(0)
	v_mul_f32_e32 v1, v27, v1
	v_add_f32_e32 v12, v34, v13
	v_fmac_f32_e32 v9, v23, v11
	v_fmac_f32_e32 v5, v28, v6
	v_fmac_f32_e32 v1, v25, v0
	v_add_f32_e32 v8, v12, v9
	v_fmac_f32_e32 v5, v30, v7
	v_fmac_f32_e32 v1, v29, v2
	v_add_f32_e32 v4, v8, v5
	v_fmac_f32_e32 v1, v31, v3
	v_add_f32_e32 v0, v4, v1
	v_mul_f32_e64 v1, |v0|, s10
	v_exp_f32_e32 v1, v1
	v_min_f32_e32 v0, 0, v0
	v_mov_b32_e32 v43, 0
	v_add_f32_e32 v1, 1.0, v1
	v_cmp_gt_f32_e64 s[0:1], s8, v1
	s_nop 1
	v_cndmask_b32_e64 v2, 0, 32, s[0:1]
	v_ldexp_f32 v1, v1, v2
	v_log_f32_e32 v1, v1
	s_nop 0
	v_mul_f32_e32 v2, 0x3f317217, v1
	v_fma_f32 v2, v1, s11, -v2
	v_fmac_f32_e32 v2, 0x3377d1cf, v1
	v_fmac_f32_e32 v2, 0x3f317217, v1
	v_cmp_lt_f32_e64 s[44:45], |v1|, s12
	s_nop 1
	v_cndmask_b32_e64 v1, v1, v2, s[44:45]
	v_cndmask_b32_e64 v2, 0, v163, s[0:1]
	v_sub_f32_e32 v1, v1, v2
	v_sub_f32_e32 v0, v0, v1
	v_mul_f32_e32 v0, 0x3d800000, v0
	v_cndmask_b32_e32 v0, 0, v0, vcc
	v_add_f32_e32 v41, v39, v0
	v_mul_f32_e32 v0, 0x3fb8aa3b, v41
	v_exp_f32_e32 v0, v0
	v_mul_f32_e32 v1, 0xbfb8aa3b, v41
	v_exp_f32_e32 v1, v1
	v_mov_b32_e32 v39, 0
	v_mul_f32_e32 v0, v0, v42
	v_mul_f32_e32 v0, 0x3db504f3, v0
	v_bfe_u32 v2, v0, 16, 1
	v_add3_u32 v0, v0, v2, s33
	ds_write_b16_d16_hi v37, v0 offset:272
	v_mul_f32_e32 v0, v1, v40
	v_bfe_u32 v1, v0, 16, 1
	v_add3_u32 v0, v0, v1, s33
	ds_write_b16_d16_hi v37, v0 offset:17680
	ds_read_b128 v[12:15], v36 offset:128
	ds_read_b128 v[8:11], v36 offset:144
	ds_read_b128 v[4:7], v36 offset:160
	ds_read_b128 v[0:3], v36 offset:176
	v_add_u32_e32 v40, 2, v38
	v_cmp_gt_i32_e32 vcc, s92, v40
	v_mov_b32_e32 v42, 0
	s_and_saveexec_b64 s[0:1], vcc
	s_cbranch_execz .Lgc_c1
	s_waitcnt vmcnt(50)
	v_lshlrev_b32_e32 v42, 16, v56
	v_lshlrev_b32_e32 v43, 16, v57
.Lgc_c1:
	s_or_b64 exec, exec, s[0:1]
	s_waitcnt lgkmcnt(3)
	v_mul_f32_e32 v13, v18, v13
	v_fmac_f32_e32 v13, v16, v12
	s_waitcnt lgkmcnt(2)
	v_mul_f32_e32 v9, v19, v9
	v_fmac_f32_e32 v13, v20, v14
	v_fmac_f32_e32 v9, v17, v8
	s_waitcnt lgkmcnt(1)
	v_mul_f32_e32 v5, v26, v5
	v_fmac_f32_e32 v13, v22, v15
	v_fmac_f32_e32 v9, v21, v10
	v_fmac_f32_e32 v5, v24, v4
	s_waitcnt lgkmcnt(0)
	v_mul_f32_e32 v1, v27, v1
	v_add_f32_e32 v12, v34, v13
	v_fmac_f32_e32 v9, v23, v11
	v_fmac_f32_e32 v5, v28, v6
	v_fmac_f32_e32 v1, v25, v0
	v_add_f32_e32 v8, v12, v9
	v_fmac_f32_e32 v5, v30, v7
	v_fmac_f32_e32 v1, v29, v2
	v_add_f32_e32 v4, v8, v5
	v_fmac_f32_e32 v1, v31, v3
	v_add_f32_e32 v0, v4, v1
	v_mul_f32_e64 v1, |v0|, s10
	v_exp_f32_e32 v1, v1
	v_min_f32_e32 v0, 0, v0
	v_add_u32_e32 v38, 3, v38
	v_add_f32_e32 v1, 1.0, v1
	v_cmp_gt_f32_e64 s[0:1], s8, v1
	s_nop 1
	v_cndmask_b32_e64 v2, 0, 32, s[0:1]
	v_ldexp_f32 v1, v1, v2
	v_log_f32_e32 v1, v1
	s_nop 0
	v_mul_f32_e32 v2, 0x3f317217, v1
	v_fma_f32 v2, v1, s11, -v2
	v_fmac_f32_e32 v2, 0x3377d1cf, v1
	v_fmac_f32_e32 v2, 0x3f317217, v1
	v_cmp_lt_f32_e64 s[44:45], |v1|, s12
	s_nop 1
	v_cndmask_b32_e64 v1, v1, v2, s[44:45]
	v_cndmask_b32_e64 v2, 0, v163, s[0:1]
	v_sub_f32_e32 v1, v1, v2
	v_sub_f32_e32 v0, v0, v1
	v_mul_f32_e32 v0, 0x3d800000, v0
	v_cndmask_b32_e32 v0, 0, v0, vcc
	v_add_f32_e32 v40, v41, v0
	v_mul_f32_e32 v0, 0x3fb8aa3b, v40
	v_exp_f32_e32 v0, v0
	v_mul_f32_e32 v1, 0xbfb8aa3b, v40
	v_exp_f32_e32 v1, v1
	v_cmp_gt_i32_e32 vcc, s92, v38
	v_mul_f32_e32 v0, v0, v43
	v_mul_f32_e32 v0, 0x3db504f3, v0
	v_bfe_u32 v2, v0, 16, 1
	v_add3_u32 v0, v0, v2, s33
	ds_write_b16_d16_hi v37, v0 offset:544
	v_mul_f32_e32 v0, v1, v42
	v_bfe_u32 v1, v0, 16, 1
	v_add3_u32 v0, v0, v1, s33
	ds_write_b16_d16_hi v37, v0 offset:17952
	ds_read_b128 v[12:15], v36 offset:192
	ds_read_b128 v[8:11], v36 offset:208
	ds_read_b128 v[4:7], v36 offset:224
	ds_read_b128 v[0:3], v36 offset:240
	v_mov_b32_e32 v38, 0
	s_and_saveexec_b64 s[0:1], vcc
	s_cbranch_execz .Lgc_l1
	s_waitcnt vmcnt(48)
	v_lshlrev_b32_e32 v39, 16, v58
	v_lshlrev_b32_e32 v38, 16, v59
	s_branch .Lgc_l1

.Lgc_h2:
	ds_read_b128 v[12:15], v36
	ds_read_b128 v[8:11], v36 offset:16
	ds_read_b128 v[4:7], v36 offset:32
	ds_read_b128 v[0:3], v36 offset:48
	v_add_u32_e32 v38, s95, v121
	v_cmp_gt_i32_e32 vcc, s92, v38
	v_mov_b32_e32 v40, 0
	v_mov_b32_e32 v42, 0
	v_mov_b32_e32 v43, 0
	s_and_saveexec_b64 s[0:1], vcc
	s_cbranch_execz .Lgc_a2
	s_waitcnt vmcnt(46)
	v_lshlrev_b32_e32 v42, 16, v60
	v_lshlrev_b32_e32 v43, 16, v61
.Lgc_a2:
	s_or_b64 exec, exec, s[0:1]
	s_waitcnt lgkmcnt(3)
	v_mul_f32_e32 v13, v18, v13
	v_fmac_f32_e32 v13, v16, v12
	s_waitcnt lgkmcnt(2)
	v_mul_f32_e32 v9, v19, v9
	v_fmac_f32_e32 v13, v20, v14
	v_fmac_f32_e32 v9, v17, v8
	s_waitcnt lgkmcnt(1)
	v_mul_f32_e32 v5, v26, v5
	v_fmac_f32_e32 v13, v22, v15
	v_fmac_f32_e32 v9, v21, v10
	v_fmac_f32_e32 v5, v24, v4
	s_waitcnt lgkmcnt(0)
	v_mul_f32_e32 v1, v27, v1
	v_add_f32_e32 v12, v34, v13
	v_fmac_f32_e32 v9, v23, v11
	v_fmac_f32_e32 v5, v28, v6
	v_fmac_f32_e32 v1, v25, v0
	v_add_f32_e32 v8, v12, v9
	v_fmac_f32_e32 v5, v30, v7
	v_fmac_f32_e32 v1, v29, v2
	v_add_f32_e32 v4, v8, v5
	v_fmac_f32_e32 v1, v31, v3
	v_add_f32_e32 v0, v4, v1
	v_mul_f32_e64 v1, |v0|, s10
	v_exp_f32_e32 v1, v1
	v_min_f32_e32 v0, 0, v0
	v_add_f32_e32 v1, 1.0, v1
	v_cmp_gt_f32_e64 s[0:1], s8, v1
	s_nop 1
	v_cndmask_b32_e64 v2, 0, 32, s[0:1]
	v_ldexp_f32 v1, v1, v2
	v_log_f32_e32 v1, v1
	s_nop 0
	v_mul_f32_e32 v2, 0x3f317217, v1
	v_fma_f32 v2, v1, s11, -v2
	v_fmac_f32_e32 v2, 0x3377d1cf, v1
	v_fmac_f32_e32 v2, 0x3f317217, v1
	v_cmp_lt_f32_e64 s[44:45], |v1|, s12
	s_nop 1
	v_cndmask_b32_e64 v1, v1, v2, s[44:45]
	v_cndmask_b32_e64 v2, 0, v163, s[0:1]
	v_sub_f32_e32 v1, v1, v2
	v_sub_f32_e32 v0, v0, v1
	v_mul_f32_e32 v0, 0x3d800000, v0
	v_cndmask_b32_e32 v0, 0, v0, vcc
	v_add_f32_e32 v39, v41, v0
	v_mul_f32_e32 v0, 0x3fb8aa3b, v39
	v_exp_f32_e32 v0, v0
	v_mul_f32_e32 v1, 0xbfb8aa3b, v39
	v_exp_f32_e32 v1, v1
	v_add_u32_e32 v41, 1, v38
	v_mul_f32_e32 v0, v0, v43
	v_mul_f32_e32 v0, 0x3db504f3, v0
	v_bfe_u32 v2, v0, 16, 1
	v_add3_u32 v0, v0, v2, s33
	ds_write_b16_d16_hi v37, v0
	v_mul_f32_e32 v0, v1, v42
	v_bfe_u32 v1, v0, 16, 1
	v_add3_u32 v0, v0, v1, s33
	ds_write_b16_d16_hi v37, v0 offset:17408
	ds_read_b128 v[12:15], v36 offset:64
	ds_read_b128 v[8:11], v36 offset:80
	ds_read_b128 v[4:7], v36 offset:96
	ds_read_b128 v[0:3], v36 offset:112
	v_cmp_gt_i32_e32 vcc, s92, v41
	v_mov_b32_e32 v42, 0
	s_and_saveexec_b64 s[0:1], vcc
	s_cbranch_execz .Lgc_b2
	s_waitcnt vmcnt(44)
	v_lshlrev_b32_e32 v40, 16, v62
	v_lshlrev_b32_e32 v42, 16, v63
.Lgc_b2:
	s_or_b64 exec, exec, s[0:1]
	s_waitcnt lgkmcnt(3)
	v_mul_f32_e32 v13, v18, v13
	v_fmac_f32_e32 v13, v16, v12
	s_waitcnt lgkmcnt(2)
	v_mul_f32_e32 v9, v19, v9
	v_fmac_f32_e32 v13, v20, v14
	v_fmac_f32_e32 v9, v17, v8
	s_waitcnt lgkmcnt(1)
	v_mul_f32_e32 v5, v26, v5
	v_fmac_f32_e32 v13, v22, v15
	v_fmac_f32_e32 v9, v21, v10
	v_fmac_f32_e32 v5, v24, v4
	s_waitcnt lgkmcnt(0)
	v_mul_f32_e32 v1, v27, v1
	v_add_f32_e32 v12, v34, v13
	v_fmac_f32_e32 v9, v23, v11
	v_fmac_f32_e32 v5, v28, v6
	v_fmac_f32_e32 v1, v25, v0
	v_add_f32_e32 v8, v12, v9
	v_fmac_f32_e32 v5, v30, v7
	v_fmac_f32_e32 v1, v29, v2
	v_add_f32_e32 v4, v8, v5
	v_fmac_f32_e32 v1, v31, v3
	v_add_f32_e32 v0, v4, v1
	v_mul_f32_e64 v1, |v0|, s10
	v_exp_f32_e32 v1, v1
	v_min_f32_e32 v0, 0, v0
	v_mov_b32_e32 v43, 0
	v_add_f32_e32 v1, 1.0, v1
	v_cmp_gt_f32_e64 s[0:1], s8, v1
	s_nop 1
	v_cndmask_b32_e64 v2, 0, 32, s[0:1]
	v_ldexp_f32 v1, v1, v2
	v_log_f32_e32 v1, v1
	s_nop 0
	v_mul_f32_e32 v2, 0x3f317217, v1
	v_fma_f32 v2, v1, s11, -v2
	v_fmac_f32_e32 v2, 0x3377d1cf, v1
	v_fmac_f32_e32 v2, 0x3f317217, v1
	v_cmp_lt_f32_e64 s[44:45], |v1|, s12
	s_nop 1
	v_cndmask_b32_e64 v1, v1, v2, s[44:45]
	v_cndmask_b32_e64 v2, 0, v163, s[0:1]
	v_sub_f32_e32 v1, v1, v2
	v_sub_f32_e32 v0, v0, v1
	v_mul_f32_e32 v0, 0x3d800000, v0
	v_cndmask_b32_e32 v0, 0, v0, vcc
	v_add_f32_e32 v41, v39, v0
	v_mul_f32_e32 v0, 0x3fb8aa3b, v41
	v_exp_f32_e32 v0, v0
	v_mul_f32_e32 v1, 0xbfb8aa3b, v41
	v_exp_f32_e32 v1, v1
	v_mov_b32_e32 v39, 0
	v_mul_f32_e32 v0, v0, v42
	v_mul_f32_e32 v0, 0x3db504f3, v0
	v_bfe_u32 v2, v0, 16, 1
	v_add3_u32 v0, v0, v2, s33
	ds_write_b16_d16_hi v37, v0 offset:272
	v_mul_f32_e32 v0, v1, v40
	v_bfe_u32 v1, v0, 16, 1
	v_add3_u32 v0, v0, v1, s33
	ds_write_b16_d16_hi v37, v0 offset:17680
	ds_read_b128 v[12:15], v36 offset:128
	ds_read_b128 v[8:11], v36 offset:144
	ds_read_b128 v[4:7], v36 offset:160
	ds_read_b128 v[0:3], v36 offset:176
	v_add_u32_e32 v40, 2, v38
	v_cmp_gt_i32_e32 vcc, s92, v40
	v_mov_b32_e32 v42, 0
	s_and_saveexec_b64 s[0:1], vcc
	s_cbranch_execz .Lgc_c2
	s_waitcnt vmcnt(42)
	v_lshlrev_b32_e32 v42, 16, v102
	v_lshlrev_b32_e32 v43, 16, v103
.Lgc_c2:
	s_or_b64 exec, exec, s[0:1]
	s_waitcnt lgkmcnt(3)
	v_mul_f32_e32 v13, v18, v13
	v_fmac_f32_e32 v13, v16, v12
	s_waitcnt lgkmcnt(2)
	v_mul_f32_e32 v9, v19, v9
	v_fmac_f32_e32 v13, v20, v14
	v_fmac_f32_e32 v9, v17, v8
	s_waitcnt lgkmcnt(1)
	v_mul_f32_e32 v5, v26, v5
	v_fmac_f32_e32 v13, v22, v15
	v_fmac_f32_e32 v9, v21, v10
	v_fmac_f32_e32 v5, v24, v4
	s_waitcnt lgkmcnt(0)
	v_mul_f32_e32 v1, v27, v1
	v_add_f32_e32 v12, v34, v13
	v_fmac_f32_e32 v9, v23, v11
	v_fmac_f32_e32 v5, v28, v6
	v_fmac_f32_e32 v1, v25, v0
	v_add_f32_e32 v8, v12, v9
	v_fmac_f32_e32 v5, v30, v7
	v_fmac_f32_e32 v1, v29, v2
	v_add_f32_e32 v4, v8, v5
	v_fmac_f32_e32 v1, v31, v3
	v_add_f32_e32 v0, v4, v1
	v_mul_f32_e64 v1, |v0|, s10
	v_exp_f32_e32 v1, v1
	v_min_f32_e32 v0, 0, v0
	v_add_u32_e32 v38, 3, v38
	v_add_f32_e32 v1, 1.0, v1
	v_cmp_gt_f32_e64 s[0:1], s8, v1
	s_nop 1
	v_cndmask_b32_e64 v2, 0, 32, s[0:1]
	v_ldexp_f32 v1, v1, v2
	v_log_f32_e32 v1, v1
	s_nop 0
	v_mul_f32_e32 v2, 0x3f317217, v1
	v_fma_f32 v2, v1, s11, -v2
	v_fmac_f32_e32 v2, 0x3377d1cf, v1
	v_fmac_f32_e32 v2, 0x3f317217, v1
	v_cmp_lt_f32_e64 s[44:45], |v1|, s12
	s_nop 1
	v_cndmask_b32_e64 v1, v1, v2, s[44:45]
	v_cndmask_b32_e64 v2, 0, v163, s[0:1]
	v_sub_f32_e32 v1, v1, v2
	v_sub_f32_e32 v0, v0, v1
	v_mul_f32_e32 v0, 0x3d800000, v0
	v_cndmask_b32_e32 v0, 0, v0, vcc
	v_add_f32_e32 v40, v41, v0
	v_mul_f32_e32 v0, 0x3fb8aa3b, v40
	v_exp_f32_e32 v0, v0
	v_mul_f32_e32 v1, 0xbfb8aa3b, v40
	v_exp_f32_e32 v1, v1
	v_cmp_gt_i32_e32 vcc, s92, v38
	v_mul_f32_e32 v0, v0, v43
	v_mul_f32_e32 v0, 0x3db504f3, v0
	v_bfe_u32 v2, v0, 16, 1
	v_add3_u32 v0, v0, v2, s33
	ds_write_b16_d16_hi v37, v0 offset:544
	v_mul_f32_e32 v0, v1, v42
	v_bfe_u32 v1, v0, 16, 1
	v_add3_u32 v0, v0, v1, s33
	ds_write_b16_d16_hi v37, v0 offset:17952
	ds_read_b128 v[12:15], v36 offset:192
	ds_read_b128 v[8:11], v36 offset:208
	ds_read_b128 v[4:7], v36 offset:224
	ds_read_b128 v[0:3], v36 offset:240
	v_mov_b32_e32 v38, 0
	s_and_saveexec_b64 s[0:1], vcc
	s_cbranch_execz .Lgc_l2
	s_waitcnt vmcnt(40)
	v_lshlrev_b32_e32 v39, 16, v104
	v_lshlrev_b32_e32 v38, 16, v105
	s_branch .Lgc_l2

.Lgc_h3:
	ds_read_b128 v[12:15], v36
	ds_read_b128 v[8:11], v36 offset:16
	ds_read_b128 v[4:7], v36 offset:32
	ds_read_b128 v[0:3], v36 offset:48
	v_add_u32_e32 v38, s95, v121
	v_cmp_gt_i32_e32 vcc, s92, v38
	v_mov_b32_e32 v40, 0
	v_mov_b32_e32 v42, 0
	v_mov_b32_e32 v43, 0
	s_and_saveexec_b64 s[0:1], vcc
	s_cbranch_execz .Lgc_a3
	s_waitcnt vmcnt(38)
	v_lshlrev_b32_e32 v42, 16, v106
	v_lshlrev_b32_e32 v43, 16, v107
.Lgc_a3:
	s_or_b64 exec, exec, s[0:1]
	s_waitcnt lgkmcnt(3)
	v_mul_f32_e32 v13, v18, v13
	v_fmac_f32_e32 v13, v16, v12
	s_waitcnt lgkmcnt(2)
	v_mul_f32_e32 v9, v19, v9
	v_fmac_f32_e32 v13, v20, v14
	v_fmac_f32_e32 v9, v17, v8
	s_waitcnt lgkmcnt(1)
	v_mul_f32_e32 v5, v26, v5
	v_fmac_f32_e32 v13, v22, v15
	v_fmac_f32_e32 v9, v21, v10
	v_fmac_f32_e32 v5, v24, v4
	s_waitcnt lgkmcnt(0)
	v_mul_f32_e32 v1, v27, v1
	v_add_f32_e32 v12, v34, v13
	v_fmac_f32_e32 v9, v23, v11
	v_fmac_f32_e32 v5, v28, v6
	v_fmac_f32_e32 v1, v25, v0
	v_add_f32_e32 v8, v12, v9
	v_fmac_f32_e32 v5, v30, v7
	v_fmac_f32_e32 v1, v29, v2
	v_add_f32_e32 v4, v8, v5
	v_fmac_f32_e32 v1, v31, v3
	v_add_f32_e32 v0, v4, v1
	v_mul_f32_e64 v1, |v0|, s10
	v_exp_f32_e32 v1, v1
	v_min_f32_e32 v0, 0, v0
	v_add_f32_e32 v1, 1.0, v1
	v_cmp_gt_f32_e64 s[0:1], s8, v1
	s_nop 1
	v_cndmask_b32_e64 v2, 0, 32, s[0:1]
	v_ldexp_f32 v1, v1, v2
	v_log_f32_e32 v1, v1
	s_nop 0
	v_mul_f32_e32 v2, 0x3f317217, v1
	v_fma_f32 v2, v1, s11, -v2
	v_fmac_f32_e32 v2, 0x3377d1cf, v1
	v_fmac_f32_e32 v2, 0x3f317217, v1
	v_cmp_lt_f32_e64 s[44:45], |v1|, s12
	s_nop 1
	v_cndmask_b32_e64 v1, v1, v2, s[44:45]
	v_cndmask_b32_e64 v2, 0, v163, s[0:1]
	v_sub_f32_e32 v1, v1, v2
	v_sub_f32_e32 v0, v0, v1
	v_mul_f32_e32 v0, 0x3d800000, v0
	v_cndmask_b32_e32 v0, 0, v0, vcc
	v_add_f32_e32 v39, v41, v0
	v_mul_f32_e32 v0, 0x3fb8aa3b, v39
	v_exp_f32_e32 v0, v0
	v_mul_f32_e32 v1, 0xbfb8aa3b, v39
	v_exp_f32_e32 v1, v1
	v_add_u32_e32 v41, 1, v38
	v_mul_f32_e32 v0, v0, v43
	v_mul_f32_e32 v0, 0x3db504f3, v0
	v_bfe_u32 v2, v0, 16, 1
	v_add3_u32 v0, v0, v2, s33
	ds_write_b16_d16_hi v37, v0
	v_mul_f32_e32 v0, v1, v42
	v_bfe_u32 v1, v0, 16, 1
	v_add3_u32 v0, v0, v1, s33
	ds_write_b16_d16_hi v37, v0 offset:17408
	ds_read_b128 v[12:15], v36 offset:64
	ds_read_b128 v[8:11], v36 offset:80
	ds_read_b128 v[4:7], v36 offset:96
	ds_read_b128 v[0:3], v36 offset:112
	v_cmp_gt_i32_e32 vcc, s92, v41
	v_mov_b32_e32 v42, 0
	s_and_saveexec_b64 s[0:1], vcc
	s_cbranch_execz .Lgc_b3
	s_waitcnt vmcnt(36)
	v_lshlrev_b32_e32 v40, 16, v108
	v_lshlrev_b32_e32 v42, 16, v109
.Lgc_b3:
	s_or_b64 exec, exec, s[0:1]
	s_waitcnt lgkmcnt(3)
	v_mul_f32_e32 v13, v18, v13
	v_fmac_f32_e32 v13, v16, v12
	s_waitcnt lgkmcnt(2)
	v_mul_f32_e32 v9, v19, v9
	v_fmac_f32_e32 v13, v20, v14
	v_fmac_f32_e32 v9, v17, v8
	s_waitcnt lgkmcnt(1)
	v_mul_f32_e32 v5, v26, v5
	v_fmac_f32_e32 v13, v22, v15
	v_fmac_f32_e32 v9, v21, v10
	v_fmac_f32_e32 v5, v24, v4
	s_waitcnt lgkmcnt(0)
	v_mul_f32_e32 v1, v27, v1
	v_add_f32_e32 v12, v34, v13
	v_fmac_f32_e32 v9, v23, v11
	v_fmac_f32_e32 v5, v28, v6
	v_fmac_f32_e32 v1, v25, v0
	v_add_f32_e32 v8, v12, v9
	v_fmac_f32_e32 v5, v30, v7
	v_fmac_f32_e32 v1, v29, v2
	v_add_f32_e32 v4, v8, v5
	v_fmac_f32_e32 v1, v31, v3
	v_add_f32_e32 v0, v4, v1
	v_mul_f32_e64 v1, |v0|, s10
	v_exp_f32_e32 v1, v1
	v_min_f32_e32 v0, 0, v0
	v_mov_b32_e32 v43, 0
	v_add_f32_e32 v1, 1.0, v1
	v_cmp_gt_f32_e64 s[0:1], s8, v1
	s_nop 1
	v_cndmask_b32_e64 v2, 0, 32, s[0:1]
	v_ldexp_f32 v1, v1, v2
	v_log_f32_e32 v1, v1
	s_nop 0
	v_mul_f32_e32 v2, 0x3f317217, v1
	v_fma_f32 v2, v1, s11, -v2
	v_fmac_f32_e32 v2, 0x3377d1cf, v1
	v_fmac_f32_e32 v2, 0x3f317217, v1
	v_cmp_lt_f32_e64 s[44:45], |v1|, s12
	s_nop 1
	v_cndmask_b32_e64 v1, v1, v2, s[44:45]
	v_cndmask_b32_e64 v2, 0, v163, s[0:1]
	v_sub_f32_e32 v1, v1, v2
	v_sub_f32_e32 v0, v0, v1
	v_mul_f32_e32 v0, 0x3d800000, v0
	v_cndmask_b32_e32 v0, 0, v0, vcc
	v_add_f32_e32 v41, v39, v0
	v_mul_f32_e32 v0, 0x3fb8aa3b, v41
	v_exp_f32_e32 v0, v0
	v_mul_f32_e32 v1, 0xbfb8aa3b, v41
	v_exp_f32_e32 v1, v1
	v_mov_b32_e32 v39, 0
	v_mul_f32_e32 v0, v0, v42
	v_mul_f32_e32 v0, 0x3db504f3, v0
	v_bfe_u32 v2, v0, 16, 1
	v_add3_u32 v0, v0, v2, s33
	ds_write_b16_d16_hi v37, v0 offset:272
	v_mul_f32_e32 v0, v1, v40
	v_bfe_u32 v1, v0, 16, 1
	v_add3_u32 v0, v0, v1, s33
	ds_write_b16_d16_hi v37, v0 offset:17680
	ds_read_b128 v[12:15], v36 offset:128
	ds_read_b128 v[8:11], v36 offset:144
	ds_read_b128 v[4:7], v36 offset:160
	ds_read_b128 v[0:3], v36 offset:176
	v_add_u32_e32 v40, 2, v38
	v_cmp_gt_i32_e32 vcc, s92, v40
	v_mov_b32_e32 v42, 0
	s_and_saveexec_b64 s[0:1], vcc
	s_cbranch_execz .Lgc_c3
	s_waitcnt vmcnt(34)
	v_lshlrev_b32_e32 v42, 16, v110
	v_lshlrev_b32_e32 v43, 16, v111
.Lgc_c3:
	s_or_b64 exec, exec, s[0:1]
	s_waitcnt lgkmcnt(3)
	v_mul_f32_e32 v13, v18, v13
	v_fmac_f32_e32 v13, v16, v12
	s_waitcnt lgkmcnt(2)
	v_mul_f32_e32 v9, v19, v9
	v_fmac_f32_e32 v13, v20, v14
	v_fmac_f32_e32 v9, v17, v8
	s_waitcnt lgkmcnt(1)
	v_mul_f32_e32 v5, v26, v5
	v_fmac_f32_e32 v13, v22, v15
	v_fmac_f32_e32 v9, v21, v10
	v_fmac_f32_e32 v5, v24, v4
	s_waitcnt lgkmcnt(0)
	v_mul_f32_e32 v1, v27, v1
	v_add_f32_e32 v12, v34, v13
	v_fmac_f32_e32 v9, v23, v11
	v_fmac_f32_e32 v5, v28, v6
	v_fmac_f32_e32 v1, v25, v0
	v_add_f32_e32 v8, v12, v9
	v_fmac_f32_e32 v5, v30, v7
	v_fmac_f32_e32 v1, v29, v2
	v_add_f32_e32 v4, v8, v5
	v_fmac_f32_e32 v1, v31, v3
	v_add_f32_e32 v0, v4, v1
	v_mul_f32_e64 v1, |v0|, s10
	v_exp_f32_e32 v1, v1
	v_min_f32_e32 v0, 0, v0
	v_add_u32_e32 v38, 3, v38
	v_add_f32_e32 v1, 1.0, v1
	v_cmp_gt_f32_e64 s[0:1], s8, v1
	s_nop 1
	v_cndmask_b32_e64 v2, 0, 32, s[0:1]
	v_ldexp_f32 v1, v1, v2
	v_log_f32_e32 v1, v1
	s_nop 0
	v_mul_f32_e32 v2, 0x3f317217, v1
	v_fma_f32 v2, v1, s11, -v2
	v_fmac_f32_e32 v2, 0x3377d1cf, v1
	v_fmac_f32_e32 v2, 0x3f317217, v1
	v_cmp_lt_f32_e64 s[44:45], |v1|, s12
	s_nop 1
	v_cndmask_b32_e64 v1, v1, v2, s[44:45]
	v_cndmask_b32_e64 v2, 0, v163, s[0:1]
	v_sub_f32_e32 v1, v1, v2
	v_sub_f32_e32 v0, v0, v1
	v_mul_f32_e32 v0, 0x3d800000, v0
	v_cndmask_b32_e32 v0, 0, v0, vcc
	v_add_f32_e32 v40, v41, v0
	v_mul_f32_e32 v0, 0x3fb8aa3b, v40
	v_exp_f32_e32 v0, v0
	v_mul_f32_e32 v1, 0xbfb8aa3b, v40
	v_exp_f32_e32 v1, v1
	v_cmp_gt_i32_e32 vcc, s92, v38
	v_mul_f32_e32 v0, v0, v43
	v_mul_f32_e32 v0, 0x3db504f3, v0
	v_bfe_u32 v2, v0, 16, 1
	v_add3_u32 v0, v0, v2, s33
	ds_write_b16_d16_hi v37, v0 offset:544
	v_mul_f32_e32 v0, v1, v42
	v_bfe_u32 v1, v0, 16, 1
	v_add3_u32 v0, v0, v1, s33
	ds_write_b16_d16_hi v37, v0 offset:17952
	ds_read_b128 v[12:15], v36 offset:192
	ds_read_b128 v[8:11], v36 offset:208
	ds_read_b128 v[4:7], v36 offset:224
	ds_read_b128 v[0:3], v36 offset:240
	v_mov_b32_e32 v38, 0
	s_and_saveexec_b64 s[0:1], vcc
	s_cbranch_execz .Lgc_l3
	s_waitcnt vmcnt(32)
	v_lshlrev_b32_e32 v39, 16, v209
	v_lshlrev_b32_e32 v38, 16, v210
	s_branch .Lgc_l3

.Lgc_h4:
	ds_read_b128 v[12:15], v36
	ds_read_b128 v[8:11], v36 offset:16
	ds_read_b128 v[4:7], v36 offset:32
	ds_read_b128 v[0:3], v36 offset:48
	v_add_u32_e32 v38, s95, v121
	v_cmp_gt_i32_e32 vcc, s92, v38
	v_mov_b32_e32 v40, 0
	v_mov_b32_e32 v42, 0
	v_mov_b32_e32 v43, 0
	s_and_saveexec_b64 s[0:1], vcc
	s_cbranch_execz .Lgc_a4
	s_waitcnt vmcnt(30)
	v_lshlrev_b32_e32 v42, 16, v211
	v_lshlrev_b32_e32 v43, 16, v212
.Lgc_a4:
	s_or_b64 exec, exec, s[0:1]
	s_waitcnt lgkmcnt(3)
	v_mul_f32_e32 v13, v18, v13
	v_fmac_f32_e32 v13, v16, v12
	s_waitcnt lgkmcnt(2)
	v_mul_f32_e32 v9, v19, v9
	v_fmac_f32_e32 v13, v20, v14
	v_fmac_f32_e32 v9, v17, v8
	s_waitcnt lgkmcnt(1)
	v_mul_f32_e32 v5, v26, v5
	v_fmac_f32_e32 v13, v22, v15
	v_fmac_f32_e32 v9, v21, v10
	v_fmac_f32_e32 v5, v24, v4
	s_waitcnt lgkmcnt(0)
	v_mul_f32_e32 v1, v27, v1
	v_add_f32_e32 v12, v34, v13
	v_fmac_f32_e32 v9, v23, v11
	v_fmac_f32_e32 v5, v28, v6
	v_fmac_f32_e32 v1, v25, v0
	v_add_f32_e32 v8, v12, v9
	v_fmac_f32_e32 v5, v30, v7
	v_fmac_f32_e32 v1, v29, v2
	v_add_f32_e32 v4, v8, v5
	v_fmac_f32_e32 v1, v31, v3
	v_add_f32_e32 v0, v4, v1
	v_mul_f32_e64 v1, |v0|, s10
	v_exp_f32_e32 v1, v1
	v_min_f32_e32 v0, 0, v0
	v_add_f32_e32 v1, 1.0, v1
	v_cmp_gt_f32_e64 s[0:1], s8, v1
	s_nop 1
	v_cndmask_b32_e64 v2, 0, 32, s[0:1]
	v_ldexp_f32 v1, v1, v2
	v_log_f32_e32 v1, v1
	s_nop 0
	v_mul_f32_e32 v2, 0x3f317217, v1
	v_fma_f32 v2, v1, s11, -v2
	v_fmac_f32_e32 v2, 0x3377d1cf, v1
	v_fmac_f32_e32 v2, 0x3f317217, v1
	v_cmp_lt_f32_e64 s[44:45], |v1|, s12
	s_nop 1
	v_cndmask_b32_e64 v1, v1, v2, s[44:45]
	v_cndmask_b32_e64 v2, 0, v163, s[0:1]
	v_sub_f32_e32 v1, v1, v2
	v_sub_f32_e32 v0, v0, v1
	v_mul_f32_e32 v0, 0x3d800000, v0
	v_cndmask_b32_e32 v0, 0, v0, vcc
	v_add_f32_e32 v39, v41, v0
	v_mul_f32_e32 v0, 0x3fb8aa3b, v39
	v_exp_f32_e32 v0, v0
	v_mul_f32_e32 v1, 0xbfb8aa3b, v39
	v_exp_f32_e32 v1, v1
	v_add_u32_e32 v41, 1, v38
	v_mul_f32_e32 v0, v0, v43
	v_mul_f32_e32 v0, 0x3db504f3, v0
	v_bfe_u32 v2, v0, 16, 1
	v_add3_u32 v0, v0, v2, s33
	ds_write_b16_d16_hi v37, v0
	v_mul_f32_e32 v0, v1, v42
	v_bfe_u32 v1, v0, 16, 1
	v_add3_u32 v0, v0, v1, s33
	ds_write_b16_d16_hi v37, v0 offset:17408
	ds_read_b128 v[12:15], v36 offset:64
	ds_read_b128 v[8:11], v36 offset:80
	ds_read_b128 v[4:7], v36 offset:96
	ds_read_b128 v[0:3], v36 offset:112
	v_cmp_gt_i32_e32 vcc, s92, v41
	v_mov_b32_e32 v42, 0
	s_and_saveexec_b64 s[0:1], vcc
	s_cbranch_execz .Lgc_b4
	s_waitcnt vmcnt(28)
	v_lshlrev_b32_e32 v40, 16, v213
	v_lshlrev_b32_e32 v42, 16, v214
.Lgc_b4:
	s_or_b64 exec, exec, s[0:1]
	s_waitcnt lgkmcnt(3)
	v_mul_f32_e32 v13, v18, v13
	v_fmac_f32_e32 v13, v16, v12
	s_waitcnt lgkmcnt(2)
	v_mul_f32_e32 v9, v19, v9
	v_fmac_f32_e32 v13, v20, v14
	v_fmac_f32_e32 v9, v17, v8
	s_waitcnt lgkmcnt(1)
	v_mul_f32_e32 v5, v26, v5
	v_fmac_f32_e32 v13, v22, v15
	v_fmac_f32_e32 v9, v21, v10
	v_fmac_f32_e32 v5, v24, v4
	s_waitcnt lgkmcnt(0)
	v_mul_f32_e32 v1, v27, v1
	v_add_f32_e32 v12, v34, v13
	v_fmac_f32_e32 v9, v23, v11
	v_fmac_f32_e32 v5, v28, v6
	v_fmac_f32_e32 v1, v25, v0
	v_add_f32_e32 v8, v12, v9
	v_fmac_f32_e32 v5, v30, v7
	v_fmac_f32_e32 v1, v29, v2
	v_add_f32_e32 v4, v8, v5
	v_fmac_f32_e32 v1, v31, v3
	v_add_f32_e32 v0, v4, v1
	v_mul_f32_e64 v1, |v0|, s10
	v_exp_f32_e32 v1, v1
	v_min_f32_e32 v0, 0, v0
	v_mov_b32_e32 v43, 0
	v_add_f32_e32 v1, 1.0, v1
	v_cmp_gt_f32_e64 s[0:1], s8, v1
	s_nop 1
	v_cndmask_b32_e64 v2, 0, 32, s[0:1]
	v_ldexp_f32 v1, v1, v2
	v_log_f32_e32 v1, v1
	s_nop 0
	v_mul_f32_e32 v2, 0x3f317217, v1
	v_fma_f32 v2, v1, s11, -v2
	v_fmac_f32_e32 v2, 0x3377d1cf, v1
	v_fmac_f32_e32 v2, 0x3f317217, v1
	v_cmp_lt_f32_e64 s[44:45], |v1|, s12
	s_nop 1
	v_cndmask_b32_e64 v1, v1, v2, s[44:45]
	v_cndmask_b32_e64 v2, 0, v163, s[0:1]
	v_sub_f32_e32 v1, v1, v2
	v_sub_f32_e32 v0, v0, v1
	v_mul_f32_e32 v0, 0x3d800000, v0
	v_cndmask_b32_e32 v0, 0, v0, vcc
	v_add_f32_e32 v41, v39, v0
	v_mul_f32_e32 v0, 0x3fb8aa3b, v41
	v_exp_f32_e32 v0, v0
	v_mul_f32_e32 v1, 0xbfb8aa3b, v41
	v_exp_f32_e32 v1, v1
	v_mov_b32_e32 v39, 0
	v_mul_f32_e32 v0, v0, v42
	v_mul_f32_e32 v0, 0x3db504f3, v0
	v_bfe_u32 v2, v0, 16, 1
	v_add3_u32 v0, v0, v2, s33
	ds_write_b16_d16_hi v37, v0 offset:272
	v_mul_f32_e32 v0, v1, v40
	v_bfe_u32 v1, v0, 16, 1
	v_add3_u32 v0, v0, v1, s33
	ds_write_b16_d16_hi v37, v0 offset:17680
	ds_read_b128 v[12:15], v36 offset:128
	ds_read_b128 v[8:11], v36 offset:144
	ds_read_b128 v[4:7], v36 offset:160
	ds_read_b128 v[0:3], v36 offset:176
	v_add_u32_e32 v40, 2, v38
	v_cmp_gt_i32_e32 vcc, s92, v40
	v_mov_b32_e32 v42, 0
	s_and_saveexec_b64 s[0:1], vcc
	s_cbranch_execz .Lgc_c4
	s_waitcnt vmcnt(26)
	v_lshlrev_b32_e32 v42, 16, v215
	v_lshlrev_b32_e32 v43, 16, v216
.Lgc_c4:
	s_or_b64 exec, exec, s[0:1]
	s_waitcnt lgkmcnt(3)
	v_mul_f32_e32 v13, v18, v13
	v_fmac_f32_e32 v13, v16, v12
	s_waitcnt lgkmcnt(2)
	v_mul_f32_e32 v9, v19, v9
	v_fmac_f32_e32 v13, v20, v14
	v_fmac_f32_e32 v9, v17, v8
	s_waitcnt lgkmcnt(1)
	v_mul_f32_e32 v5, v26, v5
	v_fmac_f32_e32 v13, v22, v15
	v_fmac_f32_e32 v9, v21, v10
	v_fmac_f32_e32 v5, v24, v4
	s_waitcnt lgkmcnt(0)
	v_mul_f32_e32 v1, v27, v1
	v_add_f32_e32 v12, v34, v13
	v_fmac_f32_e32 v9, v23, v11
	v_fmac_f32_e32 v5, v28, v6
	v_fmac_f32_e32 v1, v25, v0
	v_add_f32_e32 v8, v12, v9
	v_fmac_f32_e32 v5, v30, v7
	v_fmac_f32_e32 v1, v29, v2
	v_add_f32_e32 v4, v8, v5
	v_fmac_f32_e32 v1, v31, v3
	v_add_f32_e32 v0, v4, v1
	v_mul_f32_e64 v1, |v0|, s10
	v_exp_f32_e32 v1, v1
	v_min_f32_e32 v0, 0, v0
	v_add_u32_e32 v38, 3, v38
	v_add_f32_e32 v1, 1.0, v1
	v_cmp_gt_f32_e64 s[0:1], s8, v1
	s_nop 1
	v_cndmask_b32_e64 v2, 0, 32, s[0:1]
	v_ldexp_f32 v1, v1, v2
	v_log_f32_e32 v1, v1
	s_nop 0
	v_mul_f32_e32 v2, 0x3f317217, v1
	v_fma_f32 v2, v1, s11, -v2
	v_fmac_f32_e32 v2, 0x3377d1cf, v1
	v_fmac_f32_e32 v2, 0x3f317217, v1
	v_cmp_lt_f32_e64 s[44:45], |v1|, s12
	s_nop 1
	v_cndmask_b32_e64 v1, v1, v2, s[44:45]
	v_cndmask_b32_e64 v2, 0, v163, s[0:1]
	v_sub_f32_e32 v1, v1, v2
	v_sub_f32_e32 v0, v0, v1
	v_mul_f32_e32 v0, 0x3d800000, v0
	v_cndmask_b32_e32 v0, 0, v0, vcc
	v_add_f32_e32 v40, v41, v0
	v_mul_f32_e32 v0, 0x3fb8aa3b, v40
	v_exp_f32_e32 v0, v0
	v_mul_f32_e32 v1, 0xbfb8aa3b, v40
	v_exp_f32_e32 v1, v1
	v_cmp_gt_i32_e32 vcc, s92, v38
	v_mul_f32_e32 v0, v0, v43
	v_mul_f32_e32 v0, 0x3db504f3, v0
	v_bfe_u32 v2, v0, 16, 1
	v_add3_u32 v0, v0, v2, s33
	ds_write_b16_d16_hi v37, v0 offset:544
	v_mul_f32_e32 v0, v1, v42
	v_bfe_u32 v1, v0, 16, 1
	v_add3_u32 v0, v0, v1, s33
	ds_write_b16_d16_hi v37, v0 offset:17952
	ds_read_b128 v[12:15], v36 offset:192
	ds_read_b128 v[8:11], v36 offset:208
	ds_read_b128 v[4:7], v36 offset:224
	ds_read_b128 v[0:3], v36 offset:240
	v_mov_b32_e32 v38, 0
	s_and_saveexec_b64 s[0:1], vcc
	s_cbranch_execz .Lgc_l4
	s_waitcnt vmcnt(24)
	v_lshlrev_b32_e32 v39, 16, v217
	v_lshlrev_b32_e32 v38, 16, v218
	s_branch .Lgc_l4

.Lgc_h5:
	ds_read_b128 v[12:15], v36
	ds_read_b128 v[8:11], v36 offset:16
	ds_read_b128 v[4:7], v36 offset:32
	ds_read_b128 v[0:3], v36 offset:48
	v_add_u32_e32 v38, s95, v121
	v_cmp_gt_i32_e32 vcc, s92, v38
	v_mov_b32_e32 v40, 0
	v_mov_b32_e32 v42, 0
	v_mov_b32_e32 v43, 0
	s_and_saveexec_b64 s[0:1], vcc
	s_cbranch_execz .Lgc_a5
	s_waitcnt vmcnt(22)
	v_lshlrev_b32_e32 v42, 16, v219
	v_lshlrev_b32_e32 v43, 16, v220
.Lgc_a5:
	s_or_b64 exec, exec, s[0:1]
	s_waitcnt lgkmcnt(3)
	v_mul_f32_e32 v13, v18, v13
	v_fmac_f32_e32 v13, v16, v12
	s_waitcnt lgkmcnt(2)
	v_mul_f32_e32 v9, v19, v9
	v_fmac_f32_e32 v13, v20, v14
	v_fmac_f32_e32 v9, v17, v8
	s_waitcnt lgkmcnt(1)
	v_mul_f32_e32 v5, v26, v5
	v_fmac_f32_e32 v13, v22, v15
	v_fmac_f32_e32 v9, v21, v10
	v_fmac_f32_e32 v5, v24, v4
	s_waitcnt lgkmcnt(0)
	v_mul_f32_e32 v1, v27, v1
	v_add_f32_e32 v12, v34, v13
	v_fmac_f32_e32 v9, v23, v11
	v_fmac_f32_e32 v5, v28, v6
	v_fmac_f32_e32 v1, v25, v0
	v_add_f32_e32 v8, v12, v9
	v_fmac_f32_e32 v5, v30, v7
	v_fmac_f32_e32 v1, v29, v2
	v_add_f32_e32 v4, v8, v5
	v_fmac_f32_e32 v1, v31, v3
	v_add_f32_e32 v0, v4, v1
	v_mul_f32_e64 v1, |v0|, s10
	v_exp_f32_e32 v1, v1
	v_min_f32_e32 v0, 0, v0
	v_add_f32_e32 v1, 1.0, v1
	v_cmp_gt_f32_e64 s[0:1], s8, v1
	s_nop 1
	v_cndmask_b32_e64 v2, 0, 32, s[0:1]
	v_ldexp_f32 v1, v1, v2
	v_log_f32_e32 v1, v1
	s_nop 0
	v_mul_f32_e32 v2, 0x3f317217, v1
	v_fma_f32 v2, v1, s11, -v2
	v_fmac_f32_e32 v2, 0x3377d1cf, v1
	v_fmac_f32_e32 v2, 0x3f317217, v1
	v_cmp_lt_f32_e64 s[44:45], |v1|, s12
	s_nop 1
	v_cndmask_b32_e64 v1, v1, v2, s[44:45]
	v_cndmask_b32_e64 v2, 0, v163, s[0:1]
	v_sub_f32_e32 v1, v1, v2
	v_sub_f32_e32 v0, v0, v1
	v_mul_f32_e32 v0, 0x3d800000, v0
	v_cndmask_b32_e32 v0, 0, v0, vcc
	v_add_f32_e32 v39, v41, v0
	v_mul_f32_e32 v0, 0x3fb8aa3b, v39
	v_exp_f32_e32 v0, v0
	v_mul_f32_e32 v1, 0xbfb8aa3b, v39
	v_exp_f32_e32 v1, v1
	v_add_u32_e32 v41, 1, v38
	v_mul_f32_e32 v0, v0, v43
	v_mul_f32_e32 v0, 0x3db504f3, v0
	v_bfe_u32 v2, v0, 16, 1
	v_add3_u32 v0, v0, v2, s33
	ds_write_b16_d16_hi v37, v0
	v_mul_f32_e32 v0, v1, v42
	v_bfe_u32 v1, v0, 16, 1
	v_add3_u32 v0, v0, v1, s33
	ds_write_b16_d16_hi v37, v0 offset:17408
	ds_read_b128 v[12:15], v36 offset:64
	ds_read_b128 v[8:11], v36 offset:80
	ds_read_b128 v[4:7], v36 offset:96
	ds_read_b128 v[0:3], v36 offset:112
	v_cmp_gt_i32_e32 vcc, s92, v41
	v_mov_b32_e32 v42, 0
	s_and_saveexec_b64 s[0:1], vcc
	s_cbranch_execz .Lgc_b5
	s_waitcnt vmcnt(20)
	v_lshlrev_b32_e32 v40, 16, v221
	v_lshlrev_b32_e32 v42, 16, v222
.Lgc_b5:
	s_or_b64 exec, exec, s[0:1]
	s_waitcnt lgkmcnt(3)
	v_mul_f32_e32 v13, v18, v13
	v_fmac_f32_e32 v13, v16, v12
	s_waitcnt lgkmcnt(2)
	v_mul_f32_e32 v9, v19, v9
	v_fmac_f32_e32 v13, v20, v14
	v_fmac_f32_e32 v9, v17, v8
	s_waitcnt lgkmcnt(1)
	v_mul_f32_e32 v5, v26, v5
	v_fmac_f32_e32 v13, v22, v15
	v_fmac_f32_e32 v9, v21, v10
	v_fmac_f32_e32 v5, v24, v4
	s_waitcnt lgkmcnt(0)
	v_mul_f32_e32 v1, v27, v1
	v_add_f32_e32 v12, v34, v13
	v_fmac_f32_e32 v9, v23, v11
	v_fmac_f32_e32 v5, v28, v6
	v_fmac_f32_e32 v1, v25, v0
	v_add_f32_e32 v8, v12, v9
	v_fmac_f32_e32 v5, v30, v7
	v_fmac_f32_e32 v1, v29, v2
	v_add_f32_e32 v4, v8, v5
	v_fmac_f32_e32 v1, v31, v3
	v_add_f32_e32 v0, v4, v1
	v_mul_f32_e64 v1, |v0|, s10
	v_exp_f32_e32 v1, v1
	v_min_f32_e32 v0, 0, v0
	v_mov_b32_e32 v43, 0
	v_add_f32_e32 v1, 1.0, v1
	v_cmp_gt_f32_e64 s[0:1], s8, v1
	s_nop 1
	v_cndmask_b32_e64 v2, 0, 32, s[0:1]
	v_ldexp_f32 v1, v1, v2
	v_log_f32_e32 v1, v1
	s_nop 0
	v_mul_f32_e32 v2, 0x3f317217, v1
	v_fma_f32 v2, v1, s11, -v2
	v_fmac_f32_e32 v2, 0x3377d1cf, v1
	v_fmac_f32_e32 v2, 0x3f317217, v1
	v_cmp_lt_f32_e64 s[44:45], |v1|, s12
	s_nop 1
	v_cndmask_b32_e64 v1, v1, v2, s[44:45]
	v_cndmask_b32_e64 v2, 0, v163, s[0:1]
	v_sub_f32_e32 v1, v1, v2
	v_sub_f32_e32 v0, v0, v1
	v_mul_f32_e32 v0, 0x3d800000, v0
	v_cndmask_b32_e32 v0, 0, v0, vcc
	v_add_f32_e32 v41, v39, v0
	v_mul_f32_e32 v0, 0x3fb8aa3b, v41
	v_exp_f32_e32 v0, v0
	v_mul_f32_e32 v1, 0xbfb8aa3b, v41
	v_exp_f32_e32 v1, v1
	v_mov_b32_e32 v39, 0
	v_mul_f32_e32 v0, v0, v42
	v_mul_f32_e32 v0, 0x3db504f3, v0
	v_bfe_u32 v2, v0, 16, 1
	v_add3_u32 v0, v0, v2, s33
	ds_write_b16_d16_hi v37, v0 offset:272
	v_mul_f32_e32 v0, v1, v40
	v_bfe_u32 v1, v0, 16, 1
	v_add3_u32 v0, v0, v1, s33
	ds_write_b16_d16_hi v37, v0 offset:17680
	ds_read_b128 v[12:15], v36 offset:128
	ds_read_b128 v[8:11], v36 offset:144
	ds_read_b128 v[4:7], v36 offset:160
	ds_read_b128 v[0:3], v36 offset:176
	v_add_u32_e32 v40, 2, v38
	v_cmp_gt_i32_e32 vcc, s92, v40
	v_mov_b32_e32 v42, 0
	s_and_saveexec_b64 s[0:1], vcc
	s_cbranch_execz .Lgc_c5
	s_waitcnt vmcnt(18)
	v_lshlrev_b32_e32 v42, 16, v223
	v_lshlrev_b32_e32 v43, 16, v224
.Lgc_c5:
	s_or_b64 exec, exec, s[0:1]
	s_waitcnt lgkmcnt(3)
	v_mul_f32_e32 v13, v18, v13
	v_fmac_f32_e32 v13, v16, v12
	s_waitcnt lgkmcnt(2)
	v_mul_f32_e32 v9, v19, v9
	v_fmac_f32_e32 v13, v20, v14
	v_fmac_f32_e32 v9, v17, v8
	s_waitcnt lgkmcnt(1)
	v_mul_f32_e32 v5, v26, v5
	v_fmac_f32_e32 v13, v22, v15
	v_fmac_f32_e32 v9, v21, v10
	v_fmac_f32_e32 v5, v24, v4
	s_waitcnt lgkmcnt(0)
	v_mul_f32_e32 v1, v27, v1
	v_add_f32_e32 v12, v34, v13
	v_fmac_f32_e32 v9, v23, v11
	v_fmac_f32_e32 v5, v28, v6
	v_fmac_f32_e32 v1, v25, v0
	v_add_f32_e32 v8, v12, v9
	v_fmac_f32_e32 v5, v30, v7
	v_fmac_f32_e32 v1, v29, v2
	v_add_f32_e32 v4, v8, v5
	v_fmac_f32_e32 v1, v31, v3
	v_add_f32_e32 v0, v4, v1
	v_mul_f32_e64 v1, |v0|, s10
	v_exp_f32_e32 v1, v1
	v_min_f32_e32 v0, 0, v0
	v_add_u32_e32 v38, 3, v38
	v_add_f32_e32 v1, 1.0, v1
	v_cmp_gt_f32_e64 s[0:1], s8, v1
	s_nop 1
	v_cndmask_b32_e64 v2, 0, 32, s[0:1]
	v_ldexp_f32 v1, v1, v2
	v_log_f32_e32 v1, v1
	s_nop 0
	v_mul_f32_e32 v2, 0x3f317217, v1
	v_fma_f32 v2, v1, s11, -v2
	v_fmac_f32_e32 v2, 0x3377d1cf, v1
	v_fmac_f32_e32 v2, 0x3f317217, v1
	v_cmp_lt_f32_e64 s[44:45], |v1|, s12
	s_nop 1
	v_cndmask_b32_e64 v1, v1, v2, s[44:45]
	v_cndmask_b32_e64 v2, 0, v163, s[0:1]
	v_sub_f32_e32 v1, v1, v2
	v_sub_f32_e32 v0, v0, v1
	v_mul_f32_e32 v0, 0x3d800000, v0
	v_cndmask_b32_e32 v0, 0, v0, vcc
	v_add_f32_e32 v40, v41, v0
	v_mul_f32_e32 v0, 0x3fb8aa3b, v40
	v_exp_f32_e32 v0, v0
	v_mul_f32_e32 v1, 0xbfb8aa3b, v40
	v_exp_f32_e32 v1, v1
	v_cmp_gt_i32_e32 vcc, s92, v38
	v_mul_f32_e32 v0, v0, v43
	v_mul_f32_e32 v0, 0x3db504f3, v0
	v_bfe_u32 v2, v0, 16, 1
	v_add3_u32 v0, v0, v2, s33
	ds_write_b16_d16_hi v37, v0 offset:544
	v_mul_f32_e32 v0, v1, v42
	v_bfe_u32 v1, v0, 16, 1
	v_add3_u32 v0, v0, v1, s33
	ds_write_b16_d16_hi v37, v0 offset:17952
	ds_read_b128 v[12:15], v36 offset:192
	ds_read_b128 v[8:11], v36 offset:208
	ds_read_b128 v[4:7], v36 offset:224
	ds_read_b128 v[0:3], v36 offset:240
	v_mov_b32_e32 v38, 0
	s_and_saveexec_b64 s[0:1], vcc
	s_cbranch_execz .Lgc_l5
	s_waitcnt vmcnt(16)
	v_lshlrev_b32_e32 v39, 16, v225
	v_lshlrev_b32_e32 v38, 16, v226
	s_branch .Lgc_l5

.Lgc_h6:
	ds_read_b128 v[12:15], v36
	ds_read_b128 v[8:11], v36 offset:16
	ds_read_b128 v[4:7], v36 offset:32
	ds_read_b128 v[0:3], v36 offset:48
	v_add_u32_e32 v38, s95, v121
	v_cmp_gt_i32_e32 vcc, s92, v38
	v_mov_b32_e32 v40, 0
	v_mov_b32_e32 v42, 0
	v_mov_b32_e32 v43, 0
	s_and_saveexec_b64 s[0:1], vcc
	s_cbranch_execz .Lgc_a6
	s_waitcnt vmcnt(14)
	v_lshlrev_b32_e32 v42, 16, v227
	v_lshlrev_b32_e32 v43, 16, v228
.Lgc_a6:
	s_or_b64 exec, exec, s[0:1]
	s_waitcnt lgkmcnt(3)
	v_mul_f32_e32 v13, v18, v13
	v_fmac_f32_e32 v13, v16, v12
	s_waitcnt lgkmcnt(2)
	v_mul_f32_e32 v9, v19, v9
	v_fmac_f32_e32 v13, v20, v14
	v_fmac_f32_e32 v9, v17, v8
	s_waitcnt lgkmcnt(1)
	v_mul_f32_e32 v5, v26, v5
	v_fmac_f32_e32 v13, v22, v15
	v_fmac_f32_e32 v9, v21, v10
	v_fmac_f32_e32 v5, v24, v4
	s_waitcnt lgkmcnt(0)
	v_mul_f32_e32 v1, v27, v1
	v_add_f32_e32 v12, v34, v13
	v_fmac_f32_e32 v9, v23, v11
	v_fmac_f32_e32 v5, v28, v6
	v_fmac_f32_e32 v1, v25, v0
	v_add_f32_e32 v8, v12, v9
	v_fmac_f32_e32 v5, v30, v7
	v_fmac_f32_e32 v1, v29, v2
	v_add_f32_e32 v4, v8, v5
	v_fmac_f32_e32 v1, v31, v3
	v_add_f32_e32 v0, v4, v1
	v_mul_f32_e64 v1, |v0|, s10
	v_exp_f32_e32 v1, v1
	v_min_f32_e32 v0, 0, v0
	v_add_f32_e32 v1, 1.0, v1
	v_cmp_gt_f32_e64 s[0:1], s8, v1
	s_nop 1
	v_cndmask_b32_e64 v2, 0, 32, s[0:1]
	v_ldexp_f32 v1, v1, v2
	v_log_f32_e32 v1, v1
	s_nop 0
	v_mul_f32_e32 v2, 0x3f317217, v1
	v_fma_f32 v2, v1, s11, -v2
	v_fmac_f32_e32 v2, 0x3377d1cf, v1
	v_fmac_f32_e32 v2, 0x3f317217, v1
	v_cmp_lt_f32_e64 s[44:45], |v1|, s12
	s_nop 1
	v_cndmask_b32_e64 v1, v1, v2, s[44:45]
	v_cndmask_b32_e64 v2, 0, v163, s[0:1]
	v_sub_f32_e32 v1, v1, v2
	v_sub_f32_e32 v0, v0, v1
	v_mul_f32_e32 v0, 0x3d800000, v0
	v_cndmask_b32_e32 v0, 0, v0, vcc
	v_add_f32_e32 v39, v41, v0
	v_mul_f32_e32 v0, 0x3fb8aa3b, v39
	v_exp_f32_e32 v0, v0
	v_mul_f32_e32 v1, 0xbfb8aa3b, v39
	v_exp_f32_e32 v1, v1
	v_add_u32_e32 v41, 1, v38
	v_mul_f32_e32 v0, v0, v43
	v_mul_f32_e32 v0, 0x3db504f3, v0
	v_bfe_u32 v2, v0, 16, 1
	v_add3_u32 v0, v0, v2, s33
	ds_write_b16_d16_hi v37, v0
	v_mul_f32_e32 v0, v1, v42
	v_bfe_u32 v1, v0, 16, 1
	v_add3_u32 v0, v0, v1, s33
	ds_write_b16_d16_hi v37, v0 offset:17408
	ds_read_b128 v[12:15], v36 offset:64
	ds_read_b128 v[8:11], v36 offset:80
	ds_read_b128 v[4:7], v36 offset:96
	ds_read_b128 v[0:3], v36 offset:112
	v_cmp_gt_i32_e32 vcc, s92, v41
	v_mov_b32_e32 v42, 0
	s_and_saveexec_b64 s[0:1], vcc
	s_cbranch_execz .Lgc_b6
	s_waitcnt vmcnt(12)
	v_lshlrev_b32_e32 v40, 16, v229
	v_lshlrev_b32_e32 v42, 16, v230
.Lgc_b6:
	s_or_b64 exec, exec, s[0:1]
	s_waitcnt lgkmcnt(3)
	v_mul_f32_e32 v13, v18, v13
	v_fmac_f32_e32 v13, v16, v12
	s_waitcnt lgkmcnt(2)
	v_mul_f32_e32 v9, v19, v9
	v_fmac_f32_e32 v13, v20, v14
	v_fmac_f32_e32 v9, v17, v8
	s_waitcnt lgkmcnt(1)
	v_mul_f32_e32 v5, v26, v5
	v_fmac_f32_e32 v13, v22, v15
	v_fmac_f32_e32 v9, v21, v10
	v_fmac_f32_e32 v5, v24, v4
	s_waitcnt lgkmcnt(0)
	v_mul_f32_e32 v1, v27, v1
	v_add_f32_e32 v12, v34, v13
	v_fmac_f32_e32 v9, v23, v11
	v_fmac_f32_e32 v5, v28, v6
	v_fmac_f32_e32 v1, v25, v0
	v_add_f32_e32 v8, v12, v9
	v_fmac_f32_e32 v5, v30, v7
	v_fmac_f32_e32 v1, v29, v2
	v_add_f32_e32 v4, v8, v5
	v_fmac_f32_e32 v1, v31, v3
	v_add_f32_e32 v0, v4, v1
	v_mul_f32_e64 v1, |v0|, s10
	v_exp_f32_e32 v1, v1
	v_min_f32_e32 v0, 0, v0
	v_mov_b32_e32 v43, 0
	v_add_f32_e32 v1, 1.0, v1
	v_cmp_gt_f32_e64 s[0:1], s8, v1
	s_nop 1
	v_cndmask_b32_e64 v2, 0, 32, s[0:1]
	v_ldexp_f32 v1, v1, v2
	v_log_f32_e32 v1, v1
	s_nop 0
	v_mul_f32_e32 v2, 0x3f317217, v1
	v_fma_f32 v2, v1, s11, -v2
	v_fmac_f32_e32 v2, 0x3377d1cf, v1
	v_fmac_f32_e32 v2, 0x3f317217, v1
	v_cmp_lt_f32_e64 s[44:45], |v1|, s12
	s_nop 1
	v_cndmask_b32_e64 v1, v1, v2, s[44:45]
	v_cndmask_b32_e64 v2, 0, v163, s[0:1]
	v_sub_f32_e32 v1, v1, v2
	v_sub_f32_e32 v0, v0, v1
	v_mul_f32_e32 v0, 0x3d800000, v0
	v_cndmask_b32_e32 v0, 0, v0, vcc
	v_add_f32_e32 v41, v39, v0
	v_mul_f32_e32 v0, 0x3fb8aa3b, v41
	v_exp_f32_e32 v0, v0
	v_mul_f32_e32 v1, 0xbfb8aa3b, v41
	v_exp_f32_e32 v1, v1
	v_mov_b32_e32 v39, 0
	v_mul_f32_e32 v0, v0, v42
	v_mul_f32_e32 v0, 0x3db504f3, v0
	v_bfe_u32 v2, v0, 16, 1
	v_add3_u32 v0, v0, v2, s33
	ds_write_b16_d16_hi v37, v0 offset:272
	v_mul_f32_e32 v0, v1, v40
	v_bfe_u32 v1, v0, 16, 1
	v_add3_u32 v0, v0, v1, s33
	ds_write_b16_d16_hi v37, v0 offset:17680
	ds_read_b128 v[12:15], v36 offset:128
	ds_read_b128 v[8:11], v36 offset:144
	ds_read_b128 v[4:7], v36 offset:160
	ds_read_b128 v[0:3], v36 offset:176
	v_add_u32_e32 v40, 2, v38
	v_cmp_gt_i32_e32 vcc, s92, v40
	v_mov_b32_e32 v42, 0
	s_and_saveexec_b64 s[0:1], vcc
	s_cbranch_execz .Lgc_c6
	s_waitcnt vmcnt(10)
	v_lshlrev_b32_e32 v42, 16, v231
	v_lshlrev_b32_e32 v43, 16, v232
.Lgc_c6:
	s_or_b64 exec, exec, s[0:1]
	s_waitcnt lgkmcnt(3)
	v_mul_f32_e32 v13, v18, v13
	v_fmac_f32_e32 v13, v16, v12
	s_waitcnt lgkmcnt(2)
	v_mul_f32_e32 v9, v19, v9
	v_fmac_f32_e32 v13, v20, v14
	v_fmac_f32_e32 v9, v17, v8
	s_waitcnt lgkmcnt(1)
	v_mul_f32_e32 v5, v26, v5
	v_fmac_f32_e32 v13, v22, v15
	v_fmac_f32_e32 v9, v21, v10
	v_fmac_f32_e32 v5, v24, v4
	s_waitcnt lgkmcnt(0)
	v_mul_f32_e32 v1, v27, v1
	v_add_f32_e32 v12, v34, v13
	v_fmac_f32_e32 v9, v23, v11
	v_fmac_f32_e32 v5, v28, v6
	v_fmac_f32_e32 v1, v25, v0
	v_add_f32_e32 v8, v12, v9
	v_fmac_f32_e32 v5, v30, v7
	v_fmac_f32_e32 v1, v29, v2
	v_add_f32_e32 v4, v8, v5
	v_fmac_f32_e32 v1, v31, v3
	v_add_f32_e32 v0, v4, v1
	v_mul_f32_e64 v1, |v0|, s10
	v_exp_f32_e32 v1, v1
	v_min_f32_e32 v0, 0, v0
	v_add_u32_e32 v38, 3, v38
	v_add_f32_e32 v1, 1.0, v1
	v_cmp_gt_f32_e64 s[0:1], s8, v1
	s_nop 1
	v_cndmask_b32_e64 v2, 0, 32, s[0:1]
	v_ldexp_f32 v1, v1, v2
	v_log_f32_e32 v1, v1
	s_nop 0
	v_mul_f32_e32 v2, 0x3f317217, v1
	v_fma_f32 v2, v1, s11, -v2
	v_fmac_f32_e32 v2, 0x3377d1cf, v1
	v_fmac_f32_e32 v2, 0x3f317217, v1
	v_cmp_lt_f32_e64 s[44:45], |v1|, s12
	s_nop 1
	v_cndmask_b32_e64 v1, v1, v2, s[44:45]
	v_cndmask_b32_e64 v2, 0, v163, s[0:1]
	v_sub_f32_e32 v1, v1, v2
	v_sub_f32_e32 v0, v0, v1
	v_mul_f32_e32 v0, 0x3d800000, v0
	v_cndmask_b32_e32 v0, 0, v0, vcc
	v_add_f32_e32 v40, v41, v0
	v_mul_f32_e32 v0, 0x3fb8aa3b, v40
	v_exp_f32_e32 v0, v0
	v_mul_f32_e32 v1, 0xbfb8aa3b, v40
	v_exp_f32_e32 v1, v1
	v_cmp_gt_i32_e32 vcc, s92, v38
	v_mul_f32_e32 v0, v0, v43
	v_mul_f32_e32 v0, 0x3db504f3, v0
	v_bfe_u32 v2, v0, 16, 1
	v_add3_u32 v0, v0, v2, s33
	ds_write_b16_d16_hi v37, v0 offset:544
	v_mul_f32_e32 v0, v1, v42
	v_bfe_u32 v1, v0, 16, 1
	v_add3_u32 v0, v0, v1, s33
	ds_write_b16_d16_hi v37, v0 offset:17952
	ds_read_b128 v[12:15], v36 offset:192
	ds_read_b128 v[8:11], v36 offset:208
	ds_read_b128 v[4:7], v36 offset:224
	ds_read_b128 v[0:3], v36 offset:240
	v_mov_b32_e32 v38, 0
	s_and_saveexec_b64 s[0:1], vcc
	s_cbranch_execz .Lgc_l6
	s_waitcnt vmcnt(8)
	v_lshlrev_b32_e32 v39, 16, v233
	v_lshlrev_b32_e32 v38, 16, v234
	s_branch .Lgc_l6

.Lgc_h7:
	ds_read_b128 v[12:15], v36
	ds_read_b128 v[8:11], v36 offset:16
	ds_read_b128 v[4:7], v36 offset:32
	ds_read_b128 v[0:3], v36 offset:48
	v_add_u32_e32 v38, s95, v121
	v_cmp_gt_i32_e32 vcc, s92, v38
	v_mov_b32_e32 v40, 0
	v_mov_b32_e32 v42, 0
	v_mov_b32_e32 v43, 0
	s_and_saveexec_b64 s[0:1], vcc
	s_cbranch_execz .Lgc_a7
	s_waitcnt vmcnt(6)
	v_lshlrev_b32_e32 v42, 16, v235
	v_lshlrev_b32_e32 v43, 16, v236
.Lgc_a7:
	s_or_b64 exec, exec, s[0:1]
	s_waitcnt lgkmcnt(3)
	v_mul_f32_e32 v13, v18, v13
	v_fmac_f32_e32 v13, v16, v12
	s_waitcnt lgkmcnt(2)
	v_mul_f32_e32 v9, v19, v9
	v_fmac_f32_e32 v13, v20, v14
	v_fmac_f32_e32 v9, v17, v8
	s_waitcnt lgkmcnt(1)
	v_mul_f32_e32 v5, v26, v5
	v_fmac_f32_e32 v13, v22, v15
	v_fmac_f32_e32 v9, v21, v10
	v_fmac_f32_e32 v5, v24, v4
	s_waitcnt lgkmcnt(0)
	v_mul_f32_e32 v1, v27, v1
	v_add_f32_e32 v12, v34, v13
	v_fmac_f32_e32 v9, v23, v11
	v_fmac_f32_e32 v5, v28, v6
	v_fmac_f32_e32 v1, v25, v0
	v_add_f32_e32 v8, v12, v9
	v_fmac_f32_e32 v5, v30, v7
	v_fmac_f32_e32 v1, v29, v2
	v_add_f32_e32 v4, v8, v5
	v_fmac_f32_e32 v1, v31, v3
	v_add_f32_e32 v0, v4, v1
	v_mul_f32_e64 v1, |v0|, s10
	v_exp_f32_e32 v1, v1
	v_min_f32_e32 v0, 0, v0
	v_add_f32_e32 v1, 1.0, v1
	v_cmp_gt_f32_e64 s[0:1], s8, v1
	s_nop 1
	v_cndmask_b32_e64 v2, 0, 32, s[0:1]
	v_ldexp_f32 v1, v1, v2
	v_log_f32_e32 v1, v1
	s_nop 0
	v_mul_f32_e32 v2, 0x3f317217, v1
	v_fma_f32 v2, v1, s11, -v2
	v_fmac_f32_e32 v2, 0x3377d1cf, v1
	v_fmac_f32_e32 v2, 0x3f317217, v1
	v_cmp_lt_f32_e64 s[44:45], |v1|, s12
	s_nop 1
	v_cndmask_b32_e64 v1, v1, v2, s[44:45]
	v_cndmask_b32_e64 v2, 0, v163, s[0:1]
	v_sub_f32_e32 v1, v1, v2
	v_sub_f32_e32 v0, v0, v1
	v_mul_f32_e32 v0, 0x3d800000, v0
	v_cndmask_b32_e32 v0, 0, v0, vcc
	v_add_f32_e32 v39, v41, v0
	v_mul_f32_e32 v0, 0x3fb8aa3b, v39
	v_exp_f32_e32 v0, v0
	v_mul_f32_e32 v1, 0xbfb8aa3b, v39
	v_exp_f32_e32 v1, v1
	v_add_u32_e32 v41, 1, v38
	v_mul_f32_e32 v0, v0, v43
	v_mul_f32_e32 v0, 0x3db504f3, v0
	v_bfe_u32 v2, v0, 16, 1
	v_add3_u32 v0, v0, v2, s33
	ds_write_b16_d16_hi v37, v0
	v_mul_f32_e32 v0, v1, v42
	v_bfe_u32 v1, v0, 16, 1
	v_add3_u32 v0, v0, v1, s33
	ds_write_b16_d16_hi v37, v0 offset:17408
	ds_read_b128 v[12:15], v36 offset:64
	ds_read_b128 v[8:11], v36 offset:80
	ds_read_b128 v[4:7], v36 offset:96
	ds_read_b128 v[0:3], v36 offset:112
	v_cmp_gt_i32_e32 vcc, s92, v41
	v_mov_b32_e32 v42, 0
	s_and_saveexec_b64 s[0:1], vcc
	s_cbranch_execz .Lgc_b7
	s_waitcnt vmcnt(4)
	v_lshlrev_b32_e32 v40, 16, v237
	v_lshlrev_b32_e32 v42, 16, v238
.Lgc_b7:
	s_or_b64 exec, exec, s[0:1]
	s_waitcnt lgkmcnt(3)
	v_mul_f32_e32 v13, v18, v13
	v_fmac_f32_e32 v13, v16, v12
	s_waitcnt lgkmcnt(2)
	v_mul_f32_e32 v9, v19, v9
	v_fmac_f32_e32 v13, v20, v14
	v_fmac_f32_e32 v9, v17, v8
	s_waitcnt lgkmcnt(1)
	v_mul_f32_e32 v5, v26, v5
	v_fmac_f32_e32 v13, v22, v15
	v_fmac_f32_e32 v9, v21, v10
	v_fmac_f32_e32 v5, v24, v4
	s_waitcnt lgkmcnt(0)
	v_mul_f32_e32 v1, v27, v1
	v_add_f32_e32 v12, v34, v13
	v_fmac_f32_e32 v9, v23, v11
	v_fmac_f32_e32 v5, v28, v6
	v_fmac_f32_e32 v1, v25, v0
	v_add_f32_e32 v8, v12, v9
	v_fmac_f32_e32 v5, v30, v7
	v_fmac_f32_e32 v1, v29, v2
	v_add_f32_e32 v4, v8, v5
	v_fmac_f32_e32 v1, v31, v3
	v_add_f32_e32 v0, v4, v1
	v_mul_f32_e64 v1, |v0|, s10
	v_exp_f32_e32 v1, v1
	v_min_f32_e32 v0, 0, v0
	v_mov_b32_e32 v43, 0
	v_add_f32_e32 v1, 1.0, v1
	v_cmp_gt_f32_e64 s[0:1], s8, v1
	s_nop 1
	v_cndmask_b32_e64 v2, 0, 32, s[0:1]
	v_ldexp_f32 v1, v1, v2
	v_log_f32_e32 v1, v1
	s_nop 0
	v_mul_f32_e32 v2, 0x3f317217, v1
	v_fma_f32 v2, v1, s11, -v2
	v_fmac_f32_e32 v2, 0x3377d1cf, v1
	v_fmac_f32_e32 v2, 0x3f317217, v1
	v_cmp_lt_f32_e64 s[44:45], |v1|, s12
	s_nop 1
	v_cndmask_b32_e64 v1, v1, v2, s[44:45]
	v_cndmask_b32_e64 v2, 0, v163, s[0:1]
	v_sub_f32_e32 v1, v1, v2
	v_sub_f32_e32 v0, v0, v1
	v_mul_f32_e32 v0, 0x3d800000, v0
	v_cndmask_b32_e32 v0, 0, v0, vcc
	v_add_f32_e32 v41, v39, v0
	v_mul_f32_e32 v0, 0x3fb8aa3b, v41
	v_exp_f32_e32 v0, v0
	v_mul_f32_e32 v1, 0xbfb8aa3b, v41
	v_exp_f32_e32 v1, v1
	v_mov_b32_e32 v39, 0
	v_mul_f32_e32 v0, v0, v42
	v_mul_f32_e32 v0, 0x3db504f3, v0
	v_bfe_u32 v2, v0, 16, 1
	v_add3_u32 v0, v0, v2, s33
	ds_write_b16_d16_hi v37, v0 offset:272
	v_mul_f32_e32 v0, v1, v40
	v_bfe_u32 v1, v0, 16, 1
	v_add3_u32 v0, v0, v1, s33
	ds_write_b16_d16_hi v37, v0 offset:17680
	ds_read_b128 v[12:15], v36 offset:128
	ds_read_b128 v[8:11], v36 offset:144
	ds_read_b128 v[4:7], v36 offset:160
	ds_read_b128 v[0:3], v36 offset:176
	v_add_u32_e32 v40, 2, v38
	v_cmp_gt_i32_e32 vcc, s92, v40
	v_mov_b32_e32 v42, 0
	s_and_saveexec_b64 s[0:1], vcc
	s_cbranch_execz .Lgc_c7
	s_waitcnt vmcnt(2)
	v_lshlrev_b32_e32 v42, 16, v239
	v_lshlrev_b32_e32 v43, 16, v240
.Lgc_c7:
	s_or_b64 exec, exec, s[0:1]
	s_waitcnt lgkmcnt(3)
	v_mul_f32_e32 v13, v18, v13
	v_fmac_f32_e32 v13, v16, v12
	s_waitcnt lgkmcnt(2)
	v_mul_f32_e32 v9, v19, v9
	v_fmac_f32_e32 v13, v20, v14
	v_fmac_f32_e32 v9, v17, v8
	s_waitcnt lgkmcnt(1)
	v_mul_f32_e32 v5, v26, v5
	v_fmac_f32_e32 v13, v22, v15
	v_fmac_f32_e32 v9, v21, v10
	v_fmac_f32_e32 v5, v24, v4
	s_waitcnt lgkmcnt(0)
	v_mul_f32_e32 v1, v27, v1
	v_add_f32_e32 v12, v34, v13
	v_fmac_f32_e32 v9, v23, v11
	v_fmac_f32_e32 v5, v28, v6
	v_fmac_f32_e32 v1, v25, v0
	v_add_f32_e32 v8, v12, v9
	v_fmac_f32_e32 v5, v30, v7
	v_fmac_f32_e32 v1, v29, v2
	v_add_f32_e32 v4, v8, v5
	v_fmac_f32_e32 v1, v31, v3
	v_add_f32_e32 v0, v4, v1
	v_mul_f32_e64 v1, |v0|, s10
	v_exp_f32_e32 v1, v1
	v_min_f32_e32 v0, 0, v0
	v_add_u32_e32 v38, 3, v38
	v_add_f32_e32 v1, 1.0, v1
	v_cmp_gt_f32_e64 s[0:1], s8, v1
	s_nop 1
	v_cndmask_b32_e64 v2, 0, 32, s[0:1]
	v_ldexp_f32 v1, v1, v2
	v_log_f32_e32 v1, v1
	s_nop 0
	v_mul_f32_e32 v2, 0x3f317217, v1
	v_fma_f32 v2, v1, s11, -v2
	v_fmac_f32_e32 v2, 0x3377d1cf, v1
	v_fmac_f32_e32 v2, 0x3f317217, v1
	v_cmp_lt_f32_e64 s[44:45], |v1|, s12
	s_nop 1
	v_cndmask_b32_e64 v1, v1, v2, s[44:45]
	v_cndmask_b32_e64 v2, 0, v163, s[0:1]
	v_sub_f32_e32 v1, v1, v2
	v_sub_f32_e32 v0, v0, v1
	v_mul_f32_e32 v0, 0x3d800000, v0
	v_cndmask_b32_e32 v0, 0, v0, vcc
	v_add_f32_e32 v40, v41, v0
	v_mul_f32_e32 v0, 0x3fb8aa3b, v40
	v_exp_f32_e32 v0, v0
	v_mul_f32_e32 v1, 0xbfb8aa3b, v40
	v_exp_f32_e32 v1, v1
	v_cmp_gt_i32_e32 vcc, s92, v38
	v_mul_f32_e32 v0, v0, v43
	v_mul_f32_e32 v0, 0x3db504f3, v0
	v_bfe_u32 v2, v0, 16, 1
	v_add3_u32 v0, v0, v2, s33
	ds_write_b16_d16_hi v37, v0 offset:544
	v_mul_f32_e32 v0, v1, v42
	v_bfe_u32 v1, v0, 16, 1
	v_add3_u32 v0, v0, v1, s33
	ds_write_b16_d16_hi v37, v0 offset:17952
	ds_read_b128 v[12:15], v36 offset:192
	ds_read_b128 v[8:11], v36 offset:208
	ds_read_b128 v[4:7], v36 offset:224
	ds_read_b128 v[0:3], v36 offset:240
	v_mov_b32_e32 v38, 0
	s_and_saveexec_b64 s[0:1], vcc
	s_cbranch_execz .Lgc_l7
	s_waitcnt vmcnt(0)
	v_lshlrev_b32_e32 v39, 16, v241
	v_lshlrev_b32_e32 v38, 16, v242
	s_branch .Lgc_l7
.Lgc_l7:
	s_or_b64 exec, exec, s[0:1]
	s_waitcnt lgkmcnt(3)
	v_mul_f32_e32 v13, v18, v13
	v_fmac_f32_e32 v13, v16, v12
	s_waitcnt lgkmcnt(2)
	v_mul_f32_e32 v9, v19, v9
	v_fmac_f32_e32 v13, v20, v14
	v_fmac_f32_e32 v9, v17, v8
	s_waitcnt lgkmcnt(1)
	v_mul_f32_e32 v5, v26, v5
	v_fmac_f32_e32 v13, v22, v15
	v_fmac_f32_e32 v9, v21, v10
	v_fmac_f32_e32 v5, v24, v4
	s_waitcnt lgkmcnt(0)
	v_mul_f32_e32 v1, v27, v1
	v_add_f32_e32 v12, v34, v13
	v_fmac_f32_e32 v9, v23, v11
	v_fmac_f32_e32 v5, v28, v6
	v_fmac_f32_e32 v1, v25, v0
	v_add_f32_e32 v8, v12, v9
	v_fmac_f32_e32 v5, v30, v7
	v_fmac_f32_e32 v1, v29, v2
	v_add_f32_e32 v4, v8, v5
	v_fmac_f32_e32 v1, v31, v3
	v_add_f32_e32 v0, v4, v1
	v_mul_f32_e64 v1, |v0|, s10
	v_exp_f32_e32 v1, v1
	v_min_f32_e32 v0, 0, v0
	s_add_i32 s95, s95, 4
	s_cmp_eq_u32 s95, 32
	v_add_f32_e32 v1, 1.0, v1
	v_cmp_gt_f32_e64 s[0:1], s8, v1
	v_add_u32_e32 v36, 0x100, v36
	s_nop 0
	v_cndmask_b32_e64 v2, 0, 32, s[0:1]
	v_ldexp_f32 v1, v1, v2
	v_log_f32_e32 v1, v1
	s_nop 0
	v_mul_f32_e32 v2, 0x3f317217, v1
	v_fma_f32 v2, v1, s11, -v2
	v_fmac_f32_e32 v2, 0x3377d1cf, v1
	v_fmac_f32_e32 v2, 0x3f317217, v1
	v_cmp_lt_f32_e64 s[44:45], |v1|, s12
	s_nop 1
	v_cndmask_b32_e64 v1, v1, v2, s[44:45]
	v_cndmask_b32_e64 v2, 0, v163, s[0:1]
	v_sub_f32_e32 v1, v1, v2
	v_sub_f32_e32 v0, v0, v1
	v_mul_f32_e32 v0, 0x3d800000, v0
	v_cndmask_b32_e32 v0, 0, v0, vcc
	v_add_f32_e32 v41, v40, v0
	v_mul_f32_e32 v0, 0x3fb8aa3b, v41
	v_exp_f32_e32 v0, v0
	v_mul_f32_e32 v1, 0xbfb8aa3b, v41
	v_exp_f32_e32 v1, v1
	v_mul_f32_e32 v0, v0, v38
	v_mul_f32_e32 v0, 0x3db504f3, v0
	v_bfe_u32 v2, v0, 16, 1
	v_add3_u32 v0, v0, v2, s33
	ds_write_b16_d16_hi v37, v0 offset:816
	v_mul_f32_e32 v0, v1, v39
	v_bfe_u32 v1, v0, 16, 1
	v_add3_u32 v0, v0, v1, s33
	ds_write_b16_d16_hi v37, v0 offset:18224
	v_add_u32_e32 v37, 0x440, v37
	s_branch .LBB0_277
.LBB0_277:
	s_waitcnt vmcnt(0) lgkmcnt(0)
	s_barrier
	ds_read_b128 v[0:3], v80 offset:6144
	v_add_u32_e32 v56, v78, v113
	ds_read_b128 v[4:7], v56 offset:23552
	ds_read_b128 v[8:11], v80 offset:6208
	ds_read_b128 v[12:15], v56 offset:23616
	ds_read_b128 v[16:19], v56 offset:27904
	ds_read_b128 v[20:23], v56 offset:27968
	ds_read_b128 v[24:27], v56 offset:32256
	ds_read_b128 v[28:31], v56 offset:32320
	ds_read_b128 v[32:35], v56 offset:36608
	ds_read_b128 v[36:39], v56 offset:36672
	s_waitcnt lgkmcnt(8)
	v_mfma_f32_16x16x32_bf16 v[4:7], v[0:3], v[4:7], 0
	v_readlane_b32 s0, v254, 63
	v_readlane_b32 s1, v255, 0
	v_mov_b32_e32 v95, v115
	s_waitcnt lgkmcnt(5)
	v_mfma_f32_16x16x32_bf16 v[16:19], v[0:3], v[16:19], 0
	s_mov_b32 s8, 0x1ea32000
	s_mov_b32 s9, 0x1ea33000
	s_waitcnt lgkmcnt(3)
	v_mfma_f32_16x16x32_bf16 v[24:27], v[0:3], v[24:27], 0
	s_waitcnt lgkmcnt(1)
	v_mfma_f32_16x16x32_bf16 v[0:3], v[0:3], v[32:35], 0
	v_mfma_f32_16x16x32_bf16 v[4:7], v[8:11], v[12:15], v[4:7]
	ds_read_b128 v[12:15], v80 offset:6272
	ds_read_b128 v[32:35], v56 offset:23680
	v_mfma_f32_16x16x32_bf16 v[16:19], v[8:11], v[20:23], v[16:19]
	ds_read_b128 v[20:23], v80 offset:6336
	ds_read_b128 v[40:43], v56 offset:23744
	s_waitcnt lgkmcnt(2)
	v_mfma_f32_16x16x32_bf16 v[4:7], v[12:15], v[32:35], v[4:7]
	ds_read_b128 v[32:35], v56 offset:28032
	ds_read_b128 v[44:47], v56 offset:28096
	ds_read_b128 v[48:51], v56 offset:32384
	ds_read_b128 v[52:55], v56 offset:32448
	s_waitcnt lgkmcnt(4)
	v_mfma_f32_16x16x32_bf16 v[4:7], v[20:23], v[40:43], v[4:7]
	ds_read_b128 v[40:43], v56 offset:36736
	ds_read_b128 v[56:59], v56 offset:36800
	v_mfma_f32_16x16x32_bf16 v[24:27], v[8:11], v[28:31], v[24:27]
	s_nop 4
	v_cndmask_b32_e64 v4, v4, 0, s[0:1]
	v_bfe_u32 v60, v4, 16, 1
	v_readlane_b32 s0, v255, 1
	v_add3_u32 v4, v4, v60, s33
	v_readlane_b32 s1, v255, 2
	ds_write_b16_d16_hi v183, v4 offset:40960
	v_mfma_f32_16x16x32_bf16 v[0:3], v[8:11], v[36:39], v[0:3]
	v_cndmask_b32_e64 v4, v5, 0, s[0:1]
	v_bfe_u32 v5, v4, 16, 1
	v_readlane_b32 s0, v255, 3
	v_add3_u32 v4, v4, v5, s33
	s_waitcnt lgkmcnt(6)
	v_mfma_f32_16x16x32_bf16 v[8:11], v[12:15], v[32:35], v[16:19]
	v_readlane_b32 s1, v255, 4
	ds_write_b16_d16_hi v183, v4 offset:41104
	s_nop 0
	v_cndmask_b32_e64 v4, v6, 0, s[0:1]
	v_bfe_u32 v5, v4, 16, 1
	v_readlane_b32 s0, v255, 5
	v_add3_u32 v4, v4, v5, s33
	v_readlane_b32 s1, v255, 6
	s_waitcnt lgkmcnt(5)
	v_mfma_f32_16x16x32_bf16 v[16:19], v[12:15], v[48:51], v[24:27]
	ds_write_b16_d16_hi v183, v4 offset:41248
	s_nop 1
	v_cndmask_b32_e64 v24, v7, 0, s[0:1]
	v_mfma_f32_16x16x32_bf16 v[4:7], v[20:23], v[44:47], v[8:11]
	v_bfe_u32 v25, v24, 16, 1
	s_mov_b64 s[0:1], 0
	s_nop 0
	v_add3_u32 v8, v24, v25, s33
	ds_write_b16_d16_hi v183, v8 offset:41392
	s_nop 2
	v_cndmask_b32_e64 v4, v4, 0, s[14:15]
	v_bfe_u32 v8, v4, 16, 1
	v_add3_u32 v4, v4, v8, s33
	ds_write_b16_d16_hi v183, v4 offset:40992
	v_cndmask_b32_e64 v4, v5, 0, s[46:47]
	v_bfe_u32 v5, v4, 16, 1
	v_add3_u32 v4, v4, v5, s33
	ds_write_b16_d16_hi v183, v4 offset:41136
	v_cndmask_b32_e64 v4, v6, 0, s[48:49]
	v_bfe_u32 v5, v4, 16, 1
	s_waitcnt lgkmcnt(8)
	v_mfma_f32_16x16x32_bf16 v[8:11], v[20:23], v[52:55], v[16:19]
	v_add3_u32 v4, v4, v5, s33
	ds_write_b16_d16_hi v183, v4 offset:41280
	v_cndmask_b32_e64 v4, v7, 0, s[4:5]
	v_bfe_u32 v5, v4, 16, 1
	v_add3_u32 v4, v4, v5, s33
	ds_write_b16_d16_hi v183, v4 offset:41424
	s_nop 1
	v_cndmask_b32_e64 v4, v8, 0, s[52:53]
	v_bfe_u32 v5, v4, 16, 1
	v_add3_u32 v4, v4, v5, s33
	s_waitcnt lgkmcnt(9)
	v_mfma_f32_16x16x32_bf16 v[0:3], v[12:15], v[40:43], v[0:3]
	ds_write_b16_d16_hi v183, v4 offset:41024
	v_cndmask_b32_e64 v4, v9, 0, s[54:55]
	v_bfe_u32 v5, v4, 16, 1
	v_add3_u32 v4, v4, v5, s33
	ds_write_b16_d16_hi v183, v4 offset:41168
	v_cndmask_b32_e64 v4, v10, 0, s[56:57]
	s_waitcnt lgkmcnt(10)
	v_mfma_f32_16x16x32_bf16 v[0:3], v[20:23], v[56:59], v[0:3]
	v_bfe_u32 v5, v4, 16, 1
	v_add3_u32 v4, v4, v5, s33
	ds_write_b16_d16_hi v183, v4 offset:41312
	v_cndmask_b32_e64 v4, v11, 0, s[58:59]
	v_bfe_u32 v5, v4, 16, 1
	v_add3_u32 v4, v4, v5, s33
	s_nop 1
	v_cndmask_b32_e64 v0, v0, 0, s[60:61]
	ds_write_b16_d16_hi v183, v4 offset:41456
	v_bfe_u32 v4, v0, 16, 1
	v_add3_u32 v0, v0, v4, s33
	ds_write_b16_d16_hi v183, v0 offset:41056
	v_cndmask_b32_e64 v0, v1, 0, s[34:35]
	v_bfe_u32 v1, v0, 16, 1
	v_add3_u32 v0, v0, v1, s33
	ds_write_b16_d16_hi v183, v0 offset:41200
	v_cndmask_b32_e64 v0, v2, 0, s[36:37]
	v_bfe_u32 v1, v0, 16, 1
	v_add3_u32 v0, v0, v1, s33
	ds_write_b16_d16_hi v183, v0 offset:41344
	v_cndmask_b32_e64 v0, v3, 0, s[38:39]
	v_bfe_u32 v1, v0, 16, 1
	v_add3_u32 v0, v0, v1, s33
	v_mov_b32_e32 v16, 0
	ds_write_b16_d16_hi v183, v0 offset:41488
	v_mov_b32_e32 v17, v16
	v_mov_b32_e32 v18, v16
	v_mov_b32_e32 v19, v16
	v_mov_b32_e32 v20, v16
	v_mov_b32_e32 v21, v16
	v_mov_b32_e32 v22, v16
	v_mov_b32_e32 v23, v16
	v_mov_b32_e32 v24, v16
	v_mov_b32_e32 v25, v16
	v_mov_b32_e32 v26, v16
	v_mov_b32_e32 v27, v16
	v_mov_b32_e32 v28, v16
	v_mov_b32_e32 v29, v16
	v_mov_b32_e32 v30, v16
	v_mov_b32_e32 v31, v16
	v_mov_b32_e32 v32, v16
	v_mov_b32_e32 v33, v16
	v_mov_b32_e32 v34, v16
	v_mov_b32_e32 v35, v16
	v_mov_b32_e32 v36, v16
	v_mov_b32_e32 v37, v16
	v_mov_b32_e32 v38, v16
	v_mov_b32_e32 v39, v16
	v_mov_b32_e32 v40, v16
	v_mov_b32_e32 v41, v16
	v_mov_b32_e32 v42, v16
	v_mov_b32_e32 v43, v16
	v_mov_b32_e32 v44, v16
	v_mov_b32_e32 v45, v16
	v_mov_b32_e32 v46, v16
	v_mov_b32_e32 v47, v16
	v_mov_b32_e32 v48, v16
	v_mov_b32_e32 v49, v16
	v_mov_b32_e32 v50, v16
	v_mov_b32_e32 v51, v16
	v_mov_b32_e32 v52, v16
	v_mov_b32_e32 v53, v16
	v_mov_b32_e32 v54, v16
	v_mov_b32_e32 v55, v16
	v_mov_b32_e32 v56, v16
	v_mov_b32_e32 v57, v16
	v_mov_b32_e32 v58, v16
	v_mov_b32_e32 v59, v16
	v_mov_b32_e32 v60, v16
	v_mov_b32_e32 v61, v16
	v_mov_b32_e32 v62, v16
	v_mov_b32_e32 v63, v16
	v_mov_b32_e32 v12, v16
	v_mov_b32_e32 v13, v16
	v_mov_b32_e32 v14, v16
	v_mov_b32_e32 v15, v16
	v_mov_b32_e32 v8, v16
	v_mov_b32_e32 v9, v16
	v_mov_b32_e32 v10, v16
	v_mov_b32_e32 v11, v16
	v_mov_b32_e32 v4, v16
	v_mov_b32_e32 v5, v16
	v_mov_b32_e32 v6, v16
	v_mov_b32_e32 v7, v16
	v_mov_b32_e32 v0, v16
	v_mov_b32_e32 v1, v16
	v_mov_b32_e32 v2, v16
	v_mov_b32_e32 v3, v16
	s_waitcnt lgkmcnt(0)
	s_barrier

.LBB0_397:
	ds_read_b128 v[12:15], v10
	ds_read_b128 v[0:3], v10 offset:16
	ds_read_b128 v[36:39], v10 offset:32
	ds_read_b128 v[4:7], v10 offset:48
	ds_read_b128 v[40:43], v10 offset:80
	ds_read_b128 v[44:47], v10 offset:64
	ds_read_b128 v[48:51], v10 offset:112
	ds_read_b128 v[52:55], v10 offset:96
	s_waitcnt lgkmcnt(6)
	v_mov_b32_e32 v33, v0
	v_mov_b32_e32 v0, v13
	v_mov_b32_e32 v32, v12
	v_mov_b32_e32 v13, v2
	v_mov_b32_e32 v2, v15
	s_waitcnt lgkmcnt(4)
	v_mov_b32_e32 v15, v4
	v_mov_b32_e32 v4, v37
	v_mov_b32_e32 v37, v6
	v_mov_b32_e32 v6, v39
	s_waitcnt lgkmcnt(3)
	v_mov_b32_e32 v39, v40
	s_waitcnt lgkmcnt(2)
	v_mov_b32_e32 v40, v45
	s_waitcnt vmcnt(11)
	v_pk_mul_f32 v[0:1], v[18:19], v[0:1]
	v_mov_b32_e32 v12, v14
	v_mov_b32_e32 v14, v36
	v_mov_b32_e32 v36, v38
	v_mov_b32_e32 v38, v44
	s_waitcnt vmcnt(3)
	v_pk_mul_f32 v[4:5], v[26:27], v[4:5]
	v_pk_mul_f32 v[40:41], v[18:19], v[40:41]
	v_pk_fma_f32 v[0:1], v[16:17], v[32:33], v[0:1]
	v_mov_b32_e32 v44, v46
	v_mov_b32_e32 v45, v42
	v_mov_b32_e32 v42, v47
	s_waitcnt lgkmcnt(1)
	v_mov_b32_e32 v47, v48
	s_waitcnt lgkmcnt(0)
	v_mov_b32_e32 v48, v53
	v_pk_fma_f32 v[4:5], v[24:25], v[14:15], v[4:5]
	v_pk_fma_f32 v[14:15], v[16:17], v[38:39], v[40:41]
	v_pk_fma_f32 v[0:1], v[20:21], v[12:13], v[0:1]
	v_mov_b32_e32 v46, v52
	v_pk_mul_f32 v[48:49], v[26:27], v[48:49]
	s_waitcnt vmcnt(2)
	v_pk_fma_f32 v[4:5], v[28:29], v[36:37], v[4:5]
	v_pk_fma_f32 v[12:13], v[20:21], v[44:45], v[14:15]
	v_pk_fma_f32 v[0:1], v[22:23], v[2:3], v[0:1]
	v_mov_b32_e32 v52, v54
	v_mov_b32_e32 v53, v50
	v_pk_fma_f32 v[32:33], v[24:25], v[46:47], v[48:49]
	s_waitcnt vmcnt(1)
	v_pk_fma_f32 v[2:3], v[30:31], v[6:7], v[4:5]
	v_pk_fma_f32 v[4:5], v[22:23], v[42:43], v[12:13]
	s_waitcnt vmcnt(0)
	v_add_f32_e32 v0, v34, v0
	v_mov_b32_e32 v50, v55
	v_pk_fma_f32 v[14:15], v[28:29], v[52:53], v[32:33]
	v_add_f32_e32 v4, v34, v4
	v_add_f32_e32 v0, v0, v1
	v_pk_fma_f32 v[6:7], v[30:31], v[50:51], v[14:15]
	v_add_f32_e32 v1, v4, v5
	v_add_f32_e32 v0, v0, v2
	v_add_f32_e32 v1, v1, v6
	v_add_f32_e32 v0, v0, v3
	v_add_f32_e32 v1, v1, v7
	v_min_f32_e32 v2, 0, v0
	v_mul_f32_e64 v0, |v0|, s95
	v_min_f32_e32 v3, 0, v1
	v_mul_f32_e64 v1, |v1|, s95
	v_exp_f32_e32 v0, v0
	v_exp_f32_e32 v1, v1
	s_add_i32 s47, s7, 1
	v_add_u32_e32 v10, 0x80, v10
	v_add_f32_e32 v0, 1.0, v0
	v_add_f32_e32 v1, 1.0, v1
	v_cmp_gt_f32_e32 vcc, s94, v0
	v_cmp_gt_f32_e64 s[0:1], s94, v1
	s_nop 0
	v_cndmask_b32_e64 v4, 0, 32, vcc
	v_cndmask_b32_e64 v5, 0, 32, s[0:1]
	v_ldexp_f32 v0, v0, v4
	v_ldexp_f32 v1, v1, v5
	v_log_f32_e32 v0, v0
	v_log_f32_e32 v1, v1
	v_cndmask_b32_e64 v7, 0, v163, s[0:1]
	v_cndmask_b32_e32 v6, 0, v163, vcc
	v_mul_f32_e32 v4, 0x3f317217, v0
	v_mul_f32_e32 v5, 0x3f317217, v1
	v_fma_f32 v4, v0, s44, -v4
	v_fma_f32 v5, v1, s44, -v5
	v_fmac_f32_e32 v4, 0x3377d1cf, v0
	v_fmac_f32_e32 v5, 0x3377d1cf, v1
	v_fmac_f32_e32 v4, 0x3f317217, v0
	v_cmp_lt_f32_e64 s[0:1], |v0|, s45
	v_fmac_f32_e32 v5, 0x3f317217, v1
	v_cmp_lt_f32_e64 vcc, |v1|, s45
	v_cndmask_b32_e64 v0, v0, v4, s[0:1]
	v_sub_f32_e32 v0, v0, v6
	v_cndmask_b32_e32 v1, v1, v5, vcc
	v_sub_f32_e32 v1, v1, v7
	v_sub_f32_e32 v0, v2, v0
	v_sub_f32_e32 v1, v3, v1
	v_mul_f32_e32 v0, 0x3d800000, v0
	v_cmp_lt_i32_e32 vcc, s7, v8
	v_mul_f32_e32 v1, 0x3d800000, v1
	v_cmp_lt_i32_e64 s[0:1], s47, v8
	v_cndmask_b32_e32 v0, 0, v0, vcc
	s_add_i32 s7, s7, 2
	v_cndmask_b32_e64 v1, 0, v1, s[0:1]
	v_add_f32_e32 v0, v9, v0
	s_cmp_lg_u32 s7, 32
	v_add_f32_e32 v9, v0, v1
	s_cbranch_scc1 .LBB0_397
	ds_write_b32 v187, v9 offset:4096
	s_waitcnt lgkmcnt(0)
	s_barrier
	ds_read2st64_b32 v[0:1], v71 offset0:16 offset1:18
	s_lshl_b32 s0, s6, 1
	s_mov_b32 s1, s3
	s_mov_b32 s45, 0x7f800000
	s_mov_b32 s44, 0x3f317217
	s_waitcnt lgkmcnt(0)
	v_cndmask_b32_e64 v41, v0, 0, s[40:41]
	v_add_f32_e32 v35, v0, v1
	v_lshl_add_u64 v[32:33], v[82:83], 0, s[0:1]
	v_add_u32_e32 v36, s63, v129
	s_mov_b32 s47, 0
	v_mov_b32_e32 v37, v128
	v_mov_b32_e32 v38, v118
	s_mov_b32 s94, 0x1ea31000
	s_movk_i32 s6, 0x3200
	v_mad_i64_i32 v[222:223], s[0:1], v36, s6, v[32:33]
	s_mov_b64 s[0:1], 0x3200
	global_load_ushort v188, v[222:223], off offset:1024
	v_lshl_add_u64 v[222:223], v[222:223], 0, s[0:1]
	global_load_ushort v189, v[222:223], off offset:1024
	v_lshl_add_u64 v[222:223], v[222:223], 0, s[0:1]
	global_load_ushort v190, v[222:223], off offset:1024
	v_lshl_add_u64 v[222:223], v[222:223], 0, s[0:1]
	global_load_ushort v191, v[222:223], off offset:1024
	v_lshl_add_u64 v[222:223], v[222:223], 0, s[0:1]
	global_load_ushort v192, v[222:223], off offset:1024
	v_lshl_add_u64 v[222:223], v[222:223], 0, s[0:1]
	global_load_ushort v193, v[222:223], off offset:1024
	v_lshl_add_u64 v[222:223], v[222:223], 0, s[0:1]
	global_load_ushort v194, v[222:223], off offset:1024
	v_lshl_add_u64 v[222:223], v[222:223], 0, s[0:1]
	global_load_ushort v195, v[222:223], off offset:1024
	v_lshl_add_u64 v[222:223], v[222:223], 0, s[0:1]
	global_load_ushort v196, v[222:223], off offset:1024
	v_lshl_add_u64 v[222:223], v[222:223], 0, s[0:1]
	global_load_ushort v197, v[222:223], off offset:1024
	v_lshl_add_u64 v[222:223], v[222:223], 0, s[0:1]
	global_load_ushort v198, v[222:223], off offset:1024
	v_lshl_add_u64 v[222:223], v[222:223], 0, s[0:1]
	global_load_ushort v199, v[222:223], off offset:1024
	v_lshl_add_u64 v[222:223], v[222:223], 0, s[0:1]
	global_load_ushort v200, v[222:223], off offset:1024
	v_lshl_add_u64 v[222:223], v[222:223], 0, s[0:1]
	global_load_ushort v201, v[222:223], off offset:1024
	v_lshl_add_u64 v[222:223], v[222:223], 0, s[0:1]
	global_load_ushort v202, v[222:223], off offset:1024
	v_lshl_add_u64 v[222:223], v[222:223], 0, s[0:1]
	global_load_ushort v203, v[222:223], off offset:1024
	v_lshl_add_u64 v[222:223], v[222:223], 0, s[0:1]
	global_load_ushort v204, v[222:223], off offset:1024
	v_lshl_add_u64 v[222:223], v[222:223], 0, s[0:1]
	global_load_ushort v206, v[222:223], off offset:1024
	v_lshl_add_u64 v[222:223], v[222:223], 0, s[0:1]
	global_load_ushort v207, v[222:223], off offset:1024
	v_lshl_add_u64 v[222:223], v[222:223], 0, s[0:1]
	global_load_ushort v208, v[222:223], off offset:1024
	v_lshl_add_u64 v[222:223], v[222:223], 0, s[0:1]
	global_load_ushort v209, v[222:223], off offset:1024
	v_lshl_add_u64 v[222:223], v[222:223], 0, s[0:1]
	global_load_ushort v210, v[222:223], off offset:1024
	v_lshl_add_u64 v[222:223], v[222:223], 0, s[0:1]
	global_load_ushort v211, v[222:223], off offset:1024
	v_lshl_add_u64 v[222:223], v[222:223], 0, s[0:1]
	global_load_ushort v212, v[222:223], off offset:1024
	v_lshl_add_u64 v[222:223], v[222:223], 0, s[0:1]
	global_load_ushort v213, v[222:223], off offset:1024
	v_lshl_add_u64 v[222:223], v[222:223], 0, s[0:1]
	global_load_ushort v214, v[222:223], off offset:1024
	v_lshl_add_u64 v[222:223], v[222:223], 0, s[0:1]
	global_load_ushort v215, v[222:223], off offset:1024
	v_lshl_add_u64 v[222:223], v[222:223], 0, s[0:1]
	global_load_ushort v216, v[222:223], off offset:1024
	v_lshl_add_u64 v[222:223], v[222:223], 0, s[0:1]
	global_load_ushort v217, v[222:223], off offset:1024
	v_lshl_add_u64 v[222:223], v[222:223], 0, s[0:1]
	global_load_ushort v218, v[222:223], off offset:1024
	v_lshl_add_u64 v[222:223], v[222:223], 0, s[0:1]
	global_load_ushort v219, v[222:223], off offset:1024
	v_lshl_add_u64 v[222:223], v[222:223], 0, s[0:1]
	global_load_ushort v220, v[222:223], off offset:1024
	s_branch .Lga_h0
.Lga_h0:
	ds_read_b128 v[12:15], v37
	ds_read_b128 v[8:11], v37 offset:16
	ds_read_b128 v[4:7], v37 offset:32
	ds_read_b128 v[0:3], v37 offset:48
	v_add_u32_e32 v39, s47, v129
	v_cmp_gt_i32_e32 vcc, s46, v39
	v_mov_b32_e32 v40, 0
	v_mov_b32_e32 v42, 0
	s_and_saveexec_b64 s[0:1], vcc
	s_cbranch_execz .Lga_a0
	s_waitcnt vmcnt(31)
	v_lshlrev_b32_e32 v42, 16, v188
.Lga_a0:
	s_or_b64 exec, exec, s[0:1]
	s_waitcnt lgkmcnt(2)
	v_mov_b32_e32 v45, v8
	v_mov_b32_e32 v8, v13
	v_mov_b32_e32 v44, v12
	v_pk_mul_f32 v[8:9], v[18:19], v[8:9]
	v_mov_b32_e32 v12, v14
	v_pk_fma_f32 v[8:9], v[16:17], v[44:45], v[8:9]
	v_mov_b32_e32 v13, v10
	v_pk_fma_f32 v[8:9], v[20:21], v[12:13], v[8:9]
	v_mov_b32_e32 v10, v15
	v_pk_fma_f32 v[8:9], v[22:23], v[10:11], v[8:9]
	s_mov_b32 s0, 0x800000
	v_add_f32_e32 v8, v34, v8
	v_add_f32_e32 v10, v8, v9
	s_waitcnt lgkmcnt(0)
	v_mov_b32_e32 v9, v0
	v_mov_b32_e32 v0, v5
	v_mov_b32_e32 v8, v4
	v_pk_mul_f32 v[0:1], v[26:27], v[0:1]
	v_mov_b32_e32 v4, v6
	v_pk_fma_f32 v[0:1], v[24:25], v[8:9], v[0:1]
	v_mov_b32_e32 v5, v2
	v_pk_fma_f32 v[0:1], v[28:29], v[4:5], v[0:1]
	v_mov_b32_e32 v2, v7
	v_pk_fma_f32 v[0:1], v[30:31], v[2:3], v[0:1]
	s_nop 0
	v_add_f32_e32 v0, v10, v0
	v_add_f32_e32 v0, v0, v1
	v_mul_f32_e64 v1, |v0|, s95
	v_exp_f32_e32 v1, v1
	v_min_f32_e32 v0, 0, v0
	v_add_f32_e32 v1, 1.0, v1
	v_cmp_gt_f32_e64 s[0:1], s0, v1
	s_nop 1
	v_cndmask_b32_e64 v2, 0, 32, s[0:1]
	v_ldexp_f32 v1, v1, v2
	v_log_f32_e32 v1, v1
	s_nop 0
	v_mul_f32_e32 v2, 0x3f317217, v1
	v_fma_f32 v2, v1, s44, -v2
	v_fmac_f32_e32 v2, 0x3377d1cf, v1
	v_fmac_f32_e32 v2, 0x3f317217, v1
	v_cmp_lt_f32_e64 s[6:7], |v1|, s45
	s_nop 1
	v_cndmask_b32_e64 v1, v1, v2, s[6:7]
	v_cndmask_b32_e64 v2, 0, v163, s[0:1]
	v_sub_f32_e32 v1, v1, v2
	v_sub_f32_e32 v0, v0, v1
	v_mul_f32_e32 v0, 0x3d800000, v0
	v_cndmask_b32_e32 v0, 0, v0, vcc
	v_add_f32_e32 v41, v41, v0
	v_sub_f32_e32 v0, v35, v41
	v_mul_f32_e32 v0, 0x3fb8aa3b, v0
	v_exp_f32_e32 v0, v0
	s_nop 0
	v_mul_f32_e32 v0, v0, v42
	v_bfe_u32 v1, v0, 16, 1
	v_add3_u32 v0, v0, v1, s33
	ds_write_b16_d16_hi v38, v0
	ds_read_b128 v[12:15], v37 offset:64
	ds_read_b128 v[8:11], v37 offset:80
	ds_read_b128 v[4:7], v37 offset:96
	ds_read_b128 v[0:3], v37 offset:112
	v_add_u32_e32 v42, 1, v39
	v_cmp_gt_i32_e32 vcc, s46, v42
	s_and_saveexec_b64 s[0:1], vcc
	s_cbranch_execz .Lga_b0
	s_waitcnt vmcnt(30)
	v_lshlrev_b32_e32 v40, 16, v189
.Lga_b0:
	s_or_b64 exec, exec, s[0:1]
	s_waitcnt lgkmcnt(2)
	v_mov_b32_e32 v43, v8
	v_mov_b32_e32 v8, v13
	v_mov_b32_e32 v42, v12
	v_pk_mul_f32 v[8:9], v[18:19], v[8:9]
	v_mov_b32_e32 v12, v14
	v_pk_fma_f32 v[8:9], v[16:17], v[42:43], v[8:9]
	v_mov_b32_e32 v13, v10
	v_pk_fma_f32 v[8:9], v[20:21], v[12:13], v[8:9]
	v_mov_b32_e32 v10, v15
	v_pk_fma_f32 v[8:9], v[22:23], v[10:11], v[8:9]
	s_mov_b32 s0, 0x800000
	v_add_f32_e32 v8, v34, v8
	v_add_f32_e32 v10, v8, v9
	s_waitcnt lgkmcnt(0)
	v_mov_b32_e32 v9, v0
	v_mov_b32_e32 v0, v5
	v_mov_b32_e32 v8, v4
	v_pk_mul_f32 v[0:1], v[26:27], v[0:1]
	v_mov_b32_e32 v4, v6
	v_pk_fma_f32 v[0:1], v[24:25], v[8:9], v[0:1]
	v_mov_b32_e32 v5, v2
	v_pk_fma_f32 v[0:1], v[28:29], v[4:5], v[0:1]
	v_mov_b32_e32 v2, v7
	v_pk_fma_f32 v[0:1], v[30:31], v[2:3], v[0:1]
	v_add_u32_e32 v42, 2, v39
	v_add_f32_e32 v0, v10, v0
	v_add_f32_e32 v0, v0, v1
	v_mul_f32_e64 v1, |v0|, s95
	v_exp_f32_e32 v1, v1
	v_min_f32_e32 v0, 0, v0
	v_add_f32_e32 v1, 1.0, v1
	v_cmp_gt_f32_e64 s[0:1], s0, v1
	s_nop 1
	v_cndmask_b32_e64 v2, 0, 32, s[0:1]
	v_ldexp_f32 v1, v1, v2
	v_log_f32_e32 v1, v1
	s_nop 0
	v_mul_f32_e32 v2, 0x3f317217, v1
	v_fma_f32 v2, v1, s44, -v2
	v_fmac_f32_e32 v2, 0x3377d1cf, v1
	v_fmac_f32_e32 v2, 0x3f317217, v1
	v_cmp_lt_f32_e64 s[6:7], |v1|, s45
	s_nop 1
	v_cndmask_b32_e64 v1, v1, v2, s[6:7]
	v_cndmask_b32_e64 v2, 0, v163, s[0:1]
	v_sub_f32_e32 v1, v1, v2
	v_sub_f32_e32 v0, v0, v1
	v_mul_f32_e32 v0, 0x3d800000, v0
	v_cndmask_b32_e32 v0, 0, v0, vcc
	v_add_f32_e32 v41, v41, v0
	v_sub_f32_e32 v0, v35, v41
	v_mul_f32_e32 v0, 0x3fb8aa3b, v0
	v_exp_f32_e32 v0, v0
	v_cmp_gt_i32_e32 vcc, s46, v42
	v_mov_b32_e32 v42, 0
	v_mul_f32_e32 v0, v0, v40
	v_bfe_u32 v1, v0, 16, 1
	v_add3_u32 v0, v0, v1, s33
	ds_write_b16_d16_hi v38, v0 offset:272
	ds_read_b128 v[12:15], v37 offset:128
	ds_read_b128 v[8:11], v37 offset:144
	ds_read_b128 v[4:7], v37 offset:160
	ds_read_b128 v[0:3], v37 offset:176
	v_mov_b32_e32 v40, 0
	s_and_saveexec_b64 s[0:1], vcc
	s_cbranch_execz .Lga_c0
	s_waitcnt vmcnt(29)
	v_lshlrev_b32_e32 v42, 16, v190
.Lga_c0:
	s_or_b64 exec, exec, s[0:1]
	s_waitcnt lgkmcnt(2)
	v_mov_b32_e32 v45, v8
	v_mov_b32_e32 v8, v13
	v_mov_b32_e32 v44, v12
	v_pk_mul_f32 v[8:9], v[18:19], v[8:9]
	v_mov_b32_e32 v12, v14
	v_pk_fma_f32 v[8:9], v[16:17], v[44:45], v[8:9]
	v_mov_b32_e32 v13, v10
	v_pk_fma_f32 v[8:9], v[20:21], v[12:13], v[8:9]
	v_mov_b32_e32 v10, v15
	v_pk_fma_f32 v[8:9], v[22:23], v[10:11], v[8:9]
	s_mov_b32 s0, 0x800000
	v_add_f32_e32 v8, v34, v8
	v_add_f32_e32 v10, v8, v9
	s_waitcnt lgkmcnt(0)
	v_mov_b32_e32 v9, v0
	v_mov_b32_e32 v0, v5
	v_mov_b32_e32 v8, v4
	v_pk_mul_f32 v[0:1], v[26:27], v[0:1]
	v_mov_b32_e32 v4, v6
	v_pk_fma_f32 v[0:1], v[24:25], v[8:9], v[0:1]
	v_mov_b32_e32 v5, v2
	v_pk_fma_f32 v[0:1], v[28:29], v[4:5], v[0:1]
	v_mov_b32_e32 v2, v7
	v_pk_fma_f32 v[0:1], v[30:31], v[2:3], v[0:1]
	v_add_u32_e32 v39, 3, v39
	v_add_f32_e32 v0, v10, v0
	v_add_f32_e32 v0, v0, v1
	v_mul_f32_e64 v1, |v0|, s95
	v_exp_f32_e32 v1, v1
	v_min_f32_e32 v0, 0, v0
	v_add_f32_e32 v1, 1.0, v1
	v_cmp_gt_f32_e64 s[0:1], s0, v1
	s_nop 1
	v_cndmask_b32_e64 v2, 0, 32, s[0:1]
	v_ldexp_f32 v1, v1, v2
	v_log_f32_e32 v1, v1
	s_nop 0
	v_mul_f32_e32 v2, 0x3f317217, v1
	v_fma_f32 v2, v1, s44, -v2
	v_fmac_f32_e32 v2, 0x3377d1cf, v1
	v_fmac_f32_e32 v2, 0x3f317217, v1
	v_cmp_lt_f32_e64 s[6:7], |v1|, s45
	s_nop 1
	v_cndmask_b32_e64 v1, v1, v2, s[6:7]
	v_cndmask_b32_e64 v2, 0, v163, s[0:1]
	v_sub_f32_e32 v1, v1, v2
	v_sub_f32_e32 v0, v0, v1
	v_mul_f32_e32 v0, 0x3d800000, v0
	v_cndmask_b32_e32 v0, 0, v0, vcc
	v_add_f32_e32 v41, v41, v0
	v_sub_f32_e32 v0, v35, v41
	v_mul_f32_e32 v0, 0x3fb8aa3b, v0
	v_exp_f32_e32 v0, v0
	v_cmp_gt_i32_e32 vcc, s46, v39
	v_mul_f32_e32 v0, v0, v42
	v_bfe_u32 v1, v0, 16, 1
	v_add3_u32 v0, v0, v1, s33
	ds_write_b16_d16_hi v38, v0 offset:544
	ds_read_b128 v[12:15], v37 offset:192
	ds_read_b128 v[8:11], v37 offset:208
	ds_read_b128 v[4:7], v37 offset:224
	ds_read_b128 v[0:3], v37 offset:240
	s_and_saveexec_b64 s[0:1], vcc
	s_cbranch_execz .Lga_l0
	s_waitcnt vmcnt(28)
	v_lshlrev_b32_e32 v40, 16, v191
	s_branch .Lga_l0

.Lga_h1:
	ds_read_b128 v[12:15], v37
	ds_read_b128 v[8:11], v37 offset:16
	ds_read_b128 v[4:7], v37 offset:32
	ds_read_b128 v[0:3], v37 offset:48
	v_add_u32_e32 v39, s47, v129
	v_cmp_gt_i32_e32 vcc, s46, v39
	v_mov_b32_e32 v40, 0
	v_mov_b32_e32 v42, 0
	s_and_saveexec_b64 s[0:1], vcc
	s_cbranch_execz .Lga_a1
	s_waitcnt vmcnt(27)
	v_lshlrev_b32_e32 v42, 16, v192
.Lga_a1:
	s_or_b64 exec, exec, s[0:1]
	s_waitcnt lgkmcnt(2)
	v_mov_b32_e32 v45, v8
	v_mov_b32_e32 v8, v13
	v_mov_b32_e32 v44, v12
	v_pk_mul_f32 v[8:9], v[18:19], v[8:9]
	v_mov_b32_e32 v12, v14
	v_pk_fma_f32 v[8:9], v[16:17], v[44:45], v[8:9]
	v_mov_b32_e32 v13, v10
	v_pk_fma_f32 v[8:9], v[20:21], v[12:13], v[8:9]
	v_mov_b32_e32 v10, v15
	v_pk_fma_f32 v[8:9], v[22:23], v[10:11], v[8:9]
	s_mov_b32 s0, 0x800000
	v_add_f32_e32 v8, v34, v8
	v_add_f32_e32 v10, v8, v9
	s_waitcnt lgkmcnt(0)
	v_mov_b32_e32 v9, v0
	v_mov_b32_e32 v0, v5
	v_mov_b32_e32 v8, v4
	v_pk_mul_f32 v[0:1], v[26:27], v[0:1]
	v_mov_b32_e32 v4, v6
	v_pk_fma_f32 v[0:1], v[24:25], v[8:9], v[0:1]
	v_mov_b32_e32 v5, v2
	v_pk_fma_f32 v[0:1], v[28:29], v[4:5], v[0:1]
	v_mov_b32_e32 v2, v7
	v_pk_fma_f32 v[0:1], v[30:31], v[2:3], v[0:1]
	s_nop 0
	v_add_f32_e32 v0, v10, v0
	v_add_f32_e32 v0, v0, v1
	v_mul_f32_e64 v1, |v0|, s95
	v_exp_f32_e32 v1, v1
	v_min_f32_e32 v0, 0, v0
	v_add_f32_e32 v1, 1.0, v1
	v_cmp_gt_f32_e64 s[0:1], s0, v1
	s_nop 1
	v_cndmask_b32_e64 v2, 0, 32, s[0:1]
	v_ldexp_f32 v1, v1, v2
	v_log_f32_e32 v1, v1
	s_nop 0
	v_mul_f32_e32 v2, 0x3f317217, v1
	v_fma_f32 v2, v1, s44, -v2
	v_fmac_f32_e32 v2, 0x3377d1cf, v1
	v_fmac_f32_e32 v2, 0x3f317217, v1
	v_cmp_lt_f32_e64 s[6:7], |v1|, s45
	s_nop 1
	v_cndmask_b32_e64 v1, v1, v2, s[6:7]
	v_cndmask_b32_e64 v2, 0, v163, s[0:1]
	v_sub_f32_e32 v1, v1, v2
	v_sub_f32_e32 v0, v0, v1
	v_mul_f32_e32 v0, 0x3d800000, v0
	v_cndmask_b32_e32 v0, 0, v0, vcc
	v_add_f32_e32 v41, v41, v0
	v_sub_f32_e32 v0, v35, v41
	v_mul_f32_e32 v0, 0x3fb8aa3b, v0
	v_exp_f32_e32 v0, v0
	s_nop 0
	v_mul_f32_e32 v0, v0, v42
	v_bfe_u32 v1, v0, 16, 1
	v_add3_u32 v0, v0, v1, s33
	ds_write_b16_d16_hi v38, v0
	ds_read_b128 v[12:15], v37 offset:64
	ds_read_b128 v[8:11], v37 offset:80
	ds_read_b128 v[4:7], v37 offset:96
	ds_read_b128 v[0:3], v37 offset:112
	v_add_u32_e32 v42, 1, v39
	v_cmp_gt_i32_e32 vcc, s46, v42
	s_and_saveexec_b64 s[0:1], vcc
	s_cbranch_execz .Lga_b1
	s_waitcnt vmcnt(26)
	v_lshlrev_b32_e32 v40, 16, v193
.Lga_b1:
	s_or_b64 exec, exec, s[0:1]
	s_waitcnt lgkmcnt(2)
	v_mov_b32_e32 v43, v8
	v_mov_b32_e32 v8, v13
	v_mov_b32_e32 v42, v12
	v_pk_mul_f32 v[8:9], v[18:19], v[8:9]
	v_mov_b32_e32 v12, v14
	v_pk_fma_f32 v[8:9], v[16:17], v[42:43], v[8:9]
	v_mov_b32_e32 v13, v10
	v_pk_fma_f32 v[8:9], v[20:21], v[12:13], v[8:9]
	v_mov_b32_e32 v10, v15
	v_pk_fma_f32 v[8:9], v[22:23], v[10:11], v[8:9]
	s_mov_b32 s0, 0x800000
	v_add_f32_e32 v8, v34, v8
	v_add_f32_e32 v10, v8, v9
	s_waitcnt lgkmcnt(0)
	v_mov_b32_e32 v9, v0
	v_mov_b32_e32 v0, v5
	v_mov_b32_e32 v8, v4
	v_pk_mul_f32 v[0:1], v[26:27], v[0:1]
	v_mov_b32_e32 v4, v6
	v_pk_fma_f32 v[0:1], v[24:25], v[8:9], v[0:1]
	v_mov_b32_e32 v5, v2
	v_pk_fma_f32 v[0:1], v[28:29], v[4:5], v[0:1]
	v_mov_b32_e32 v2, v7
	v_pk_fma_f32 v[0:1], v[30:31], v[2:3], v[0:1]
	v_add_u32_e32 v42, 2, v39
	v_add_f32_e32 v0, v10, v0
	v_add_f32_e32 v0, v0, v1
	v_mul_f32_e64 v1, |v0|, s95
	v_exp_f32_e32 v1, v1
	v_min_f32_e32 v0, 0, v0
	v_add_f32_e32 v1, 1.0, v1
	v_cmp_gt_f32_e64 s[0:1], s0, v1
	s_nop 1
	v_cndmask_b32_e64 v2, 0, 32, s[0:1]
	v_ldexp_f32 v1, v1, v2
	v_log_f32_e32 v1, v1
	s_nop 0
	v_mul_f32_e32 v2, 0x3f317217, v1
	v_fma_f32 v2, v1, s44, -v2
	v_fmac_f32_e32 v2, 0x3377d1cf, v1
	v_fmac_f32_e32 v2, 0x3f317217, v1
	v_cmp_lt_f32_e64 s[6:7], |v1|, s45
	s_nop 1
	v_cndmask_b32_e64 v1, v1, v2, s[6:7]
	v_cndmask_b32_e64 v2, 0, v163, s[0:1]
	v_sub_f32_e32 v1, v1, v2
	v_sub_f32_e32 v0, v0, v1
	v_mul_f32_e32 v0, 0x3d800000, v0
	v_cndmask_b32_e32 v0, 0, v0, vcc
	v_add_f32_e32 v41, v41, v0
	v_sub_f32_e32 v0, v35, v41
	v_mul_f32_e32 v0, 0x3fb8aa3b, v0
	v_exp_f32_e32 v0, v0
	v_cmp_gt_i32_e32 vcc, s46, v42
	v_mov_b32_e32 v42, 0
	v_mul_f32_e32 v0, v0, v40
	v_bfe_u32 v1, v0, 16, 1
	v_add3_u32 v0, v0, v1, s33
	ds_write_b16_d16_hi v38, v0 offset:272
	ds_read_b128 v[12:15], v37 offset:128
	ds_read_b128 v[8:11], v37 offset:144
	ds_read_b128 v[4:7], v37 offset:160
	ds_read_b128 v[0:3], v37 offset:176
	v_mov_b32_e32 v40, 0
	s_and_saveexec_b64 s[0:1], vcc
	s_cbranch_execz .Lga_c1
	s_waitcnt vmcnt(25)
	v_lshlrev_b32_e32 v42, 16, v194
.Lga_c1:
	s_or_b64 exec, exec, s[0:1]
	s_waitcnt lgkmcnt(2)
	v_mov_b32_e32 v45, v8
	v_mov_b32_e32 v8, v13
	v_mov_b32_e32 v44, v12
	v_pk_mul_f32 v[8:9], v[18:19], v[8:9]
	v_mov_b32_e32 v12, v14
	v_pk_fma_f32 v[8:9], v[16:17], v[44:45], v[8:9]
	v_mov_b32_e32 v13, v10
	v_pk_fma_f32 v[8:9], v[20:21], v[12:13], v[8:9]
	v_mov_b32_e32 v10, v15
	v_pk_fma_f32 v[8:9], v[22:23], v[10:11], v[8:9]
	s_mov_b32 s0, 0x800000
	v_add_f32_e32 v8, v34, v8
	v_add_f32_e32 v10, v8, v9
	s_waitcnt lgkmcnt(0)
	v_mov_b32_e32 v9, v0
	v_mov_b32_e32 v0, v5
	v_mov_b32_e32 v8, v4
	v_pk_mul_f32 v[0:1], v[26:27], v[0:1]
	v_mov_b32_e32 v4, v6
	v_pk_fma_f32 v[0:1], v[24:25], v[8:9], v[0:1]
	v_mov_b32_e32 v5, v2
	v_pk_fma_f32 v[0:1], v[28:29], v[4:5], v[0:1]
	v_mov_b32_e32 v2, v7
	v_pk_fma_f32 v[0:1], v[30:31], v[2:3], v[0:1]
	v_add_u32_e32 v39, 3, v39
	v_add_f32_e32 v0, v10, v0
	v_add_f32_e32 v0, v0, v1
	v_mul_f32_e64 v1, |v0|, s95
	v_exp_f32_e32 v1, v1
	v_min_f32_e32 v0, 0, v0
	v_add_f32_e32 v1, 1.0, v1
	v_cmp_gt_f32_e64 s[0:1], s0, v1
	s_nop 1
	v_cndmask_b32_e64 v2, 0, 32, s[0:1]
	v_ldexp_f32 v1, v1, v2
	v_log_f32_e32 v1, v1
	s_nop 0
	v_mul_f32_e32 v2, 0x3f317217, v1
	v_fma_f32 v2, v1, s44, -v2
	v_fmac_f32_e32 v2, 0x3377d1cf, v1
	v_fmac_f32_e32 v2, 0x3f317217, v1
	v_cmp_lt_f32_e64 s[6:7], |v1|, s45
	s_nop 1
	v_cndmask_b32_e64 v1, v1, v2, s[6:7]
	v_cndmask_b32_e64 v2, 0, v163, s[0:1]
	v_sub_f32_e32 v1, v1, v2
	v_sub_f32_e32 v0, v0, v1
	v_mul_f32_e32 v0, 0x3d800000, v0
	v_cndmask_b32_e32 v0, 0, v0, vcc
	v_add_f32_e32 v41, v41, v0
	v_sub_f32_e32 v0, v35, v41
	v_mul_f32_e32 v0, 0x3fb8aa3b, v0
	v_exp_f32_e32 v0, v0
	v_cmp_gt_i32_e32 vcc, s46, v39
	v_mul_f32_e32 v0, v0, v42
	v_bfe_u32 v1, v0, 16, 1
	v_add3_u32 v0, v0, v1, s33
	ds_write_b16_d16_hi v38, v0 offset:544
	ds_read_b128 v[12:15], v37 offset:192
	ds_read_b128 v[8:11], v37 offset:208
	ds_read_b128 v[4:7], v37 offset:224
	ds_read_b128 v[0:3], v37 offset:240
	s_and_saveexec_b64 s[0:1], vcc
	s_cbranch_execz .Lga_l1
	s_waitcnt vmcnt(24)
	v_lshlrev_b32_e32 v40, 16, v195
	s_branch .Lga_l1

.Lga_h2:
	ds_read_b128 v[12:15], v37
	ds_read_b128 v[8:11], v37 offset:16
	ds_read_b128 v[4:7], v37 offset:32
	ds_read_b128 v[0:3], v37 offset:48
	v_add_u32_e32 v39, s47, v129
	v_cmp_gt_i32_e32 vcc, s46, v39
	v_mov_b32_e32 v40, 0
	v_mov_b32_e32 v42, 0
	s_and_saveexec_b64 s[0:1], vcc
	s_cbranch_execz .Lga_a2
	s_waitcnt vmcnt(23)
	v_lshlrev_b32_e32 v42, 16, v196
.Lga_a2:
	s_or_b64 exec, exec, s[0:1]
	s_waitcnt lgkmcnt(2)
	v_mov_b32_e32 v45, v8
	v_mov_b32_e32 v8, v13
	v_mov_b32_e32 v44, v12
	v_pk_mul_f32 v[8:9], v[18:19], v[8:9]
	v_mov_b32_e32 v12, v14
	v_pk_fma_f32 v[8:9], v[16:17], v[44:45], v[8:9]
	v_mov_b32_e32 v13, v10
	v_pk_fma_f32 v[8:9], v[20:21], v[12:13], v[8:9]
	v_mov_b32_e32 v10, v15
	v_pk_fma_f32 v[8:9], v[22:23], v[10:11], v[8:9]
	s_mov_b32 s0, 0x800000
	v_add_f32_e32 v8, v34, v8
	v_add_f32_e32 v10, v8, v9
	s_waitcnt lgkmcnt(0)
	v_mov_b32_e32 v9, v0
	v_mov_b32_e32 v0, v5
	v_mov_b32_e32 v8, v4
	v_pk_mul_f32 v[0:1], v[26:27], v[0:1]
	v_mov_b32_e32 v4, v6
	v_pk_fma_f32 v[0:1], v[24:25], v[8:9], v[0:1]
	v_mov_b32_e32 v5, v2
	v_pk_fma_f32 v[0:1], v[28:29], v[4:5], v[0:1]
	v_mov_b32_e32 v2, v7
	v_pk_fma_f32 v[0:1], v[30:31], v[2:3], v[0:1]
	s_nop 0
	v_add_f32_e32 v0, v10, v0
	v_add_f32_e32 v0, v0, v1
	v_mul_f32_e64 v1, |v0|, s95
	v_exp_f32_e32 v1, v1
	v_min_f32_e32 v0, 0, v0
	v_add_f32_e32 v1, 1.0, v1
	v_cmp_gt_f32_e64 s[0:1], s0, v1
	s_nop 1
	v_cndmask_b32_e64 v2, 0, 32, s[0:1]
	v_ldexp_f32 v1, v1, v2
	v_log_f32_e32 v1, v1
	s_nop 0
	v_mul_f32_e32 v2, 0x3f317217, v1
	v_fma_f32 v2, v1, s44, -v2
	v_fmac_f32_e32 v2, 0x3377d1cf, v1
	v_fmac_f32_e32 v2, 0x3f317217, v1
	v_cmp_lt_f32_e64 s[6:7], |v1|, s45
	s_nop 1
	v_cndmask_b32_e64 v1, v1, v2, s[6:7]
	v_cndmask_b32_e64 v2, 0, v163, s[0:1]
	v_sub_f32_e32 v1, v1, v2
	v_sub_f32_e32 v0, v0, v1
	v_mul_f32_e32 v0, 0x3d800000, v0
	v_cndmask_b32_e32 v0, 0, v0, vcc
	v_add_f32_e32 v41, v41, v0
	v_sub_f32_e32 v0, v35, v41
	v_mul_f32_e32 v0, 0x3fb8aa3b, v0
	v_exp_f32_e32 v0, v0
	s_nop 0
	v_mul_f32_e32 v0, v0, v42
	v_bfe_u32 v1, v0, 16, 1
	v_add3_u32 v0, v0, v1, s33
	ds_write_b16_d16_hi v38, v0
	ds_read_b128 v[12:15], v37 offset:64
	ds_read_b128 v[8:11], v37 offset:80
	ds_read_b128 v[4:7], v37 offset:96
	ds_read_b128 v[0:3], v37 offset:112
	v_add_u32_e32 v42, 1, v39
	v_cmp_gt_i32_e32 vcc, s46, v42
	s_and_saveexec_b64 s[0:1], vcc
	s_cbranch_execz .Lga_b2
	s_waitcnt vmcnt(22)
	v_lshlrev_b32_e32 v40, 16, v197
.Lga_b2:
	s_or_b64 exec, exec, s[0:1]
	s_waitcnt lgkmcnt(2)
	v_mov_b32_e32 v43, v8
	v_mov_b32_e32 v8, v13
	v_mov_b32_e32 v42, v12
	v_pk_mul_f32 v[8:9], v[18:19], v[8:9]
	v_mov_b32_e32 v12, v14
	v_pk_fma_f32 v[8:9], v[16:17], v[42:43], v[8:9]
	v_mov_b32_e32 v13, v10
	v_pk_fma_f32 v[8:9], v[20:21], v[12:13], v[8:9]
	v_mov_b32_e32 v10, v15
	v_pk_fma_f32 v[8:9], v[22:23], v[10:11], v[8:9]
	s_mov_b32 s0, 0x800000
	v_add_f32_e32 v8, v34, v8
	v_add_f32_e32 v10, v8, v9
	s_waitcnt lgkmcnt(0)
	v_mov_b32_e32 v9, v0
	v_mov_b32_e32 v0, v5
	v_mov_b32_e32 v8, v4
	v_pk_mul_f32 v[0:1], v[26:27], v[0:1]
	v_mov_b32_e32 v4, v6
	v_pk_fma_f32 v[0:1], v[24:25], v[8:9], v[0:1]
	v_mov_b32_e32 v5, v2
	v_pk_fma_f32 v[0:1], v[28:29], v[4:5], v[0:1]
	v_mov_b32_e32 v2, v7
	v_pk_fma_f32 v[0:1], v[30:31], v[2:3], v[0:1]
	v_add_u32_e32 v42, 2, v39
	v_add_f32_e32 v0, v10, v0
	v_add_f32_e32 v0, v0, v1
	v_mul_f32_e64 v1, |v0|, s95
	v_exp_f32_e32 v1, v1
	v_min_f32_e32 v0, 0, v0
	v_add_f32_e32 v1, 1.0, v1
	v_cmp_gt_f32_e64 s[0:1], s0, v1
	s_nop 1
	v_cndmask_b32_e64 v2, 0, 32, s[0:1]
	v_ldexp_f32 v1, v1, v2
	v_log_f32_e32 v1, v1
	s_nop 0
	v_mul_f32_e32 v2, 0x3f317217, v1
	v_fma_f32 v2, v1, s44, -v2
	v_fmac_f32_e32 v2, 0x3377d1cf, v1
	v_fmac_f32_e32 v2, 0x3f317217, v1
	v_cmp_lt_f32_e64 s[6:7], |v1|, s45
	s_nop 1
	v_cndmask_b32_e64 v1, v1, v2, s[6:7]
	v_cndmask_b32_e64 v2, 0, v163, s[0:1]
	v_sub_f32_e32 v1, v1, v2
	v_sub_f32_e32 v0, v0, v1
	v_mul_f32_e32 v0, 0x3d800000, v0
	v_cndmask_b32_e32 v0, 0, v0, vcc
	v_add_f32_e32 v41, v41, v0
	v_sub_f32_e32 v0, v35, v41
	v_mul_f32_e32 v0, 0x3fb8aa3b, v0
	v_exp_f32_e32 v0, v0
	v_cmp_gt_i32_e32 vcc, s46, v42
	v_mov_b32_e32 v42, 0
	v_mul_f32_e32 v0, v0, v40
	v_bfe_u32 v1, v0, 16, 1
	v_add3_u32 v0, v0, v1, s33
	ds_write_b16_d16_hi v38, v0 offset:272
	ds_read_b128 v[12:15], v37 offset:128
	ds_read_b128 v[8:11], v37 offset:144
	ds_read_b128 v[4:7], v37 offset:160
	ds_read_b128 v[0:3], v37 offset:176
	v_mov_b32_e32 v40, 0
	s_and_saveexec_b64 s[0:1], vcc
	s_cbranch_execz .Lga_c2
	s_waitcnt vmcnt(21)
	v_lshlrev_b32_e32 v42, 16, v198
.Lga_c2:
	s_or_b64 exec, exec, s[0:1]
	s_waitcnt lgkmcnt(2)
	v_mov_b32_e32 v45, v8
	v_mov_b32_e32 v8, v13
	v_mov_b32_e32 v44, v12
	v_pk_mul_f32 v[8:9], v[18:19], v[8:9]
	v_mov_b32_e32 v12, v14
	v_pk_fma_f32 v[8:9], v[16:17], v[44:45], v[8:9]
	v_mov_b32_e32 v13, v10
	v_pk_fma_f32 v[8:9], v[20:21], v[12:13], v[8:9]
	v_mov_b32_e32 v10, v15
	v_pk_fma_f32 v[8:9], v[22:23], v[10:11], v[8:9]
	s_mov_b32 s0, 0x800000
	v_add_f32_e32 v8, v34, v8
	v_add_f32_e32 v10, v8, v9
	s_waitcnt lgkmcnt(0)
	v_mov_b32_e32 v9, v0
	v_mov_b32_e32 v0, v5
	v_mov_b32_e32 v8, v4
	v_pk_mul_f32 v[0:1], v[26:27], v[0:1]
	v_mov_b32_e32 v4, v6
	v_pk_fma_f32 v[0:1], v[24:25], v[8:9], v[0:1]
	v_mov_b32_e32 v5, v2
	v_pk_fma_f32 v[0:1], v[28:29], v[4:5], v[0:1]
	v_mov_b32_e32 v2, v7
	v_pk_fma_f32 v[0:1], v[30:31], v[2:3], v[0:1]
	v_add_u32_e32 v39, 3, v39
	v_add_f32_e32 v0, v10, v0
	v_add_f32_e32 v0, v0, v1
	v_mul_f32_e64 v1, |v0|, s95
	v_exp_f32_e32 v1, v1
	v_min_f32_e32 v0, 0, v0
	v_add_f32_e32 v1, 1.0, v1
	v_cmp_gt_f32_e64 s[0:1], s0, v1
	s_nop 1
	v_cndmask_b32_e64 v2, 0, 32, s[0:1]
	v_ldexp_f32 v1, v1, v2
	v_log_f32_e32 v1, v1
	s_nop 0
	v_mul_f32_e32 v2, 0x3f317217, v1
	v_fma_f32 v2, v1, s44, -v2
	v_fmac_f32_e32 v2, 0x3377d1cf, v1
	v_fmac_f32_e32 v2, 0x3f317217, v1
	v_cmp_lt_f32_e64 s[6:7], |v1|, s45
	s_nop 1
	v_cndmask_b32_e64 v1, v1, v2, s[6:7]
	v_cndmask_b32_e64 v2, 0, v163, s[0:1]
	v_sub_f32_e32 v1, v1, v2
	v_sub_f32_e32 v0, v0, v1
	v_mul_f32_e32 v0, 0x3d800000, v0
	v_cndmask_b32_e32 v0, 0, v0, vcc
	v_add_f32_e32 v41, v41, v0
	v_sub_f32_e32 v0, v35, v41
	v_mul_f32_e32 v0, 0x3fb8aa3b, v0
	v_exp_f32_e32 v0, v0
	v_cmp_gt_i32_e32 vcc, s46, v39
	v_mul_f32_e32 v0, v0, v42
	v_bfe_u32 v1, v0, 16, 1
	v_add3_u32 v0, v0, v1, s33
	ds_write_b16_d16_hi v38, v0 offset:544
	ds_read_b128 v[12:15], v37 offset:192
	ds_read_b128 v[8:11], v37 offset:208
	ds_read_b128 v[4:7], v37 offset:224
	ds_read_b128 v[0:3], v37 offset:240
	s_and_saveexec_b64 s[0:1], vcc
	s_cbranch_execz .Lga_l2
	s_waitcnt vmcnt(20)
	v_lshlrev_b32_e32 v40, 16, v199
	s_branch .Lga_l2

.Lga_h3:
	ds_read_b128 v[12:15], v37
	ds_read_b128 v[8:11], v37 offset:16
	ds_read_b128 v[4:7], v37 offset:32
	ds_read_b128 v[0:3], v37 offset:48
	v_add_u32_e32 v39, s47, v129
	v_cmp_gt_i32_e32 vcc, s46, v39
	v_mov_b32_e32 v40, 0
	v_mov_b32_e32 v42, 0
	s_and_saveexec_b64 s[0:1], vcc
	s_cbranch_execz .Lga_a3
	s_waitcnt vmcnt(19)
	v_lshlrev_b32_e32 v42, 16, v200
.Lga_a3:
	s_or_b64 exec, exec, s[0:1]
	s_waitcnt lgkmcnt(2)
	v_mov_b32_e32 v45, v8
	v_mov_b32_e32 v8, v13
	v_mov_b32_e32 v44, v12
	v_pk_mul_f32 v[8:9], v[18:19], v[8:9]
	v_mov_b32_e32 v12, v14
	v_pk_fma_f32 v[8:9], v[16:17], v[44:45], v[8:9]
	v_mov_b32_e32 v13, v10
	v_pk_fma_f32 v[8:9], v[20:21], v[12:13], v[8:9]
	v_mov_b32_e32 v10, v15
	v_pk_fma_f32 v[8:9], v[22:23], v[10:11], v[8:9]
	s_mov_b32 s0, 0x800000
	v_add_f32_e32 v8, v34, v8
	v_add_f32_e32 v10, v8, v9
	s_waitcnt lgkmcnt(0)
	v_mov_b32_e32 v9, v0
	v_mov_b32_e32 v0, v5
	v_mov_b32_e32 v8, v4
	v_pk_mul_f32 v[0:1], v[26:27], v[0:1]
	v_mov_b32_e32 v4, v6
	v_pk_fma_f32 v[0:1], v[24:25], v[8:9], v[0:1]
	v_mov_b32_e32 v5, v2
	v_pk_fma_f32 v[0:1], v[28:29], v[4:5], v[0:1]
	v_mov_b32_e32 v2, v7
	v_pk_fma_f32 v[0:1], v[30:31], v[2:3], v[0:1]
	s_nop 0
	v_add_f32_e32 v0, v10, v0
	v_add_f32_e32 v0, v0, v1
	v_mul_f32_e64 v1, |v0|, s95
	v_exp_f32_e32 v1, v1
	v_min_f32_e32 v0, 0, v0
	v_add_f32_e32 v1, 1.0, v1
	v_cmp_gt_f32_e64 s[0:1], s0, v1
	s_nop 1
	v_cndmask_b32_e64 v2, 0, 32, s[0:1]
	v_ldexp_f32 v1, v1, v2
	v_log_f32_e32 v1, v1
	s_nop 0
	v_mul_f32_e32 v2, 0x3f317217, v1
	v_fma_f32 v2, v1, s44, -v2
	v_fmac_f32_e32 v2, 0x3377d1cf, v1
	v_fmac_f32_e32 v2, 0x3f317217, v1
	v_cmp_lt_f32_e64 s[6:7], |v1|, s45
	s_nop 1
	v_cndmask_b32_e64 v1, v1, v2, s[6:7]
	v_cndmask_b32_e64 v2, 0, v163, s[0:1]
	v_sub_f32_e32 v1, v1, v2
	v_sub_f32_e32 v0, v0, v1
	v_mul_f32_e32 v0, 0x3d800000, v0
	v_cndmask_b32_e32 v0, 0, v0, vcc
	v_add_f32_e32 v41, v41, v0
	v_sub_f32_e32 v0, v35, v41
	v_mul_f32_e32 v0, 0x3fb8aa3b, v0
	v_exp_f32_e32 v0, v0
	s_nop 0
	v_mul_f32_e32 v0, v0, v42
	v_bfe_u32 v1, v0, 16, 1
	v_add3_u32 v0, v0, v1, s33
	ds_write_b16_d16_hi v38, v0
	ds_read_b128 v[12:15], v37 offset:64
	ds_read_b128 v[8:11], v37 offset:80
	ds_read_b128 v[4:7], v37 offset:96
	ds_read_b128 v[0:3], v37 offset:112
	v_add_u32_e32 v42, 1, v39
	v_cmp_gt_i32_e32 vcc, s46, v42
	s_and_saveexec_b64 s[0:1], vcc
	s_cbranch_execz .Lga_b3
	s_waitcnt vmcnt(18)
	v_lshlrev_b32_e32 v40, 16, v201
.Lga_b3:
	s_or_b64 exec, exec, s[0:1]
	s_waitcnt lgkmcnt(2)
	v_mov_b32_e32 v43, v8
	v_mov_b32_e32 v8, v13
	v_mov_b32_e32 v42, v12
	v_pk_mul_f32 v[8:9], v[18:19], v[8:9]
	v_mov_b32_e32 v12, v14
	v_pk_fma_f32 v[8:9], v[16:17], v[42:43], v[8:9]
	v_mov_b32_e32 v13, v10
	v_pk_fma_f32 v[8:9], v[20:21], v[12:13], v[8:9]
	v_mov_b32_e32 v10, v15
	v_pk_fma_f32 v[8:9], v[22:23], v[10:11], v[8:9]
	s_mov_b32 s0, 0x800000
	v_add_f32_e32 v8, v34, v8
	v_add_f32_e32 v10, v8, v9
	s_waitcnt lgkmcnt(0)
	v_mov_b32_e32 v9, v0
	v_mov_b32_e32 v0, v5
	v_mov_b32_e32 v8, v4
	v_pk_mul_f32 v[0:1], v[26:27], v[0:1]
	v_mov_b32_e32 v4, v6
	v_pk_fma_f32 v[0:1], v[24:25], v[8:9], v[0:1]
	v_mov_b32_e32 v5, v2
	v_pk_fma_f32 v[0:1], v[28:29], v[4:5], v[0:1]
	v_mov_b32_e32 v2, v7
	v_pk_fma_f32 v[0:1], v[30:31], v[2:3], v[0:1]
	v_add_u32_e32 v42, 2, v39
	v_add_f32_e32 v0, v10, v0
	v_add_f32_e32 v0, v0, v1
	v_mul_f32_e64 v1, |v0|, s95
	v_exp_f32_e32 v1, v1
	v_min_f32_e32 v0, 0, v0
	v_add_f32_e32 v1, 1.0, v1
	v_cmp_gt_f32_e64 s[0:1], s0, v1
	s_nop 1
	v_cndmask_b32_e64 v2, 0, 32, s[0:1]
	v_ldexp_f32 v1, v1, v2
	v_log_f32_e32 v1, v1
	s_nop 0
	v_mul_f32_e32 v2, 0x3f317217, v1
	v_fma_f32 v2, v1, s44, -v2
	v_fmac_f32_e32 v2, 0x3377d1cf, v1
	v_fmac_f32_e32 v2, 0x3f317217, v1
	v_cmp_lt_f32_e64 s[6:7], |v1|, s45
	s_nop 1
	v_cndmask_b32_e64 v1, v1, v2, s[6:7]
	v_cndmask_b32_e64 v2, 0, v163, s[0:1]
	v_sub_f32_e32 v1, v1, v2
	v_sub_f32_e32 v0, v0, v1
	v_mul_f32_e32 v0, 0x3d800000, v0
	v_cndmask_b32_e32 v0, 0, v0, vcc
	v_add_f32_e32 v41, v41, v0
	v_sub_f32_e32 v0, v35, v41
	v_mul_f32_e32 v0, 0x3fb8aa3b, v0
	v_exp_f32_e32 v0, v0
	v_cmp_gt_i32_e32 vcc, s46, v42
	v_mov_b32_e32 v42, 0
	v_mul_f32_e32 v0, v0, v40
	v_bfe_u32 v1, v0, 16, 1
	v_add3_u32 v0, v0, v1, s33
	ds_write_b16_d16_hi v38, v0 offset:272
	ds_read_b128 v[12:15], v37 offset:128
	ds_read_b128 v[8:11], v37 offset:144
	ds_read_b128 v[4:7], v37 offset:160
	ds_read_b128 v[0:3], v37 offset:176
	v_mov_b32_e32 v40, 0
	s_and_saveexec_b64 s[0:1], vcc
	s_cbranch_execz .Lga_c3
	s_waitcnt vmcnt(17)
	v_lshlrev_b32_e32 v42, 16, v202
.Lga_c3:
	s_or_b64 exec, exec, s[0:1]
	s_waitcnt lgkmcnt(2)
	v_mov_b32_e32 v45, v8
	v_mov_b32_e32 v8, v13
	v_mov_b32_e32 v44, v12
	v_pk_mul_f32 v[8:9], v[18:19], v[8:9]
	v_mov_b32_e32 v12, v14
	v_pk_fma_f32 v[8:9], v[16:17], v[44:45], v[8:9]
	v_mov_b32_e32 v13, v10
	v_pk_fma_f32 v[8:9], v[20:21], v[12:13], v[8:9]
	v_mov_b32_e32 v10, v15
	v_pk_fma_f32 v[8:9], v[22:23], v[10:11], v[8:9]
	s_mov_b32 s0, 0x800000
	v_add_f32_e32 v8, v34, v8
	v_add_f32_e32 v10, v8, v9
	s_waitcnt lgkmcnt(0)
	v_mov_b32_e32 v9, v0
	v_mov_b32_e32 v0, v5
	v_mov_b32_e32 v8, v4
	v_pk_mul_f32 v[0:1], v[26:27], v[0:1]
	v_mov_b32_e32 v4, v6
	v_pk_fma_f32 v[0:1], v[24:25], v[8:9], v[0:1]
	v_mov_b32_e32 v5, v2
	v_pk_fma_f32 v[0:1], v[28:29], v[4:5], v[0:1]
	v_mov_b32_e32 v2, v7
	v_pk_fma_f32 v[0:1], v[30:31], v[2:3], v[0:1]
	v_add_u32_e32 v39, 3, v39
	v_add_f32_e32 v0, v10, v0
	v_add_f32_e32 v0, v0, v1
	v_mul_f32_e64 v1, |v0|, s95
	v_exp_f32_e32 v1, v1
	v_min_f32_e32 v0, 0, v0
	v_add_f32_e32 v1, 1.0, v1
	v_cmp_gt_f32_e64 s[0:1], s0, v1
	s_nop 1
	v_cndmask_b32_e64 v2, 0, 32, s[0:1]
	v_ldexp_f32 v1, v1, v2
	v_log_f32_e32 v1, v1
	s_nop 0
	v_mul_f32_e32 v2, 0x3f317217, v1
	v_fma_f32 v2, v1, s44, -v2
	v_fmac_f32_e32 v2, 0x3377d1cf, v1
	v_fmac_f32_e32 v2, 0x3f317217, v1
	v_cmp_lt_f32_e64 s[6:7], |v1|, s45
	s_nop 1
	v_cndmask_b32_e64 v1, v1, v2, s[6:7]
	v_cndmask_b32_e64 v2, 0, v163, s[0:1]
	v_sub_f32_e32 v1, v1, v2
	v_sub_f32_e32 v0, v0, v1
	v_mul_f32_e32 v0, 0x3d800000, v0
	v_cndmask_b32_e32 v0, 0, v0, vcc
	v_add_f32_e32 v41, v41, v0
	v_sub_f32_e32 v0, v35, v41
	v_mul_f32_e32 v0, 0x3fb8aa3b, v0
	v_exp_f32_e32 v0, v0
	v_cmp_gt_i32_e32 vcc, s46, v39
	v_mul_f32_e32 v0, v0, v42
	v_bfe_u32 v1, v0, 16, 1
	v_add3_u32 v0, v0, v1, s33
	ds_write_b16_d16_hi v38, v0 offset:544
	ds_read_b128 v[12:15], v37 offset:192
	ds_read_b128 v[8:11], v37 offset:208
	ds_read_b128 v[4:7], v37 offset:224
	ds_read_b128 v[0:3], v37 offset:240
	s_and_saveexec_b64 s[0:1], vcc
	s_cbranch_execz .Lga_l3
	s_waitcnt vmcnt(16)
	v_lshlrev_b32_e32 v40, 16, v203
	s_branch .Lga_l3

.Lga_h4:
	ds_read_b128 v[12:15], v37
	ds_read_b128 v[8:11], v37 offset:16
	ds_read_b128 v[4:7], v37 offset:32
	ds_read_b128 v[0:3], v37 offset:48
	v_add_u32_e32 v39, s47, v129
	v_cmp_gt_i32_e32 vcc, s46, v39
	v_mov_b32_e32 v40, 0
	v_mov_b32_e32 v42, 0
	s_and_saveexec_b64 s[0:1], vcc
	s_cbranch_execz .Lga_a4
	s_waitcnt vmcnt(15)
	v_lshlrev_b32_e32 v42, 16, v204
.Lga_a4:
	s_or_b64 exec, exec, s[0:1]
	s_waitcnt lgkmcnt(2)
	v_mov_b32_e32 v45, v8
	v_mov_b32_e32 v8, v13
	v_mov_b32_e32 v44, v12
	v_pk_mul_f32 v[8:9], v[18:19], v[8:9]
	v_mov_b32_e32 v12, v14
	v_pk_fma_f32 v[8:9], v[16:17], v[44:45], v[8:9]
	v_mov_b32_e32 v13, v10
	v_pk_fma_f32 v[8:9], v[20:21], v[12:13], v[8:9]
	v_mov_b32_e32 v10, v15
	v_pk_fma_f32 v[8:9], v[22:23], v[10:11], v[8:9]
	s_mov_b32 s0, 0x800000
	v_add_f32_e32 v8, v34, v8
	v_add_f32_e32 v10, v8, v9
	s_waitcnt lgkmcnt(0)
	v_mov_b32_e32 v9, v0
	v_mov_b32_e32 v0, v5
	v_mov_b32_e32 v8, v4
	v_pk_mul_f32 v[0:1], v[26:27], v[0:1]
	v_mov_b32_e32 v4, v6
	v_pk_fma_f32 v[0:1], v[24:25], v[8:9], v[0:1]
	v_mov_b32_e32 v5, v2
	v_pk_fma_f32 v[0:1], v[28:29], v[4:5], v[0:1]
	v_mov_b32_e32 v2, v7
	v_pk_fma_f32 v[0:1], v[30:31], v[2:3], v[0:1]
	s_nop 0
	v_add_f32_e32 v0, v10, v0
	v_add_f32_e32 v0, v0, v1
	v_mul_f32_e64 v1, |v0|, s95
	v_exp_f32_e32 v1, v1
	v_min_f32_e32 v0, 0, v0
	v_add_f32_e32 v1, 1.0, v1
	v_cmp_gt_f32_e64 s[0:1], s0, v1
	s_nop 1
	v_cndmask_b32_e64 v2, 0, 32, s[0:1]
	v_ldexp_f32 v1, v1, v2
	v_log_f32_e32 v1, v1
	s_nop 0
	v_mul_f32_e32 v2, 0x3f317217, v1
	v_fma_f32 v2, v1, s44, -v2
	v_fmac_f32_e32 v2, 0x3377d1cf, v1
	v_fmac_f32_e32 v2, 0x3f317217, v1
	v_cmp_lt_f32_e64 s[6:7], |v1|, s45
	s_nop 1
	v_cndmask_b32_e64 v1, v1, v2, s[6:7]
	v_cndmask_b32_e64 v2, 0, v163, s[0:1]
	v_sub_f32_e32 v1, v1, v2
	v_sub_f32_e32 v0, v0, v1
	v_mul_f32_e32 v0, 0x3d800000, v0
	v_cndmask_b32_e32 v0, 0, v0, vcc
	v_add_f32_e32 v41, v41, v0
	v_sub_f32_e32 v0, v35, v41
	v_mul_f32_e32 v0, 0x3fb8aa3b, v0
	v_exp_f32_e32 v0, v0
	s_nop 0
	v_mul_f32_e32 v0, v0, v42
	v_bfe_u32 v1, v0, 16, 1
	v_add3_u32 v0, v0, v1, s33
	ds_write_b16_d16_hi v38, v0
	ds_read_b128 v[12:15], v37 offset:64
	ds_read_b128 v[8:11], v37 offset:80
	ds_read_b128 v[4:7], v37 offset:96
	ds_read_b128 v[0:3], v37 offset:112
	v_add_u32_e32 v42, 1, v39
	v_cmp_gt_i32_e32 vcc, s46, v42
	s_and_saveexec_b64 s[0:1], vcc
	s_cbranch_execz .Lga_b4
	s_waitcnt vmcnt(14)
	v_lshlrev_b32_e32 v40, 16, v206
.Lga_b4:
	s_or_b64 exec, exec, s[0:1]
	s_waitcnt lgkmcnt(2)
	v_mov_b32_e32 v43, v8
	v_mov_b32_e32 v8, v13
	v_mov_b32_e32 v42, v12
	v_pk_mul_f32 v[8:9], v[18:19], v[8:9]
	v_mov_b32_e32 v12, v14
	v_pk_fma_f32 v[8:9], v[16:17], v[42:43], v[8:9]
	v_mov_b32_e32 v13, v10
	v_pk_fma_f32 v[8:9], v[20:21], v[12:13], v[8:9]
	v_mov_b32_e32 v10, v15
	v_pk_fma_f32 v[8:9], v[22:23], v[10:11], v[8:9]
	s_mov_b32 s0, 0x800000
	v_add_f32_e32 v8, v34, v8
	v_add_f32_e32 v10, v8, v9
	s_waitcnt lgkmcnt(0)
	v_mov_b32_e32 v9, v0
	v_mov_b32_e32 v0, v5
	v_mov_b32_e32 v8, v4
	v_pk_mul_f32 v[0:1], v[26:27], v[0:1]
	v_mov_b32_e32 v4, v6
	v_pk_fma_f32 v[0:1], v[24:25], v[8:9], v[0:1]
	v_mov_b32_e32 v5, v2
	v_pk_fma_f32 v[0:1], v[28:29], v[4:5], v[0:1]
	v_mov_b32_e32 v2, v7
	v_pk_fma_f32 v[0:1], v[30:31], v[2:3], v[0:1]
	v_add_u32_e32 v42, 2, v39
	v_add_f32_e32 v0, v10, v0
	v_add_f32_e32 v0, v0, v1
	v_mul_f32_e64 v1, |v0|, s95
	v_exp_f32_e32 v1, v1
	v_min_f32_e32 v0, 0, v0
	v_add_f32_e32 v1, 1.0, v1
	v_cmp_gt_f32_e64 s[0:1], s0, v1
	s_nop 1
	v_cndmask_b32_e64 v2, 0, 32, s[0:1]
	v_ldexp_f32 v1, v1, v2
	v_log_f32_e32 v1, v1
	s_nop 0
	v_mul_f32_e32 v2, 0x3f317217, v1
	v_fma_f32 v2, v1, s44, -v2
	v_fmac_f32_e32 v2, 0x3377d1cf, v1
	v_fmac_f32_e32 v2, 0x3f317217, v1
	v_cmp_lt_f32_e64 s[6:7], |v1|, s45
	s_nop 1
	v_cndmask_b32_e64 v1, v1, v2, s[6:7]
	v_cndmask_b32_e64 v2, 0, v163, s[0:1]
	v_sub_f32_e32 v1, v1, v2
	v_sub_f32_e32 v0, v0, v1
	v_mul_f32_e32 v0, 0x3d800000, v0
	v_cndmask_b32_e32 v0, 0, v0, vcc
	v_add_f32_e32 v41, v41, v0
	v_sub_f32_e32 v0, v35, v41
	v_mul_f32_e32 v0, 0x3fb8aa3b, v0
	v_exp_f32_e32 v0, v0
	v_cmp_gt_i32_e32 vcc, s46, v42
	v_mov_b32_e32 v42, 0
	v_mul_f32_e32 v0, v0, v40
	v_bfe_u32 v1, v0, 16, 1
	v_add3_u32 v0, v0, v1, s33
	ds_write_b16_d16_hi v38, v0 offset:272
	ds_read_b128 v[12:15], v37 offset:128
	ds_read_b128 v[8:11], v37 offset:144
	ds_read_b128 v[4:7], v37 offset:160
	ds_read_b128 v[0:3], v37 offset:176
	v_mov_b32_e32 v40, 0
	s_and_saveexec_b64 s[0:1], vcc
	s_cbranch_execz .Lga_c4
	s_waitcnt vmcnt(13)
	v_lshlrev_b32_e32 v42, 16, v207
.Lga_c4:
	s_or_b64 exec, exec, s[0:1]
	s_waitcnt lgkmcnt(2)
	v_mov_b32_e32 v45, v8
	v_mov_b32_e32 v8, v13
	v_mov_b32_e32 v44, v12
	v_pk_mul_f32 v[8:9], v[18:19], v[8:9]
	v_mov_b32_e32 v12, v14
	v_pk_fma_f32 v[8:9], v[16:17], v[44:45], v[8:9]
	v_mov_b32_e32 v13, v10
	v_pk_fma_f32 v[8:9], v[20:21], v[12:13], v[8:9]
	v_mov_b32_e32 v10, v15
	v_pk_fma_f32 v[8:9], v[22:23], v[10:11], v[8:9]
	s_mov_b32 s0, 0x800000
	v_add_f32_e32 v8, v34, v8
	v_add_f32_e32 v10, v8, v9
	s_waitcnt lgkmcnt(0)
	v_mov_b32_e32 v9, v0
	v_mov_b32_e32 v0, v5
	v_mov_b32_e32 v8, v4
	v_pk_mul_f32 v[0:1], v[26:27], v[0:1]
	v_mov_b32_e32 v4, v6
	v_pk_fma_f32 v[0:1], v[24:25], v[8:9], v[0:1]
	v_mov_b32_e32 v5, v2
	v_pk_fma_f32 v[0:1], v[28:29], v[4:5], v[0:1]
	v_mov_b32_e32 v2, v7
	v_pk_fma_f32 v[0:1], v[30:31], v[2:3], v[0:1]
	v_add_u32_e32 v39, 3, v39
	v_add_f32_e32 v0, v10, v0
	v_add_f32_e32 v0, v0, v1
	v_mul_f32_e64 v1, |v0|, s95
	v_exp_f32_e32 v1, v1
	v_min_f32_e32 v0, 0, v0
	v_add_f32_e32 v1, 1.0, v1
	v_cmp_gt_f32_e64 s[0:1], s0, v1
	s_nop 1
	v_cndmask_b32_e64 v2, 0, 32, s[0:1]
	v_ldexp_f32 v1, v1, v2
	v_log_f32_e32 v1, v1
	s_nop 0
	v_mul_f32_e32 v2, 0x3f317217, v1
	v_fma_f32 v2, v1, s44, -v2
	v_fmac_f32_e32 v2, 0x3377d1cf, v1
	v_fmac_f32_e32 v2, 0x3f317217, v1
	v_cmp_lt_f32_e64 s[6:7], |v1|, s45
	s_nop 1
	v_cndmask_b32_e64 v1, v1, v2, s[6:7]
	v_cndmask_b32_e64 v2, 0, v163, s[0:1]
	v_sub_f32_e32 v1, v1, v2
	v_sub_f32_e32 v0, v0, v1
	v_mul_f32_e32 v0, 0x3d800000, v0
	v_cndmask_b32_e32 v0, 0, v0, vcc
	v_add_f32_e32 v41, v41, v0
	v_sub_f32_e32 v0, v35, v41
	v_mul_f32_e32 v0, 0x3fb8aa3b, v0
	v_exp_f32_e32 v0, v0
	v_cmp_gt_i32_e32 vcc, s46, v39
	v_mul_f32_e32 v0, v0, v42
	v_bfe_u32 v1, v0, 16, 1
	v_add3_u32 v0, v0, v1, s33
	ds_write_b16_d16_hi v38, v0 offset:544
	ds_read_b128 v[12:15], v37 offset:192
	ds_read_b128 v[8:11], v37 offset:208
	ds_read_b128 v[4:7], v37 offset:224
	ds_read_b128 v[0:3], v37 offset:240
	s_and_saveexec_b64 s[0:1], vcc
	s_cbranch_execz .Lga_l4
	s_waitcnt vmcnt(12)
	v_lshlrev_b32_e32 v40, 16, v208
	s_branch .Lga_l4

.Lga_h5:
	ds_read_b128 v[12:15], v37
	ds_read_b128 v[8:11], v37 offset:16
	ds_read_b128 v[4:7], v37 offset:32
	ds_read_b128 v[0:3], v37 offset:48
	v_add_u32_e32 v39, s47, v129
	v_cmp_gt_i32_e32 vcc, s46, v39
	v_mov_b32_e32 v40, 0
	v_mov_b32_e32 v42, 0
	s_and_saveexec_b64 s[0:1], vcc
	s_cbranch_execz .Lga_a5
	s_waitcnt vmcnt(11)
	v_lshlrev_b32_e32 v42, 16, v209
.Lga_a5:
	s_or_b64 exec, exec, s[0:1]
	s_waitcnt lgkmcnt(2)
	v_mov_b32_e32 v45, v8
	v_mov_b32_e32 v8, v13
	v_mov_b32_e32 v44, v12
	v_pk_mul_f32 v[8:9], v[18:19], v[8:9]
	v_mov_b32_e32 v12, v14
	v_pk_fma_f32 v[8:9], v[16:17], v[44:45], v[8:9]
	v_mov_b32_e32 v13, v10
	v_pk_fma_f32 v[8:9], v[20:21], v[12:13], v[8:9]
	v_mov_b32_e32 v10, v15
	v_pk_fma_f32 v[8:9], v[22:23], v[10:11], v[8:9]
	s_mov_b32 s0, 0x800000
	v_add_f32_e32 v8, v34, v8
	v_add_f32_e32 v10, v8, v9
	s_waitcnt lgkmcnt(0)
	v_mov_b32_e32 v9, v0
	v_mov_b32_e32 v0, v5
	v_mov_b32_e32 v8, v4
	v_pk_mul_f32 v[0:1], v[26:27], v[0:1]
	v_mov_b32_e32 v4, v6
	v_pk_fma_f32 v[0:1], v[24:25], v[8:9], v[0:1]
	v_mov_b32_e32 v5, v2
	v_pk_fma_f32 v[0:1], v[28:29], v[4:5], v[0:1]
	v_mov_b32_e32 v2, v7
	v_pk_fma_f32 v[0:1], v[30:31], v[2:3], v[0:1]
	s_nop 0
	v_add_f32_e32 v0, v10, v0
	v_add_f32_e32 v0, v0, v1
	v_mul_f32_e64 v1, |v0|, s95
	v_exp_f32_e32 v1, v1
	v_min_f32_e32 v0, 0, v0
	v_add_f32_e32 v1, 1.0, v1
	v_cmp_gt_f32_e64 s[0:1], s0, v1
	s_nop 1
	v_cndmask_b32_e64 v2, 0, 32, s[0:1]
	v_ldexp_f32 v1, v1, v2
	v_log_f32_e32 v1, v1
	s_nop 0
	v_mul_f32_e32 v2, 0x3f317217, v1
	v_fma_f32 v2, v1, s44, -v2
	v_fmac_f32_e32 v2, 0x3377d1cf, v1
	v_fmac_f32_e32 v2, 0x3f317217, v1
	v_cmp_lt_f32_e64 s[6:7], |v1|, s45
	s_nop 1
	v_cndmask_b32_e64 v1, v1, v2, s[6:7]
	v_cndmask_b32_e64 v2, 0, v163, s[0:1]
	v_sub_f32_e32 v1, v1, v2
	v_sub_f32_e32 v0, v0, v1
	v_mul_f32_e32 v0, 0x3d800000, v0
	v_cndmask_b32_e32 v0, 0, v0, vcc
	v_add_f32_e32 v41, v41, v0
	v_sub_f32_e32 v0, v35, v41
	v_mul_f32_e32 v0, 0x3fb8aa3b, v0
	v_exp_f32_e32 v0, v0
	s_nop 0
	v_mul_f32_e32 v0, v0, v42
	v_bfe_u32 v1, v0, 16, 1
	v_add3_u32 v0, v0, v1, s33
	ds_write_b16_d16_hi v38, v0
	ds_read_b128 v[12:15], v37 offset:64
	ds_read_b128 v[8:11], v37 offset:80
	ds_read_b128 v[4:7], v37 offset:96
	ds_read_b128 v[0:3], v37 offset:112
	v_add_u32_e32 v42, 1, v39
	v_cmp_gt_i32_e32 vcc, s46, v42
	s_and_saveexec_b64 s[0:1], vcc
	s_cbranch_execz .Lga_b5
	s_waitcnt vmcnt(10)
	v_lshlrev_b32_e32 v40, 16, v210
.Lga_b5:
	s_or_b64 exec, exec, s[0:1]
	s_waitcnt lgkmcnt(2)
	v_mov_b32_e32 v43, v8
	v_mov_b32_e32 v8, v13
	v_mov_b32_e32 v42, v12
	v_pk_mul_f32 v[8:9], v[18:19], v[8:9]
	v_mov_b32_e32 v12, v14
	v_pk_fma_f32 v[8:9], v[16:17], v[42:43], v[8:9]
	v_mov_b32_e32 v13, v10
	v_pk_fma_f32 v[8:9], v[20:21], v[12:13], v[8:9]
	v_mov_b32_e32 v10, v15
	v_pk_fma_f32 v[8:9], v[22:23], v[10:11], v[8:9]
	s_mov_b32 s0, 0x800000
	v_add_f32_e32 v8, v34, v8
	v_add_f32_e32 v10, v8, v9
	s_waitcnt lgkmcnt(0)
	v_mov_b32_e32 v9, v0
	v_mov_b32_e32 v0, v5
	v_mov_b32_e32 v8, v4
	v_pk_mul_f32 v[0:1], v[26:27], v[0:1]
	v_mov_b32_e32 v4, v6
	v_pk_fma_f32 v[0:1], v[24:25], v[8:9], v[0:1]
	v_mov_b32_e32 v5, v2
	v_pk_fma_f32 v[0:1], v[28:29], v[4:5], v[0:1]
	v_mov_b32_e32 v2, v7
	v_pk_fma_f32 v[0:1], v[30:31], v[2:3], v[0:1]
	v_add_u32_e32 v42, 2, v39
	v_add_f32_e32 v0, v10, v0
	v_add_f32_e32 v0, v0, v1
	v_mul_f32_e64 v1, |v0|, s95
	v_exp_f32_e32 v1, v1
	v_min_f32_e32 v0, 0, v0
	v_add_f32_e32 v1, 1.0, v1
	v_cmp_gt_f32_e64 s[0:1], s0, v1
	s_nop 1
	v_cndmask_b32_e64 v2, 0, 32, s[0:1]
	v_ldexp_f32 v1, v1, v2
	v_log_f32_e32 v1, v1
	s_nop 0
	v_mul_f32_e32 v2, 0x3f317217, v1
	v_fma_f32 v2, v1, s44, -v2
	v_fmac_f32_e32 v2, 0x3377d1cf, v1
	v_fmac_f32_e32 v2, 0x3f317217, v1
	v_cmp_lt_f32_e64 s[6:7], |v1|, s45
	s_nop 1
	v_cndmask_b32_e64 v1, v1, v2, s[6:7]
	v_cndmask_b32_e64 v2, 0, v163, s[0:1]
	v_sub_f32_e32 v1, v1, v2
	v_sub_f32_e32 v0, v0, v1
	v_mul_f32_e32 v0, 0x3d800000, v0
	v_cndmask_b32_e32 v0, 0, v0, vcc
	v_add_f32_e32 v41, v41, v0
	v_sub_f32_e32 v0, v35, v41
	v_mul_f32_e32 v0, 0x3fb8aa3b, v0
	v_exp_f32_e32 v0, v0
	v_cmp_gt_i32_e32 vcc, s46, v42
	v_mov_b32_e32 v42, 0
	v_mul_f32_e32 v0, v0, v40
	v_bfe_u32 v1, v0, 16, 1
	v_add3_u32 v0, v0, v1, s33
	ds_write_b16_d16_hi v38, v0 offset:272
	ds_read_b128 v[12:15], v37 offset:128
	ds_read_b128 v[8:11], v37 offset:144
	ds_read_b128 v[4:7], v37 offset:160
	ds_read_b128 v[0:3], v37 offset:176
	v_mov_b32_e32 v40, 0
	s_and_saveexec_b64 s[0:1], vcc
	s_cbranch_execz .Lga_c5
	s_waitcnt vmcnt(9)
	v_lshlrev_b32_e32 v42, 16, v211
.Lga_c5:
	s_or_b64 exec, exec, s[0:1]
	s_waitcnt lgkmcnt(2)
	v_mov_b32_e32 v45, v8
	v_mov_b32_e32 v8, v13
	v_mov_b32_e32 v44, v12
	v_pk_mul_f32 v[8:9], v[18:19], v[8:9]
	v_mov_b32_e32 v12, v14
	v_pk_fma_f32 v[8:9], v[16:17], v[44:45], v[8:9]
	v_mov_b32_e32 v13, v10
	v_pk_fma_f32 v[8:9], v[20:21], v[12:13], v[8:9]
	v_mov_b32_e32 v10, v15
	v_pk_fma_f32 v[8:9], v[22:23], v[10:11], v[8:9]
	s_mov_b32 s0, 0x800000
	v_add_f32_e32 v8, v34, v8
	v_add_f32_e32 v10, v8, v9
	s_waitcnt lgkmcnt(0)
	v_mov_b32_e32 v9, v0
	v_mov_b32_e32 v0, v5
	v_mov_b32_e32 v8, v4
	v_pk_mul_f32 v[0:1], v[26:27], v[0:1]
	v_mov_b32_e32 v4, v6
	v_pk_fma_f32 v[0:1], v[24:25], v[8:9], v[0:1]
	v_mov_b32_e32 v5, v2
	v_pk_fma_f32 v[0:1], v[28:29], v[4:5], v[0:1]
	v_mov_b32_e32 v2, v7
	v_pk_fma_f32 v[0:1], v[30:31], v[2:3], v[0:1]
	v_add_u32_e32 v39, 3, v39
	v_add_f32_e32 v0, v10, v0
	v_add_f32_e32 v0, v0, v1
	v_mul_f32_e64 v1, |v0|, s95
	v_exp_f32_e32 v1, v1
	v_min_f32_e32 v0, 0, v0
	v_add_f32_e32 v1, 1.0, v1
	v_cmp_gt_f32_e64 s[0:1], s0, v1
	s_nop 1
	v_cndmask_b32_e64 v2, 0, 32, s[0:1]
	v_ldexp_f32 v1, v1, v2
	v_log_f32_e32 v1, v1
	s_nop 0
	v_mul_f32_e32 v2, 0x3f317217, v1
	v_fma_f32 v2, v1, s44, -v2
	v_fmac_f32_e32 v2, 0x3377d1cf, v1
	v_fmac_f32_e32 v2, 0x3f317217, v1
	v_cmp_lt_f32_e64 s[6:7], |v1|, s45
	s_nop 1
	v_cndmask_b32_e64 v1, v1, v2, s[6:7]
	v_cndmask_b32_e64 v2, 0, v163, s[0:1]
	v_sub_f32_e32 v1, v1, v2
	v_sub_f32_e32 v0, v0, v1
	v_mul_f32_e32 v0, 0x3d800000, v0
	v_cndmask_b32_e32 v0, 0, v0, vcc
	v_add_f32_e32 v41, v41, v0
	v_sub_f32_e32 v0, v35, v41
	v_mul_f32_e32 v0, 0x3fb8aa3b, v0
	v_exp_f32_e32 v0, v0
	v_cmp_gt_i32_e32 vcc, s46, v39
	v_mul_f32_e32 v0, v0, v42
	v_bfe_u32 v1, v0, 16, 1
	v_add3_u32 v0, v0, v1, s33
	ds_write_b16_d16_hi v38, v0 offset:544
	ds_read_b128 v[12:15], v37 offset:192
	ds_read_b128 v[8:11], v37 offset:208
	ds_read_b128 v[4:7], v37 offset:224
	ds_read_b128 v[0:3], v37 offset:240
	s_and_saveexec_b64 s[0:1], vcc
	s_cbranch_execz .Lga_l5
	s_waitcnt vmcnt(8)
	v_lshlrev_b32_e32 v40, 16, v212
	s_branch .Lga_l5

.Lga_h6:
	ds_read_b128 v[12:15], v37
	ds_read_b128 v[8:11], v37 offset:16
	ds_read_b128 v[4:7], v37 offset:32
	ds_read_b128 v[0:3], v37 offset:48
	v_add_u32_e32 v39, s47, v129
	v_cmp_gt_i32_e32 vcc, s46, v39
	v_mov_b32_e32 v40, 0
	v_mov_b32_e32 v42, 0
	s_and_saveexec_b64 s[0:1], vcc
	s_cbranch_execz .Lga_a6
	s_waitcnt vmcnt(7)
	v_lshlrev_b32_e32 v42, 16, v213
.Lga_a6:
	s_or_b64 exec, exec, s[0:1]
	s_waitcnt lgkmcnt(2)
	v_mov_b32_e32 v45, v8
	v_mov_b32_e32 v8, v13
	v_mov_b32_e32 v44, v12
	v_pk_mul_f32 v[8:9], v[18:19], v[8:9]
	v_mov_b32_e32 v12, v14
	v_pk_fma_f32 v[8:9], v[16:17], v[44:45], v[8:9]
	v_mov_b32_e32 v13, v10
	v_pk_fma_f32 v[8:9], v[20:21], v[12:13], v[8:9]
	v_mov_b32_e32 v10, v15
	v_pk_fma_f32 v[8:9], v[22:23], v[10:11], v[8:9]
	s_mov_b32 s0, 0x800000
	v_add_f32_e32 v8, v34, v8
	v_add_f32_e32 v10, v8, v9
	s_waitcnt lgkmcnt(0)
	v_mov_b32_e32 v9, v0
	v_mov_b32_e32 v0, v5
	v_mov_b32_e32 v8, v4
	v_pk_mul_f32 v[0:1], v[26:27], v[0:1]
	v_mov_b32_e32 v4, v6
	v_pk_fma_f32 v[0:1], v[24:25], v[8:9], v[0:1]
	v_mov_b32_e32 v5, v2
	v_pk_fma_f32 v[0:1], v[28:29], v[4:5], v[0:1]
	v_mov_b32_e32 v2, v7
	v_pk_fma_f32 v[0:1], v[30:31], v[2:3], v[0:1]
	s_nop 0
	v_add_f32_e32 v0, v10, v0
	v_add_f32_e32 v0, v0, v1
	v_mul_f32_e64 v1, |v0|, s95
	v_exp_f32_e32 v1, v1
	v_min_f32_e32 v0, 0, v0
	v_add_f32_e32 v1, 1.0, v1
	v_cmp_gt_f32_e64 s[0:1], s0, v1
	s_nop 1
	v_cndmask_b32_e64 v2, 0, 32, s[0:1]
	v_ldexp_f32 v1, v1, v2
	v_log_f32_e32 v1, v1
	s_nop 0
	v_mul_f32_e32 v2, 0x3f317217, v1
	v_fma_f32 v2, v1, s44, -v2
	v_fmac_f32_e32 v2, 0x3377d1cf, v1
	v_fmac_f32_e32 v2, 0x3f317217, v1
	v_cmp_lt_f32_e64 s[6:7], |v1|, s45
	s_nop 1
	v_cndmask_b32_e64 v1, v1, v2, s[6:7]
	v_cndmask_b32_e64 v2, 0, v163, s[0:1]
	v_sub_f32_e32 v1, v1, v2
	v_sub_f32_e32 v0, v0, v1
	v_mul_f32_e32 v0, 0x3d800000, v0
	v_cndmask_b32_e32 v0, 0, v0, vcc
	v_add_f32_e32 v41, v41, v0
	v_sub_f32_e32 v0, v35, v41
	v_mul_f32_e32 v0, 0x3fb8aa3b, v0
	v_exp_f32_e32 v0, v0
	s_nop 0
	v_mul_f32_e32 v0, v0, v42
	v_bfe_u32 v1, v0, 16, 1
	v_add3_u32 v0, v0, v1, s33
	ds_write_b16_d16_hi v38, v0
	ds_read_b128 v[12:15], v37 offset:64
	ds_read_b128 v[8:11], v37 offset:80
	ds_read_b128 v[4:7], v37 offset:96
	ds_read_b128 v[0:3], v37 offset:112
	v_add_u32_e32 v42, 1, v39
	v_cmp_gt_i32_e32 vcc, s46, v42
	s_and_saveexec_b64 s[0:1], vcc
	s_cbranch_execz .Lga_b6
	s_waitcnt vmcnt(6)
	v_lshlrev_b32_e32 v40, 16, v214
.Lga_b6:
	s_or_b64 exec, exec, s[0:1]
	s_waitcnt lgkmcnt(2)
	v_mov_b32_e32 v43, v8
	v_mov_b32_e32 v8, v13
	v_mov_b32_e32 v42, v12
	v_pk_mul_f32 v[8:9], v[18:19], v[8:9]
	v_mov_b32_e32 v12, v14
	v_pk_fma_f32 v[8:9], v[16:17], v[42:43], v[8:9]
	v_mov_b32_e32 v13, v10
	v_pk_fma_f32 v[8:9], v[20:21], v[12:13], v[8:9]
	v_mov_b32_e32 v10, v15
	v_pk_fma_f32 v[8:9], v[22:23], v[10:11], v[8:9]
	s_mov_b32 s0, 0x800000
	v_add_f32_e32 v8, v34, v8
	v_add_f32_e32 v10, v8, v9
	s_waitcnt lgkmcnt(0)
	v_mov_b32_e32 v9, v0
	v_mov_b32_e32 v0, v5
	v_mov_b32_e32 v8, v4
	v_pk_mul_f32 v[0:1], v[26:27], v[0:1]
	v_mov_b32_e32 v4, v6
	v_pk_fma_f32 v[0:1], v[24:25], v[8:9], v[0:1]
	v_mov_b32_e32 v5, v2
	v_pk_fma_f32 v[0:1], v[28:29], v[4:5], v[0:1]
	v_mov_b32_e32 v2, v7
	v_pk_fma_f32 v[0:1], v[30:31], v[2:3], v[0:1]
	v_add_u32_e32 v42, 2, v39
	v_add_f32_e32 v0, v10, v0
	v_add_f32_e32 v0, v0, v1
	v_mul_f32_e64 v1, |v0|, s95
	v_exp_f32_e32 v1, v1
	v_min_f32_e32 v0, 0, v0
	v_add_f32_e32 v1, 1.0, v1
	v_cmp_gt_f32_e64 s[0:1], s0, v1
	s_nop 1
	v_cndmask_b32_e64 v2, 0, 32, s[0:1]
	v_ldexp_f32 v1, v1, v2
	v_log_f32_e32 v1, v1
	s_nop 0
	v_mul_f32_e32 v2, 0x3f317217, v1
	v_fma_f32 v2, v1, s44, -v2
	v_fmac_f32_e32 v2, 0x3377d1cf, v1
	v_fmac_f32_e32 v2, 0x3f317217, v1
	v_cmp_lt_f32_e64 s[6:7], |v1|, s45
	s_nop 1
	v_cndmask_b32_e64 v1, v1, v2, s[6:7]
	v_cndmask_b32_e64 v2, 0, v163, s[0:1]
	v_sub_f32_e32 v1, v1, v2
	v_sub_f32_e32 v0, v0, v1
	v_mul_f32_e32 v0, 0x3d800000, v0
	v_cndmask_b32_e32 v0, 0, v0, vcc
	v_add_f32_e32 v41, v41, v0
	v_sub_f32_e32 v0, v35, v41
	v_mul_f32_e32 v0, 0x3fb8aa3b, v0
	v_exp_f32_e32 v0, v0
	v_cmp_gt_i32_e32 vcc, s46, v42
	v_mov_b32_e32 v42, 0
	v_mul_f32_e32 v0, v0, v40
	v_bfe_u32 v1, v0, 16, 1
	v_add3_u32 v0, v0, v1, s33
	ds_write_b16_d16_hi v38, v0 offset:272
	ds_read_b128 v[12:15], v37 offset:128
	ds_read_b128 v[8:11], v37 offset:144
	ds_read_b128 v[4:7], v37 offset:160
	ds_read_b128 v[0:3], v37 offset:176
	v_mov_b32_e32 v40, 0
	s_and_saveexec_b64 s[0:1], vcc
	s_cbranch_execz .Lga_c6
	s_waitcnt vmcnt(5)
	v_lshlrev_b32_e32 v42, 16, v215
.Lga_c6:
	s_or_b64 exec, exec, s[0:1]
	s_waitcnt lgkmcnt(2)
	v_mov_b32_e32 v45, v8
	v_mov_b32_e32 v8, v13
	v_mov_b32_e32 v44, v12
	v_pk_mul_f32 v[8:9], v[18:19], v[8:9]
	v_mov_b32_e32 v12, v14
	v_pk_fma_f32 v[8:9], v[16:17], v[44:45], v[8:9]
	v_mov_b32_e32 v13, v10
	v_pk_fma_f32 v[8:9], v[20:21], v[12:13], v[8:9]
	v_mov_b32_e32 v10, v15
	v_pk_fma_f32 v[8:9], v[22:23], v[10:11], v[8:9]
	s_mov_b32 s0, 0x800000
	v_add_f32_e32 v8, v34, v8
	v_add_f32_e32 v10, v8, v9
	s_waitcnt lgkmcnt(0)
	v_mov_b32_e32 v9, v0
	v_mov_b32_e32 v0, v5
	v_mov_b32_e32 v8, v4
	v_pk_mul_f32 v[0:1], v[26:27], v[0:1]
	v_mov_b32_e32 v4, v6
	v_pk_fma_f32 v[0:1], v[24:25], v[8:9], v[0:1]
	v_mov_b32_e32 v5, v2
	v_pk_fma_f32 v[0:1], v[28:29], v[4:5], v[0:1]
	v_mov_b32_e32 v2, v7
	v_pk_fma_f32 v[0:1], v[30:31], v[2:3], v[0:1]
	v_add_u32_e32 v39, 3, v39
	v_add_f32_e32 v0, v10, v0
	v_add_f32_e32 v0, v0, v1
	v_mul_f32_e64 v1, |v0|, s95
	v_exp_f32_e32 v1, v1
	v_min_f32_e32 v0, 0, v0
	v_add_f32_e32 v1, 1.0, v1
	v_cmp_gt_f32_e64 s[0:1], s0, v1
	s_nop 1
	v_cndmask_b32_e64 v2, 0, 32, s[0:1]
	v_ldexp_f32 v1, v1, v2
	v_log_f32_e32 v1, v1
	s_nop 0
	v_mul_f32_e32 v2, 0x3f317217, v1
	v_fma_f32 v2, v1, s44, -v2
	v_fmac_f32_e32 v2, 0x3377d1cf, v1
	v_fmac_f32_e32 v2, 0x3f317217, v1
	v_cmp_lt_f32_e64 s[6:7], |v1|, s45
	s_nop 1
	v_cndmask_b32_e64 v1, v1, v2, s[6:7]
	v_cndmask_b32_e64 v2, 0, v163, s[0:1]
	v_sub_f32_e32 v1, v1, v2
	v_sub_f32_e32 v0, v0, v1
	v_mul_f32_e32 v0, 0x3d800000, v0
	v_cndmask_b32_e32 v0, 0, v0, vcc
	v_add_f32_e32 v41, v41, v0
	v_sub_f32_e32 v0, v35, v41
	v_mul_f32_e32 v0, 0x3fb8aa3b, v0
	v_exp_f32_e32 v0, v0
	v_cmp_gt_i32_e32 vcc, s46, v39
	v_mul_f32_e32 v0, v0, v42
	v_bfe_u32 v1, v0, 16, 1
	v_add3_u32 v0, v0, v1, s33
	ds_write_b16_d16_hi v38, v0 offset:544
	ds_read_b128 v[12:15], v37 offset:192
	ds_read_b128 v[8:11], v37 offset:208
	ds_read_b128 v[4:7], v37 offset:224
	ds_read_b128 v[0:3], v37 offset:240
	s_and_saveexec_b64 s[0:1], vcc
	s_cbranch_execz .Lga_l6
	s_waitcnt vmcnt(4)
	v_lshlrev_b32_e32 v40, 16, v216
	s_branch .Lga_l6

.Lga_h7:
	ds_read_b128 v[12:15], v37
	ds_read_b128 v[8:11], v37 offset:16
	ds_read_b128 v[4:7], v37 offset:32
	ds_read_b128 v[0:3], v37 offset:48
	v_add_u32_e32 v39, s47, v129
	v_cmp_gt_i32_e32 vcc, s46, v39
	v_mov_b32_e32 v40, 0
	v_mov_b32_e32 v42, 0
	s_and_saveexec_b64 s[0:1], vcc
	s_cbranch_execz .Lga_a7
	s_waitcnt vmcnt(3)
	v_lshlrev_b32_e32 v42, 16, v217
.Lga_a7:
	s_or_b64 exec, exec, s[0:1]
	s_waitcnt lgkmcnt(2)
	v_mov_b32_e32 v45, v8
	v_mov_b32_e32 v8, v13
	v_mov_b32_e32 v44, v12
	v_pk_mul_f32 v[8:9], v[18:19], v[8:9]
	v_mov_b32_e32 v12, v14
	v_pk_fma_f32 v[8:9], v[16:17], v[44:45], v[8:9]
	v_mov_b32_e32 v13, v10
	v_pk_fma_f32 v[8:9], v[20:21], v[12:13], v[8:9]
	v_mov_b32_e32 v10, v15
	v_pk_fma_f32 v[8:9], v[22:23], v[10:11], v[8:9]
	s_mov_b32 s0, 0x800000
	v_add_f32_e32 v8, v34, v8
	v_add_f32_e32 v10, v8, v9
	s_waitcnt lgkmcnt(0)
	v_mov_b32_e32 v9, v0
	v_mov_b32_e32 v0, v5
	v_mov_b32_e32 v8, v4
	v_pk_mul_f32 v[0:1], v[26:27], v[0:1]
	v_mov_b32_e32 v4, v6
	v_pk_fma_f32 v[0:1], v[24:25], v[8:9], v[0:1]
	v_mov_b32_e32 v5, v2
	v_pk_fma_f32 v[0:1], v[28:29], v[4:5], v[0:1]
	v_mov_b32_e32 v2, v7
	v_pk_fma_f32 v[0:1], v[30:31], v[2:3], v[0:1]
	s_nop 0
	v_add_f32_e32 v0, v10, v0
	v_add_f32_e32 v0, v0, v1
	v_mul_f32_e64 v1, |v0|, s95
	v_exp_f32_e32 v1, v1
	v_min_f32_e32 v0, 0, v0
	v_add_f32_e32 v1, 1.0, v1
	v_cmp_gt_f32_e64 s[0:1], s0, v1
	s_nop 1
	v_cndmask_b32_e64 v2, 0, 32, s[0:1]
	v_ldexp_f32 v1, v1, v2
	v_log_f32_e32 v1, v1
	s_nop 0
	v_mul_f32_e32 v2, 0x3f317217, v1
	v_fma_f32 v2, v1, s44, -v2
	v_fmac_f32_e32 v2, 0x3377d1cf, v1
	v_fmac_f32_e32 v2, 0x3f317217, v1
	v_cmp_lt_f32_e64 s[6:7], |v1|, s45
	s_nop 1
	v_cndmask_b32_e64 v1, v1, v2, s[6:7]
	v_cndmask_b32_e64 v2, 0, v163, s[0:1]
	v_sub_f32_e32 v1, v1, v2
	v_sub_f32_e32 v0, v0, v1
	v_mul_f32_e32 v0, 0x3d800000, v0
	v_cndmask_b32_e32 v0, 0, v0, vcc
	v_add_f32_e32 v41, v41, v0
	v_sub_f32_e32 v0, v35, v41
	v_mul_f32_e32 v0, 0x3fb8aa3b, v0
	v_exp_f32_e32 v0, v0
	s_nop 0
	v_mul_f32_e32 v0, v0, v42
	v_bfe_u32 v1, v0, 16, 1
	v_add3_u32 v0, v0, v1, s33
	ds_write_b16_d16_hi v38, v0
	ds_read_b128 v[12:15], v37 offset:64
	ds_read_b128 v[8:11], v37 offset:80
	ds_read_b128 v[4:7], v37 offset:96
	ds_read_b128 v[0:3], v37 offset:112
	v_add_u32_e32 v42, 1, v39
	v_cmp_gt_i32_e32 vcc, s46, v42
	s_and_saveexec_b64 s[0:1], vcc
	s_cbranch_execz .Lga_b7
	s_waitcnt vmcnt(2)
	v_lshlrev_b32_e32 v40, 16, v218
.Lga_b7:
	s_or_b64 exec, exec, s[0:1]
	s_waitcnt lgkmcnt(2)
	v_mov_b32_e32 v43, v8
	v_mov_b32_e32 v8, v13
	v_mov_b32_e32 v42, v12
	v_pk_mul_f32 v[8:9], v[18:19], v[8:9]
	v_mov_b32_e32 v12, v14
	v_pk_fma_f32 v[8:9], v[16:17], v[42:43], v[8:9]
	v_mov_b32_e32 v13, v10
	v_pk_fma_f32 v[8:9], v[20:21], v[12:13], v[8:9]
	v_mov_b32_e32 v10, v15
	v_pk_fma_f32 v[8:9], v[22:23], v[10:11], v[8:9]
	s_mov_b32 s0, 0x800000
	v_add_f32_e32 v8, v34, v8
	v_add_f32_e32 v10, v8, v9
	s_waitcnt lgkmcnt(0)
	v_mov_b32_e32 v9, v0
	v_mov_b32_e32 v0, v5
	v_mov_b32_e32 v8, v4
	v_pk_mul_f32 v[0:1], v[26:27], v[0:1]
	v_mov_b32_e32 v4, v6
	v_pk_fma_f32 v[0:1], v[24:25], v[8:9], v[0:1]
	v_mov_b32_e32 v5, v2
	v_pk_fma_f32 v[0:1], v[28:29], v[4:5], v[0:1]
	v_mov_b32_e32 v2, v7
	v_pk_fma_f32 v[0:1], v[30:31], v[2:3], v[0:1]
	v_add_u32_e32 v42, 2, v39
	v_add_f32_e32 v0, v10, v0
	v_add_f32_e32 v0, v0, v1
	v_mul_f32_e64 v1, |v0|, s95
	v_exp_f32_e32 v1, v1
	v_min_f32_e32 v0, 0, v0
	v_add_f32_e32 v1, 1.0, v1
	v_cmp_gt_f32_e64 s[0:1], s0, v1
	s_nop 1
	v_cndmask_b32_e64 v2, 0, 32, s[0:1]
	v_ldexp_f32 v1, v1, v2
	v_log_f32_e32 v1, v1
	s_nop 0
	v_mul_f32_e32 v2, 0x3f317217, v1
	v_fma_f32 v2, v1, s44, -v2
	v_fmac_f32_e32 v2, 0x3377d1cf, v1
	v_fmac_f32_e32 v2, 0x3f317217, v1
	v_cmp_lt_f32_e64 s[6:7], |v1|, s45
	s_nop 1
	v_cndmask_b32_e64 v1, v1, v2, s[6:7]
	v_cndmask_b32_e64 v2, 0, v163, s[0:1]
	v_sub_f32_e32 v1, v1, v2
	v_sub_f32_e32 v0, v0, v1
	v_mul_f32_e32 v0, 0x3d800000, v0
	v_cndmask_b32_e32 v0, 0, v0, vcc
	v_add_f32_e32 v41, v41, v0
	v_sub_f32_e32 v0, v35, v41
	v_mul_f32_e32 v0, 0x3fb8aa3b, v0
	v_exp_f32_e32 v0, v0
	v_cmp_gt_i32_e32 vcc, s46, v42
	v_mov_b32_e32 v42, 0
	v_mul_f32_e32 v0, v0, v40
	v_bfe_u32 v1, v0, 16, 1
	v_add3_u32 v0, v0, v1, s33
	ds_write_b16_d16_hi v38, v0 offset:272
	ds_read_b128 v[12:15], v37 offset:128
	ds_read_b128 v[8:11], v37 offset:144
	ds_read_b128 v[4:7], v37 offset:160
	ds_read_b128 v[0:3], v37 offset:176
	v_mov_b32_e32 v40, 0
	s_and_saveexec_b64 s[0:1], vcc
	s_cbranch_execz .Lga_c7
	s_waitcnt vmcnt(1)
	v_lshlrev_b32_e32 v42, 16, v219
.Lga_c7:
	s_or_b64 exec, exec, s[0:1]
	s_waitcnt lgkmcnt(2)
	v_mov_b32_e32 v45, v8
	v_mov_b32_e32 v8, v13
	v_mov_b32_e32 v44, v12
	v_pk_mul_f32 v[8:9], v[18:19], v[8:9]
	v_mov_b32_e32 v12, v14
	v_pk_fma_f32 v[8:9], v[16:17], v[44:45], v[8:9]
	v_mov_b32_e32 v13, v10
	v_pk_fma_f32 v[8:9], v[20:21], v[12:13], v[8:9]
	v_mov_b32_e32 v10, v15
	v_pk_fma_f32 v[8:9], v[22:23], v[10:11], v[8:9]
	s_mov_b32 s0, 0x800000
	v_add_f32_e32 v8, v34, v8
	v_add_f32_e32 v10, v8, v9
	s_waitcnt lgkmcnt(0)
	v_mov_b32_e32 v9, v0
	v_mov_b32_e32 v0, v5
	v_mov_b32_e32 v8, v4
	v_pk_mul_f32 v[0:1], v[26:27], v[0:1]
	v_mov_b32_e32 v4, v6
	v_pk_fma_f32 v[0:1], v[24:25], v[8:9], v[0:1]
	v_mov_b32_e32 v5, v2
	v_pk_fma_f32 v[0:1], v[28:29], v[4:5], v[0:1]
	v_mov_b32_e32 v2, v7
	v_pk_fma_f32 v[0:1], v[30:31], v[2:3], v[0:1]
	v_add_u32_e32 v39, 3, v39
	v_add_f32_e32 v0, v10, v0
	v_add_f32_e32 v0, v0, v1
	v_mul_f32_e64 v1, |v0|, s95
	v_exp_f32_e32 v1, v1
	v_min_f32_e32 v0, 0, v0
	v_add_f32_e32 v1, 1.0, v1
	v_cmp_gt_f32_e64 s[0:1], s0, v1
	s_nop 1
	v_cndmask_b32_e64 v2, 0, 32, s[0:1]
	v_ldexp_f32 v1, v1, v2
	v_log_f32_e32 v1, v1
	s_nop 0
	v_mul_f32_e32 v2, 0x3f317217, v1
	v_fma_f32 v2, v1, s44, -v2
	v_fmac_f32_e32 v2, 0x3377d1cf, v1
	v_fmac_f32_e32 v2, 0x3f317217, v1
	v_cmp_lt_f32_e64 s[6:7], |v1|, s45
	s_nop 1
	v_cndmask_b32_e64 v1, v1, v2, s[6:7]
	v_cndmask_b32_e64 v2, 0, v163, s[0:1]
	v_sub_f32_e32 v1, v1, v2
	v_sub_f32_e32 v0, v0, v1
	v_mul_f32_e32 v0, 0x3d800000, v0
	v_cndmask_b32_e32 v0, 0, v0, vcc
	v_add_f32_e32 v41, v41, v0
	v_sub_f32_e32 v0, v35, v41
	v_mul_f32_e32 v0, 0x3fb8aa3b, v0
	v_exp_f32_e32 v0, v0
	v_cmp_gt_i32_e32 vcc, s46, v39
	v_mul_f32_e32 v0, v0, v42
	v_bfe_u32 v1, v0, 16, 1
	v_add3_u32 v0, v0, v1, s33
	ds_write_b16_d16_hi v38, v0 offset:544
	ds_read_b128 v[12:15], v37 offset:192
	ds_read_b128 v[8:11], v37 offset:208
	ds_read_b128 v[4:7], v37 offset:224
	ds_read_b128 v[0:3], v37 offset:240
	s_and_saveexec_b64 s[0:1], vcc
	s_cbranch_execz .Lga_l7
	s_waitcnt vmcnt(0)
	v_lshlrev_b32_e32 v40, 16, v220
	s_branch .Lga_l7
.Lga_l7:
	s_or_b64 exec, exec, s[0:1]
	s_waitcnt lgkmcnt(2)
	v_mov_b32_e32 v43, v8
	v_mov_b32_e32 v8, v13
	v_mov_b32_e32 v42, v12
	v_pk_mul_f32 v[8:9], v[18:19], v[8:9]
	v_mov_b32_e32 v12, v14
	v_pk_fma_f32 v[8:9], v[16:17], v[42:43], v[8:9]
	v_mov_b32_e32 v13, v10
	v_pk_fma_f32 v[8:9], v[20:21], v[12:13], v[8:9]
	v_mov_b32_e32 v10, v15
	v_pk_fma_f32 v[8:9], v[22:23], v[10:11], v[8:9]
	s_mov_b32 s0, 0x800000
	v_add_f32_e32 v8, v34, v8
	v_add_f32_e32 v10, v8, v9
	s_waitcnt lgkmcnt(0)
	v_mov_b32_e32 v9, v0
	v_mov_b32_e32 v0, v5
	v_mov_b32_e32 v8, v4
	v_pk_mul_f32 v[0:1], v[26:27], v[0:1]
	v_mov_b32_e32 v4, v6
	v_pk_fma_f32 v[0:1], v[24:25], v[8:9], v[0:1]
	v_mov_b32_e32 v5, v2
	v_pk_fma_f32 v[0:1], v[28:29], v[4:5], v[0:1]
	v_mov_b32_e32 v2, v7
	v_pk_fma_f32 v[0:1], v[30:31], v[2:3], v[0:1]
	s_add_i32 s47, s47, 4
	v_add_f32_e32 v0, v10, v0
	v_add_f32_e32 v0, v0, v1
	v_mul_f32_e64 v1, |v0|, s95
	v_exp_f32_e32 v1, v1
	v_min_f32_e32 v0, 0, v0
	s_cmp_eq_u32 s47, 32
	v_add_u32_e32 v37, 0x100, v37
	v_add_f32_e32 v1, 1.0, v1
	v_cmp_gt_f32_e64 s[0:1], s0, v1
	s_nop 1
	v_cndmask_b32_e64 v2, 0, 32, s[0:1]
	v_ldexp_f32 v1, v1, v2
	v_log_f32_e32 v1, v1
	s_nop 0
	v_mul_f32_e32 v2, 0x3f317217, v1
	v_fma_f32 v2, v1, s44, -v2
	v_fmac_f32_e32 v2, 0x3377d1cf, v1
	v_fmac_f32_e32 v2, 0x3f317217, v1
	v_cmp_lt_f32_e64 s[6:7], |v1|, s45
	s_nop 1
	v_cndmask_b32_e64 v1, v1, v2, s[6:7]
	v_cndmask_b32_e64 v2, 0, v163, s[0:1]
	v_sub_f32_e32 v1, v1, v2
	v_sub_f32_e32 v0, v0, v1
	v_mul_f32_e32 v0, 0x3d800000, v0
	v_cndmask_b32_e32 v0, 0, v0, vcc
	v_add_f32_e32 v41, v41, v0
	v_sub_f32_e32 v0, v35, v41
	v_mul_f32_e32 v0, 0x3fb8aa3b, v0
	v_exp_f32_e32 v0, v0
	s_nop 0
	v_mul_f32_e32 v0, v0, v40
	v_bfe_u32 v1, v0, 16, 1
	v_add3_u32 v0, v0, v1, s33
	ds_write_b16_d16_hi v38, v0 offset:816
	v_add_u32_e32 v38, 0x440, v38
	s_branch .LBB0_408
.LBB0_408:
	s_waitcnt vmcnt(0)
	s_and_saveexec_b64 s[0:1], s[40:41]
	s_cbranch_execz .LBB0_410
	v_mul_f32_e32 v0, 0x3fb8aa3b, v35
	v_exp_f32_e32 v2, v0
	v_lshl_or_b32 v0, s67, 7, v176
	v_readlane_b32 s4, v254, 61
	v_ashrrev_i32_e32 v1, 31, v0
	v_readlane_b32 s5, v254, 62
	s_nop 1
	v_lshl_add_u64 v[0:1], v[0:1], 2, s[4:5]
	global_store_dword v[0:1], v2, off
